# combined: GEMM K-loop loader trims (saddr LDS-DMA, redundant waits, setprio pairs) + mLSTM M3 load hoists on top of the saddr-attention/peel version
# speedup vs baseline: 1.0045x; 1.0045x over previous
; #define PG8_STAGE(bufoff, gbase, voff) do { _Pragma("unroll") for (int _i = 0; _i < 2; ++_i) \
;         __builtin_amdgcn_global_load_lds((const unsigned*)((const char*)(gbase) + (voff)[_i]), (PG8_LAS unsigned*)(lds + (bufoff) + ldsw + _i * 8192), 16, 0, 0); } while (0)
; #define PG8_LDA(dst, b, h) do { _Pragma("unroll") for (int m = 0; m < 4; ++m) _Pragma("unroll") for (int k = 0; k < 2; ++k) dst[m][k] = *(const PG8_LAS bf16x8*)(lds + PG8_SA(b, h) + aoff + m * 2048 + k * 1024); } while (0)
; #define PG8_LDB(dst, b, h) do { _Pragma("unroll") for (int n = 0; n < 2; ++n) _Pragma("unroll") for (int k = 0; k < 2; ++k) dst[n][k] = *(const PG8_LAS bf16x8*)(lds + PG8_SB(b, h) + boff + n * 2048 + k * 1024); } while (0)
; #define PG8_WAIT_V(n) asm volatile("s_waitcnt vmcnt(" #n ")" ::: "memory")
; #define PG8_WAIT_L(n) asm volatile("s_waitcnt lgkmcnt(" #n ")" ::: "memory")
; #define PG8_BAR __builtin_amdgcn_s_barrier()
; #define PG8_SCHED __builtin_amdgcn_sched_barrier(0)
; template <class Epi, class Sched, bool ALIGN_EPI = false, bool SP2 = false>
; __device__ __forceinline__ void gemm_phase(PG8_LAS unsigned char* lds, const Gemm g, const Sched& S, const Epi& E) {
;     ...
;             const bool last = (t == nt - 2);
;             const char* a1 = cA + (size_t)(t + 1) * kstepA;
;             const char* a2 = last ? nA : cA + (size_t)(t + 2) * kstepA; const char* b2 = last ? nB : cB + (size_t)(t + 2) * kstep;
;             const char* a3 = a2 + kstepA; const char* b3 = b2 + kstep;
;             if (last && has_next) S.a_ready(nxt);
;             if constexpr (SP2) {
;             PG8_LDB(B0, 0, 0); PG8_LDB(B1, 0, 1); PG8_SCHED; PG8_LDA(At, 0, 0); PG8_STAGE(PG8_SA(1, 1), a1 + hstepA, voffA);
;             PG8_WAIT_V(8); PG8_WAIT_L(0); PG8_BAR; PG8_MMA(0, 0, At, B0); PG8_MMA(0, 1, At, B1); PG8_BAR; PG8_SCHED;
;             PG8_LDA(At, 0, 1); PG8_STAGE(PG8_SB(0, 0), b2, voffB); PG8_STAGE(PG8_SB(0, 1), b2 + hstepB, voffB); PG8_STAGE(PG8_SA(0, 0), a2, voffA);
;             PG8_WAIT_V(8); PG8_WAIT_L(0); PG8_BAR; PG8_MMA(1, 0, At, B0); PG8_MMA(1, 1, At, B1); PG8_BAR; PG8_SCHED;
;             PG8_LDB(B0, 1, 0); PG8_LDB(B1, 1, 1); PG8_SCHED; PG8_LDA(At, 1, 0); PG8_STAGE(PG8_SA(0, 1), a2 + hstepA, voffA);
;             PG8_WAIT_V(8); PG8_WAIT_L(0); PG8_BAR; PG8_MMA(0, 0, At, B0); PG8_MMA(0, 1, At, B1); PG8_BAR; PG8_SCHED;
.LBB0_34:
	s_ashr_i32 s11, s10, 31
	s_lshl_b64 s[14:15], s[10:11], 15
	s_add_u32 s14, s70, s14
	s_addc_u32 s15, s71, s15
	s_and_b64 s[0:1], s[0:1], exec
	s_cselect_b32 s11, s15, s19
	s_cselect_b32 s36, s14, s18
	s_add_u32 s0, s18, 0x404000
	s_addc_u32 s1, s19, 0
	s_add_u32 s37, s16, 0x100
	s_addc_u32 s38, s17, 0
	s_mov_b32 s39, -2
	s_add_u32 s16, s0, 0x3fc000
	s_addc_u32 s17, s1, 0
	s_cmp_eq_u32 s39, 40
	s_cselect_b32 s20, s36, s16
	s_cselect_b32 s21, s11, s17
	s_cselect_b32 s18, s12, s37
	s_cselect_b32 s19, s13, s38
	s_add_u32 s16, s20, 0x400000
	s_addc_u32 s17, s21, 0
	s_add_i32 s40, 0, 0x10000
	s_add_i32 s42, 0, 0x14000
	v_add_u32_e32 v156, s40, v153
	v_add_u32_e32 v172, s42, v153
	ds_read_b128 v[140:143], v156
	ds_read_b128 v[144:147], v156 offset:1024
	ds_read_b128 v[148:151], v156 offset:2048
	ds_read_b128 v[156:159], v156 offset:3072
	ds_read_b128 v[160:163], v172
	ds_read_b128 v[164:167], v172 offset:1024
	ds_read_b128 v[168:171], v172 offset:2048
	ds_read_b128 v[172:175], v172 offset:3072
	s_add_i32 m0, s23, 0xc000
	ds_read_b128 v[176:179], v155
	ds_read_b128 v[180:183], v155 offset:1024
	ds_read_b128 v[184:187], v155 offset:2048
	ds_read_b128 v[188:191], v155 offset:3072
	ds_read_b128 v[206:209], v155 offset:4096
	ds_read_b128 v[210:213], v155 offset:5120
	ds_read_b128 v[214:217], v155 offset:6144
	ds_read_b128 v[218:221], v155 offset:7168
	global_load_lds_dwordx4 v136, s[0:1]
	s_add_i32 m0, s23, 0xe000
	s_nop 0
	global_load_lds_dwordx4 v138, s[0:1]
	s_waitcnt vmcnt(8)
	s_waitcnt lgkmcnt(0)
	s_barrier
	s_setprio 1
	v_mfma_f32_16x16x32_bf16 v[126:129], v[140:143], v[176:179], 0
	v_mfma_f32_16x16x32_bf16 v[122:125], v[148:151], v[176:179], 0
	v_mfma_f32_16x16x32_bf16 v[118:121], v[140:143], v[184:187], 0
	v_mfma_f32_16x16x32_bf16 v[114:117], v[148:151], v[184:187], 0
	v_mfma_f32_16x16x32_bf16 v[106:109], v[140:143], v[206:209], 0
	v_mfma_f32_16x16x32_bf16 v[98:101], v[148:151], v[206:209], 0
	v_mfma_f32_16x16x32_bf16 v[90:93], v[140:143], v[214:217], 0
	v_mfma_f32_16x16x32_bf16 v[82:85], v[148:151], v[214:217], 0
	v_mfma_f32_16x16x32_bf16 v[126:129], v[144:147], v[180:183], v[126:129]
	v_mfma_f32_16x16x32_bf16 v[122:125], v[156:159], v[180:183], v[122:125]
	v_mfma_f32_16x16x32_bf16 v[118:121], v[144:147], v[188:191], v[118:121]
	v_mfma_f32_16x16x32_bf16 v[114:117], v[156:159], v[188:191], v[114:117]
	v_mfma_f32_16x16x32_bf16 v[106:109], v[144:147], v[210:213], v[106:109]
	v_mfma_f32_16x16x32_bf16 v[98:101], v[156:159], v[210:213], v[98:101]
	v_mfma_f32_16x16x32_bf16 v[90:93], v[144:147], v[218:221], v[90:93]
	v_mfma_f32_16x16x32_bf16 v[82:85], v[156:159], v[218:221], v[82:85]
	v_mfma_f32_16x16x32_bf16 v[110:113], v[160:163], v[176:179], 0
	v_mfma_f32_16x16x32_bf16 v[102:105], v[168:171], v[176:179], 0
	v_mfma_f32_16x16x32_bf16 v[94:97], v[160:163], v[184:187], 0
	v_mfma_f32_16x16x32_bf16 v[86:89], v[168:171], v[184:187], 0
	v_mfma_f32_16x16x32_bf16 v[78:81], v[160:163], v[206:209], 0
	v_mfma_f32_16x16x32_bf16 v[74:77], v[168:171], v[206:209], 0
	v_mfma_f32_16x16x32_bf16 v[70:73], v[160:163], v[214:217], 0
	v_mfma_f32_16x16x32_bf16 v[66:69], v[168:171], v[214:217], 0
	v_mfma_f32_16x16x32_bf16 v[110:113], v[164:167], v[180:183], v[110:113]
	v_mfma_f32_16x16x32_bf16 v[102:105], v[172:175], v[180:183], v[102:105]
	v_mfma_f32_16x16x32_bf16 v[94:97], v[164:167], v[188:191], v[94:97]
	v_mfma_f32_16x16x32_bf16 v[86:89], v[172:175], v[188:191], v[86:89]
	v_mfma_f32_16x16x32_bf16 v[78:81], v[164:167], v[210:213], v[78:81]
	v_mfma_f32_16x16x32_bf16 v[74:77], v[172:175], v[210:213], v[74:77]
	v_mfma_f32_16x16x32_bf16 v[70:73], v[164:167], v[218:221], v[70:73]
	v_mfma_f32_16x16x32_bf16 v[66:69], v[172:175], v[218:221], v[66:69]
	s_setprio 0
	s_barrier
	s_add_i32 s40, s40, s22
	v_lshl_add_u64 v[192:193], s[18:19], 0, v[0:1]
	s_mov_b32 m0, s40
	ds_read_b128 v[176:179], v155 offset:16384
	ds_read_b128 v[180:183], v155 offset:17408
	ds_read_b128 v[184:187], v155 offset:18432
	ds_read_b128 v[188:191], v155 offset:19456
	ds_read_b128 v[206:209], v155 offset:20480
	ds_read_b128 v[210:213], v155 offset:21504
	ds_read_b128 v[214:217], v155 offset:22528
	ds_read_b128 v[218:221], v155 offset:23552
	global_load_lds_dwordx4 v[192:193], off
	s_add_i32 m0, s40, 0x2000
	s_add_u32 s40, s18, 0xb0000
	v_lshl_add_u64 v[222:223], s[18:19], 0, v[130:131]
	s_addc_u32 s41, s19, 0
	s_add_i32 s42, s42, s22
	global_load_lds_dwordx4 v130, s[18:19]
	v_lshl_add_u64 v[224:225], s[40:41], 0, v[0:1]
	s_mov_b32 m0, s42
	s_nop 0
	global_load_lds_dwordx4 v[224:225], off
	s_add_i32 m0, s42, 0x2000
	s_nop 0
	global_load_lds_dwordx4 v130, s[40:41]
	s_mov_b32 m0, s23
	s_nop 0
	global_load_lds_dwordx4 v134, s[20:21]
	s_mov_b32 m0, s25
	s_nop 0
	global_load_lds_dwordx4 v132, s[20:21]
	s_waitcnt vmcnt(8)
	s_waitcnt lgkmcnt(0)
	s_barrier
; #define PG8_STAGE(bufoff, gbase, voff) do { _Pragma("unroll") for (int _i = 0; _i < 2; ++_i) \
;         __builtin_amdgcn_global_load_lds((const unsigned*)((const char*)(gbase) + (voff)[_i]), (PG8_LAS unsigned*)(lds + (bufoff) + ldsw + _i * 8192), 16, 0, 0); } while (0)
; #define PG8_LDA(dst, b, h) do { _Pragma("unroll") for (int m = 0; m < 4; ++m) _Pragma("unroll") for (int k = 0; k < 2; ++k) dst[m][k] = *(const PG8_LAS bf16x8*)(lds + PG8_SA(b, h) + aoff + m * 2048 + k * 1024); } while (0)
; #define PG8_LDB(dst, b, h) do { _Pragma("unroll") for (int n = 0; n < 2; ++n) _Pragma("unroll") for (int k = 0; k < 2; ++k) dst[n][k] = *(const PG8_LAS bf16x8*)(lds + PG8_SB(b, h) + boff + n * 2048 + k * 1024); } while (0)
; #define PG8_MMA(ai, bj, At, Bt) do { __builtin_amdgcn_s_setprio(1); _Pragma("unroll") for (int m = 0; m < 4; ++m) _Pragma("unroll") for (int n = 0; n < 2; ++n) _Pragma("unroll") for (int k = 0; k < 2; ++k) \
;         acc[ai][bj][m][n] = __builtin_amdgcn_mfma_f32_16x16x32_bf16(Bt[n][k], At[m][k], acc[ai][bj][m][n], 0, 0, 0); __builtin_amdgcn_s_setprio(0); } while (0)
; #define PG8_WAIT_V(n) asm volatile("s_waitcnt vmcnt(" #n ")" ::: "memory")
; #define PG8_WAIT_L(n) asm volatile("s_waitcnt lgkmcnt(" #n ")" ::: "memory")
; #define PG8_BAR __builtin_amdgcn_s_barrier()
; #define PG8_SCHED __builtin_amdgcn_sched_barrier(0)
; template <class Epi, class Sched, bool ALIGN_EPI = false, bool SP2 = false>
; __device__ __forceinline__ void gemm_phase(PG8_LAS unsigned char* lds, const Gemm g, const Sched& S, const Epi& E) {
;     ...
;             PG8_WAIT_V(8); PG8_WAIT_L(0); PG8_BAR; PG8_MMA(1, 0, At, B0); PG8_MMA(1, 1, At, B1); PG8_BAR; PG8_SCHED;
;             PG8_LDB(B0, 1, 0); PG8_LDB(B1, 1, 1); PG8_SCHED; PG8_LDA(At, 1, 0); PG8_STAGE(PG8_SA(0, 1), a2 + hstepA, voffA);
;             PG8_WAIT_V(8); PG8_WAIT_L(0); PG8_BAR; PG8_MMA(0, 0, At, B0); PG8_MMA(0, 1, At, B1); PG8_BAR; PG8_SCHED;
;             PG8_LDA(At, 1, 1); PG8_STAGE(PG8_SB(1, 0), b3, voffB); PG8_STAGE(PG8_SB(1, 1), b3 + hstepB, voffB); PG8_STAGE(PG8_SA(1, 0), a3, voffA);
;             PG8_WAIT_V(8); PG8_WAIT_L(0); PG8_BAR; PG8_MMA(1, 0, At, B0); PG8_MMA(1, 1, At, B1); PG8_BAR; PG8_SCHED;
	s_setprio 1
	v_mfma_f32_16x16x32_bf16 v[62:65], v[140:143], v[176:179], 0
	v_mfma_f32_16x16x32_bf16 v[58:61], v[148:151], v[176:179], 0
	v_mfma_f32_16x16x32_bf16 v[54:57], v[140:143], v[184:187], 0
	v_mfma_f32_16x16x32_bf16 v[46:49], v[148:151], v[184:187], 0
	v_mfma_f32_16x16x32_bf16 v[38:41], v[140:143], v[206:209], 0
	v_mfma_f32_16x16x32_bf16 v[30:33], v[148:151], v[206:209], 0
	v_mfma_f32_16x16x32_bf16 v[22:25], v[140:143], v[214:217], 0
	v_mfma_f32_16x16x32_bf16 v[14:17], v[148:151], v[214:217], 0
	v_mfma_f32_16x16x32_bf16 v[62:65], v[144:147], v[180:183], v[62:65]
	v_mfma_f32_16x16x32_bf16 v[58:61], v[156:159], v[180:183], v[58:61]
	v_mfma_f32_16x16x32_bf16 v[54:57], v[144:147], v[188:191], v[54:57]
	v_mfma_f32_16x16x32_bf16 v[46:49], v[156:159], v[188:191], v[46:49]
	v_mfma_f32_16x16x32_bf16 v[38:41], v[144:147], v[210:213], v[38:41]
	v_mfma_f32_16x16x32_bf16 v[30:33], v[156:159], v[210:213], v[30:33]
	v_mfma_f32_16x16x32_bf16 v[22:25], v[144:147], v[218:221], v[22:25]
	v_mfma_f32_16x16x32_bf16 v[14:17], v[156:159], v[218:221], v[14:17]
	v_mfma_f32_16x16x32_bf16 v[50:53], v[160:163], v[176:179], 0
	v_mfma_f32_16x16x32_bf16 v[42:45], v[168:171], v[176:179], 0
	v_mfma_f32_16x16x32_bf16 v[34:37], v[160:163], v[184:187], 0
	v_mfma_f32_16x16x32_bf16 v[26:29], v[168:171], v[184:187], 0
	v_mfma_f32_16x16x32_bf16 v[18:21], v[160:163], v[206:209], 0
	v_mfma_f32_16x16x32_bf16 v[10:13], v[168:171], v[206:209], 0
	v_mfma_f32_16x16x32_bf16 v[6:9], v[160:163], v[214:217], 0
	v_mfma_f32_16x16x32_bf16 v[2:5], v[168:171], v[214:217], 0
	v_mfma_f32_16x16x32_bf16 v[50:53], v[164:167], v[180:183], v[50:53]
	v_mfma_f32_16x16x32_bf16 v[42:45], v[172:175], v[180:183], v[42:45]
	v_mfma_f32_16x16x32_bf16 v[34:37], v[164:167], v[188:191], v[34:37]
	v_mfma_f32_16x16x32_bf16 v[26:29], v[172:175], v[188:191], v[26:29]
	v_mfma_f32_16x16x32_bf16 v[18:21], v[164:167], v[210:213], v[18:21]
	v_mfma_f32_16x16x32_bf16 v[10:13], v[172:175], v[210:213], v[10:13]
	v_mfma_f32_16x16x32_bf16 v[6:9], v[164:167], v[218:221], v[6:9]
	v_mfma_f32_16x16x32_bf16 v[2:5], v[172:175], v[218:221], v[2:5]
	s_setprio 0
	s_barrier
	s_add_i32 s40, 0, 0x18000
	s_add_i32 s41, 0, 0x1c000
	v_add_u32_e32 v156, s40, v153
	v_add_u32_e32 v172, s41, v153
	ds_read_b128 v[140:143], v156
	ds_read_b128 v[144:147], v156 offset:1024
	ds_read_b128 v[148:151], v156 offset:2048
	ds_read_b128 v[156:159], v156 offset:3072
	ds_read_b128 v[160:163], v172
	ds_read_b128 v[164:167], v172 offset:1024
	ds_read_b128 v[168:171], v172 offset:2048
	ds_read_b128 v[172:175], v172 offset:3072
	s_add_u32 s20, s20, 0x4000
	s_addc_u32 s21, s21, 0
	s_mov_b32 m0, s26
	ds_read_b128 v[176:179], v155 offset:32768
	ds_read_b128 v[180:183], v155 offset:33792
	ds_read_b128 v[184:187], v155 offset:34816
	ds_read_b128 v[188:191], v155 offset:35840
	ds_read_b128 v[206:209], v155 offset:36864
	ds_read_b128 v[210:213], v155 offset:37888
	ds_read_b128 v[214:217], v155 offset:38912
	ds_read_b128 v[218:221], v155 offset:39936
	global_load_lds_dwordx4 v134, s[20:21]
	v_lshl_add_u64 v[224:225], s[20:21], 0, v[132:133]
	s_mov_b32 m0, s27
	s_nop 0
	global_load_lds_dwordx4 v132, s[20:21]
	s_waitcnt vmcnt(8)
	s_waitcnt lgkmcnt(0)
	s_barrier
	s_setprio 1
	v_mfma_f32_16x16x32_bf16 v[126:129], v[140:143], v[176:179], v[126:129]
	v_mfma_f32_16x16x32_bf16 v[122:125], v[148:151], v[176:179], v[122:125]
	v_mfma_f32_16x16x32_bf16 v[118:121], v[140:143], v[184:187], v[118:121]
	v_mfma_f32_16x16x32_bf16 v[114:117], v[148:151], v[184:187], v[114:117]
	v_mfma_f32_16x16x32_bf16 v[106:109], v[140:143], v[206:209], v[106:109]
	v_mfma_f32_16x16x32_bf16 v[98:101], v[148:151], v[206:209], v[98:101]
	v_mfma_f32_16x16x32_bf16 v[90:93], v[140:143], v[214:217], v[90:93]
	v_mfma_f32_16x16x32_bf16 v[82:85], v[148:151], v[214:217], v[82:85]
	v_mfma_f32_16x16x32_bf16 v[126:129], v[144:147], v[180:183], v[126:129]
	v_mfma_f32_16x16x32_bf16 v[122:125], v[156:159], v[180:183], v[122:125]
	v_mfma_f32_16x16x32_bf16 v[118:121], v[144:147], v[188:191], v[118:121]
	v_mfma_f32_16x16x32_bf16 v[114:117], v[156:159], v[188:191], v[114:117]
	v_mfma_f32_16x16x32_bf16 v[106:109], v[144:147], v[210:213], v[106:109]
	v_mfma_f32_16x16x32_bf16 v[98:101], v[156:159], v[210:213], v[98:101]
	v_mfma_f32_16x16x32_bf16 v[90:93], v[144:147], v[218:221], v[90:93]
	v_mfma_f32_16x16x32_bf16 v[82:85], v[156:159], v[218:221], v[82:85]
	v_mfma_f32_16x16x32_bf16 v[110:113], v[160:163], v[176:179], v[110:113]
	v_mfma_f32_16x16x32_bf16 v[102:105], v[168:171], v[176:179], v[102:105]
	v_mfma_f32_16x16x32_bf16 v[94:97], v[160:163], v[184:187], v[94:97]
	v_mfma_f32_16x16x32_bf16 v[86:89], v[168:171], v[184:187], v[86:89]
	v_mfma_f32_16x16x32_bf16 v[78:81], v[160:163], v[206:209], v[78:81]
	v_mfma_f32_16x16x32_bf16 v[74:77], v[168:171], v[206:209], v[74:77]
	v_mfma_f32_16x16x32_bf16 v[70:73], v[160:163], v[214:217], v[70:73]
	v_mfma_f32_16x16x32_bf16 v[66:69], v[168:171], v[214:217], v[66:69]
	v_mfma_f32_16x16x32_bf16 v[110:113], v[164:167], v[180:183], v[110:113]
	v_mfma_f32_16x16x32_bf16 v[102:105], v[172:175], v[180:183], v[102:105]
	v_mfma_f32_16x16x32_bf16 v[94:97], v[164:167], v[188:191], v[94:97]
	v_mfma_f32_16x16x32_bf16 v[86:89], v[172:175], v[188:191], v[86:89]
	v_mfma_f32_16x16x32_bf16 v[78:81], v[164:167], v[210:213], v[78:81]
	v_mfma_f32_16x16x32_bf16 v[74:77], v[172:175], v[210:213], v[74:77]
	v_mfma_f32_16x16x32_bf16 v[70:73], v[164:167], v[218:221], v[70:73]
	v_mfma_f32_16x16x32_bf16 v[66:69], v[172:175], v[218:221], v[66:69]
	s_setprio 0
	s_barrier
; #define PG8_STAGE(bufoff, gbase, voff) do { _Pragma("unroll") for (int _i = 0; _i < 2; ++_i) \
;         __builtin_amdgcn_global_load_lds((const unsigned*)((const char*)(gbase) + (voff)[_i]), (PG8_LAS unsigned*)(lds + (bufoff) + ldsw + _i * 8192), 16, 0, 0); } while (0)
; #define PG8_LDA(dst, b, h) do { _Pragma("unroll") for (int m = 0; m < 4; ++m) _Pragma("unroll") for (int k = 0; k < 2; ++k) dst[m][k] = *(const PG8_LAS bf16x8*)(lds + PG8_SA(b, h) + aoff + m * 2048 + k * 1024); } while (0)
; #define PG8_LDB(dst, b, h) do { _Pragma("unroll") for (int n = 0; n < 2; ++n) _Pragma("unroll") for (int k = 0; k < 2; ++k) dst[n][k] = *(const PG8_LAS bf16x8*)(lds + PG8_SB(b, h) + boff + n * 2048 + k * 1024); } while (0)
; #define PG8_MMA(ai, bj, At, Bt) do { __builtin_amdgcn_s_setprio(1); _Pragma("unroll") for (int m = 0; m < 4; ++m) _Pragma("unroll") for (int n = 0; n < 2; ++n) _Pragma("unroll") for (int k = 0; k < 2; ++k) \
;         acc[ai][bj][m][n] = __builtin_amdgcn_mfma_f32_16x16x32_bf16(Bt[n][k], At[m][k], acc[ai][bj][m][n], 0, 0, 0); __builtin_amdgcn_s_setprio(0); } while (0)
; #define PG8_BAR __builtin_amdgcn_s_barrier()
; template <class Epi, class Sched, bool ALIGN_EPI = false, bool SP2 = false>
; __device__ __forceinline__ void gemm_phase(PG8_LAS unsigned char* lds, const Gemm g, const Sched& S, const Epi& E) {
;     ...
;             const bool last = (t == nt - 2);
;             const char* a1 = cA + (size_t)(t + 1) * kstepA;
;             const char* a2 = last ? nA : cA + (size_t)(t + 2) * kstepA; const char* b2 = last ? nB : cB + (size_t)(t + 2) * kstep;
;             const char* a3 = a2 + kstepA; const char* b3 = b2 + kstep;
;             if (last && has_next) S.a_ready(nxt);
;             if constexpr (SP2) {
;             PG8_LDB(B0, 0, 0); PG8_LDB(B1, 0, 1); PG8_SCHED; PG8_LDA(At, 0, 0); PG8_STAGE(PG8_SA(1, 1), a1 + hstepA, voffA);
;             PG8_WAIT_V(8); PG8_WAIT_L(0); PG8_BAR; PG8_MMA(0, 0, At, B0); PG8_MMA(0, 1, At, B1); PG8_BAR; PG8_SCHED;
;     ...
;             PG8_WAIT_V(8); PG8_WAIT_L(0); PG8_BAR; PG8_MMA(0, 0, At, B0); PG8_MMA(0, 1, At, B1); PG8_BAR; PG8_SCHED;
;             PG8_LDA(At, 1, 1); PG8_STAGE(PG8_SB(1, 0), b3, voffB); PG8_STAGE(PG8_SB(1, 1), b3 + hstepB, voffB); PG8_STAGE(PG8_SA(1, 0), a3, voffA);
;             PG8_WAIT_V(8); PG8_WAIT_L(0); PG8_BAR; PG8_MMA(1, 0, At, B0); PG8_MMA(1, 1, At, B1); PG8_BAR; PG8_SCHED;
	s_add_i32 s20, s40, s22
	v_lshl_add_u64 v[192:193], v[192:193], 0, s[78:79]
	s_mov_b32 m0, s20
	ds_read_b128 v[176:179], v155 offset:49152
	ds_read_b128 v[180:183], v155 offset:50176
	ds_read_b128 v[184:187], v155 offset:51200
	ds_read_b128 v[188:191], v155 offset:52224
	ds_read_b128 v[206:209], v155 offset:53248
	ds_read_b128 v[210:213], v155 offset:54272
	ds_read_b128 v[214:217], v155 offset:55296
	ds_read_b128 v[218:221], v155 offset:56320
	global_load_lds_dwordx4 v[192:193], off
	s_add_i32 m0, s20, 0x2000
	s_add_u32 s18, s18, 0xb0080
	v_lshl_add_u64 v[192:193], v[222:223], 0, s[78:79]
	s_addc_u32 s19, s19, 0
	s_add_i32 s20, s41, s22
	global_load_lds_dwordx4 v[192:193], off
	v_lshl_add_u64 v[192:193], s[18:19], 0, v[0:1]
	s_mov_b32 m0, s20
	s_nop 0
	global_load_lds_dwordx4 v[192:193], off
	s_add_i32 m0, s20, 0x2000
	s_nop 0
	global_load_lds_dwordx4 v130, s[18:19]
	s_mov_b32 m0, s28
	s_nop 0
	global_load_lds_dwordx4 v134, s[16:17]
	s_mov_b32 m0, s29
	s_nop 0
	global_load_lds_dwordx4 v132, s[16:17]
	s_waitcnt vmcnt(8)
	s_waitcnt lgkmcnt(0)
	s_barrier
	s_setprio 1
	v_mfma_f32_16x16x32_bf16 v[62:65], v[140:143], v[176:179], v[62:65]
	v_mfma_f32_16x16x32_bf16 v[58:61], v[148:151], v[176:179], v[58:61]
	v_mfma_f32_16x16x32_bf16 v[54:57], v[140:143], v[184:187], v[54:57]
	v_mfma_f32_16x16x32_bf16 v[46:49], v[148:151], v[184:187], v[46:49]
	v_mfma_f32_16x16x32_bf16 v[38:41], v[140:143], v[206:209], v[38:41]
	v_mfma_f32_16x16x32_bf16 v[30:33], v[148:151], v[206:209], v[30:33]
	v_mfma_f32_16x16x32_bf16 v[22:25], v[140:143], v[214:217], v[22:25]
	v_mfma_f32_16x16x32_bf16 v[14:17], v[148:151], v[214:217], v[14:17]
	v_mfma_f32_16x16x32_bf16 v[62:65], v[144:147], v[180:183], v[62:65]
	v_mfma_f32_16x16x32_bf16 v[58:61], v[156:159], v[180:183], v[58:61]
	v_mfma_f32_16x16x32_bf16 v[54:57], v[144:147], v[188:191], v[54:57]
	v_mfma_f32_16x16x32_bf16 v[46:49], v[156:159], v[188:191], v[46:49]
	v_mfma_f32_16x16x32_bf16 v[38:41], v[144:147], v[210:213], v[38:41]
	v_mfma_f32_16x16x32_bf16 v[30:33], v[156:159], v[210:213], v[30:33]
	v_mfma_f32_16x16x32_bf16 v[22:25], v[144:147], v[218:221], v[22:25]
	v_mfma_f32_16x16x32_bf16 v[14:17], v[156:159], v[218:221], v[14:17]
	v_mfma_f32_16x16x32_bf16 v[50:53], v[160:163], v[176:179], v[50:53]
	v_mfma_f32_16x16x32_bf16 v[42:45], v[168:171], v[176:179], v[42:45]
	v_mfma_f32_16x16x32_bf16 v[34:37], v[160:163], v[184:187], v[34:37]
	v_mfma_f32_16x16x32_bf16 v[26:29], v[168:171], v[184:187], v[26:29]
	v_mfma_f32_16x16x32_bf16 v[18:21], v[160:163], v[206:209], v[18:21]
	v_mfma_f32_16x16x32_bf16 v[10:13], v[168:171], v[206:209], v[10:13]
	v_mfma_f32_16x16x32_bf16 v[6:9], v[160:163], v[214:217], v[6:9]
	v_mfma_f32_16x16x32_bf16 v[2:5], v[168:171], v[214:217], v[2:5]
	v_mfma_f32_16x16x32_bf16 v[50:53], v[164:167], v[180:183], v[50:53]
	v_mfma_f32_16x16x32_bf16 v[42:45], v[172:175], v[180:183], v[42:45]
	v_mfma_f32_16x16x32_bf16 v[34:37], v[164:167], v[188:191], v[34:37]
	v_mfma_f32_16x16x32_bf16 v[26:29], v[172:175], v[188:191], v[26:29]
	v_mfma_f32_16x16x32_bf16 v[18:21], v[164:167], v[210:213], v[18:21]
	v_mfma_f32_16x16x32_bf16 v[10:13], v[172:175], v[210:213], v[10:13]
	v_mfma_f32_16x16x32_bf16 v[6:9], v[164:167], v[218:221], v[6:9]
	v_mfma_f32_16x16x32_bf16 v[2:5], v[172:175], v[218:221], v[2:5]
	s_setprio 0
	s_barrier
	s_add_i32 s39, s39, 2
	s_add_u32 s0, s0, 0x800000
	s_addc_u32 s1, s1, 0
	s_add_u32 s37, s37, 0x100
	s_addc_u32 s38, s38, 0
.LBB0_35:
	s_add_u32 s16, s0, 0x3fc000
	s_addc_u32 s17, s1, 0
	s_cmp_eq_u32 s39, 40
	s_cselect_b32 s20, s36, s16
	s_cselect_b32 s21, s11, s17
	s_cselect_b32 s18, s12, s37
	s_cselect_b32 s19, s13, s38
	s_add_u32 s16, s20, 0x400000
	s_addc_u32 s17, s21, 0
	s_add_i32 s40, 0, 0x10000
	s_add_i32 s42, 0, 0x14000
	v_add_u32_e32 v156, s40, v153
	v_add_u32_e32 v172, s42, v153
	ds_read_b128 v[140:143], v156
	ds_read_b128 v[144:147], v156 offset:1024
	ds_read_b128 v[148:151], v156 offset:2048
	ds_read_b128 v[156:159], v156 offset:3072
	ds_read_b128 v[160:163], v172
	ds_read_b128 v[164:167], v172 offset:1024
	ds_read_b128 v[168:171], v172 offset:2048
	ds_read_b128 v[172:175], v172 offset:3072
	s_add_i32 m0, s23, 0xc000
	ds_read_b128 v[176:179], v155
	ds_read_b128 v[180:183], v155 offset:1024
	ds_read_b128 v[184:187], v155 offset:2048
	ds_read_b128 v[188:191], v155 offset:3072
	ds_read_b128 v[206:209], v155 offset:4096
	ds_read_b128 v[210:213], v155 offset:5120
	ds_read_b128 v[214:217], v155 offset:6144
	ds_read_b128 v[218:221], v155 offset:7168
	global_load_lds_dwordx4 v136, s[0:1]
	s_add_i32 m0, s23, 0xe000
	s_nop 0
	global_load_lds_dwordx4 v138, s[0:1]
	s_waitcnt vmcnt(8)
	s_waitcnt lgkmcnt(0)
	s_barrier
; #define PG8_STAGE(bufoff, gbase, voff) do { _Pragma("unroll") for (int _i = 0; _i < 2; ++_i) \
;         __builtin_amdgcn_global_load_lds((const unsigned*)((const char*)(gbase) + (voff)[_i]), (PG8_LAS unsigned*)(lds + (bufoff) + ldsw + _i * 8192), 16, 0, 0); } while (0)
; #define PG8_LDA(dst, b, h) do { _Pragma("unroll") for (int m = 0; m < 4; ++m) _Pragma("unroll") for (int k = 0; k < 2; ++k) dst[m][k] = *(const PG8_LAS bf16x8*)(lds + PG8_SA(b, h) + aoff + m * 2048 + k * 1024); } while (0)
; #define PG8_LDB(dst, b, h) do { _Pragma("unroll") for (int n = 0; n < 2; ++n) _Pragma("unroll") for (int k = 0; k < 2; ++k) dst[n][k] = *(const PG8_LAS bf16x8*)(lds + PG8_SB(b, h) + boff + n * 2048 + k * 1024); } while (0)
; #define PG8_MMA(ai, bj, At, Bt) do { __builtin_amdgcn_s_setprio(1); _Pragma("unroll") for (int m = 0; m < 4; ++m) _Pragma("unroll") for (int n = 0; n < 2; ++n) _Pragma("unroll") for (int k = 0; k < 2; ++k) \
;         acc[ai][bj][m][n] = __builtin_amdgcn_mfma_f32_16x16x32_bf16(Bt[n][k], At[m][k], acc[ai][bj][m][n], 0, 0, 0); __builtin_amdgcn_s_setprio(0); } while (0)
; #define PG8_WAIT_V(n) asm volatile("s_waitcnt vmcnt(" #n ")" ::: "memory")
; #define PG8_WAIT_L(n) asm volatile("s_waitcnt lgkmcnt(" #n ")" ::: "memory")
; #define PG8_BAR __builtin_amdgcn_s_barrier()
; #define PG8_SCHED __builtin_amdgcn_sched_barrier(0)
; template <class Epi, class Sched, bool ALIGN_EPI = false, bool SP2 = false>
; __device__ __forceinline__ void gemm_phase(PG8_LAS unsigned char* lds, const Gemm g, const Sched& S, const Epi& E) {
;     ...
;             PG8_WAIT_V(8); PG8_WAIT_L(0); PG8_BAR; PG8_MMA(0, 0, At, B0); PG8_MMA(0, 1, At, B1); PG8_BAR; PG8_SCHED;
;             PG8_LDA(At, 0, 1); PG8_STAGE(PG8_SB(0, 0), b2, voffB); PG8_STAGE(PG8_SB(0, 1), b2 + hstepB, voffB); PG8_STAGE(PG8_SA(0, 0), a2, voffA);
;             PG8_WAIT_V(8); PG8_WAIT_L(0); PG8_BAR; PG8_MMA(1, 0, At, B0); PG8_MMA(1, 1, At, B1); PG8_BAR; PG8_SCHED;
;             PG8_LDB(B0, 1, 0); PG8_LDB(B1, 1, 1); PG8_SCHED; PG8_LDA(At, 1, 0); PG8_STAGE(PG8_SA(0, 1), a2 + hstepA, voffA);
;             PG8_WAIT_V(8); PG8_WAIT_L(0); PG8_BAR; PG8_MMA(0, 0, At, B0); PG8_MMA(0, 1, At, B1); PG8_BAR; PG8_SCHED;
	s_setprio 1
	v_mfma_f32_16x16x32_bf16 v[126:129], v[140:143], v[176:179], v[126:129]
	v_mfma_f32_16x16x32_bf16 v[122:125], v[148:151], v[176:179], v[122:125]
	v_mfma_f32_16x16x32_bf16 v[118:121], v[140:143], v[184:187], v[118:121]
	v_mfma_f32_16x16x32_bf16 v[114:117], v[148:151], v[184:187], v[114:117]
	v_mfma_f32_16x16x32_bf16 v[106:109], v[140:143], v[206:209], v[106:109]
	v_mfma_f32_16x16x32_bf16 v[98:101], v[148:151], v[206:209], v[98:101]
	v_mfma_f32_16x16x32_bf16 v[90:93], v[140:143], v[214:217], v[90:93]
	v_mfma_f32_16x16x32_bf16 v[82:85], v[148:151], v[214:217], v[82:85]
	v_mfma_f32_16x16x32_bf16 v[126:129], v[144:147], v[180:183], v[126:129]
	v_mfma_f32_16x16x32_bf16 v[122:125], v[156:159], v[180:183], v[122:125]
	v_mfma_f32_16x16x32_bf16 v[118:121], v[144:147], v[188:191], v[118:121]
	v_mfma_f32_16x16x32_bf16 v[114:117], v[156:159], v[188:191], v[114:117]
	v_mfma_f32_16x16x32_bf16 v[106:109], v[144:147], v[210:213], v[106:109]
	v_mfma_f32_16x16x32_bf16 v[98:101], v[156:159], v[210:213], v[98:101]
	v_mfma_f32_16x16x32_bf16 v[90:93], v[144:147], v[218:221], v[90:93]
	v_mfma_f32_16x16x32_bf16 v[82:85], v[156:159], v[218:221], v[82:85]
	v_mfma_f32_16x16x32_bf16 v[110:113], v[160:163], v[176:179], v[110:113]
	v_mfma_f32_16x16x32_bf16 v[102:105], v[168:171], v[176:179], v[102:105]
	v_mfma_f32_16x16x32_bf16 v[94:97], v[160:163], v[184:187], v[94:97]
	v_mfma_f32_16x16x32_bf16 v[86:89], v[168:171], v[184:187], v[86:89]
	v_mfma_f32_16x16x32_bf16 v[78:81], v[160:163], v[206:209], v[78:81]
	v_mfma_f32_16x16x32_bf16 v[74:77], v[168:171], v[206:209], v[74:77]
	v_mfma_f32_16x16x32_bf16 v[70:73], v[160:163], v[214:217], v[70:73]
	v_mfma_f32_16x16x32_bf16 v[66:69], v[168:171], v[214:217], v[66:69]
	v_mfma_f32_16x16x32_bf16 v[110:113], v[164:167], v[180:183], v[110:113]
	v_mfma_f32_16x16x32_bf16 v[102:105], v[172:175], v[180:183], v[102:105]
	v_mfma_f32_16x16x32_bf16 v[94:97], v[164:167], v[188:191], v[94:97]
	v_mfma_f32_16x16x32_bf16 v[86:89], v[172:175], v[188:191], v[86:89]
	v_mfma_f32_16x16x32_bf16 v[78:81], v[164:167], v[210:213], v[78:81]
	v_mfma_f32_16x16x32_bf16 v[74:77], v[172:175], v[210:213], v[74:77]
	v_mfma_f32_16x16x32_bf16 v[70:73], v[164:167], v[218:221], v[70:73]
	v_mfma_f32_16x16x32_bf16 v[66:69], v[172:175], v[218:221], v[66:69]
	s_setprio 0
	s_barrier
	s_add_i32 s40, s40, s22
	v_lshl_add_u64 v[192:193], s[18:19], 0, v[0:1]
	s_mov_b32 m0, s40
	ds_read_b128 v[176:179], v155 offset:16384
	ds_read_b128 v[180:183], v155 offset:17408
	ds_read_b128 v[184:187], v155 offset:18432
	ds_read_b128 v[188:191], v155 offset:19456
	ds_read_b128 v[206:209], v155 offset:20480
	ds_read_b128 v[210:213], v155 offset:21504
	ds_read_b128 v[214:217], v155 offset:22528
	ds_read_b128 v[218:221], v155 offset:23552
	global_load_lds_dwordx4 v[192:193], off
	s_add_i32 m0, s40, 0x2000
	s_add_u32 s40, s18, 0xb0000
	v_lshl_add_u64 v[222:223], s[18:19], 0, v[130:131]
	s_addc_u32 s41, s19, 0
	s_add_i32 s42, s42, s22
	global_load_lds_dwordx4 v130, s[18:19]
	v_lshl_add_u64 v[224:225], s[40:41], 0, v[0:1]
	s_mov_b32 m0, s42
	s_nop 0
	global_load_lds_dwordx4 v[224:225], off
	s_add_i32 m0, s42, 0x2000
	s_nop 0
	global_load_lds_dwordx4 v130, s[40:41]
	s_mov_b32 m0, s23
	s_nop 0
	global_load_lds_dwordx4 v134, s[20:21]
	s_mov_b32 m0, s25
	s_nop 0
	global_load_lds_dwordx4 v132, s[20:21]
	s_waitcnt vmcnt(8)
	s_waitcnt lgkmcnt(0)
	s_barrier
	s_setprio 1
	v_mfma_f32_16x16x32_bf16 v[62:65], v[140:143], v[176:179], v[62:65]
	v_mfma_f32_16x16x32_bf16 v[58:61], v[148:151], v[176:179], v[58:61]
	v_mfma_f32_16x16x32_bf16 v[54:57], v[140:143], v[184:187], v[54:57]
	v_mfma_f32_16x16x32_bf16 v[46:49], v[148:151], v[184:187], v[46:49]
	v_mfma_f32_16x16x32_bf16 v[38:41], v[140:143], v[206:209], v[38:41]
	v_mfma_f32_16x16x32_bf16 v[30:33], v[148:151], v[206:209], v[30:33]
	v_mfma_f32_16x16x32_bf16 v[22:25], v[140:143], v[214:217], v[22:25]
	v_mfma_f32_16x16x32_bf16 v[14:17], v[148:151], v[214:217], v[14:17]
	v_mfma_f32_16x16x32_bf16 v[62:65], v[144:147], v[180:183], v[62:65]
	v_mfma_f32_16x16x32_bf16 v[58:61], v[156:159], v[180:183], v[58:61]
	v_mfma_f32_16x16x32_bf16 v[54:57], v[144:147], v[188:191], v[54:57]
	v_mfma_f32_16x16x32_bf16 v[46:49], v[156:159], v[188:191], v[46:49]
	v_mfma_f32_16x16x32_bf16 v[38:41], v[144:147], v[210:213], v[38:41]
	v_mfma_f32_16x16x32_bf16 v[30:33], v[156:159], v[210:213], v[30:33]
	v_mfma_f32_16x16x32_bf16 v[22:25], v[144:147], v[218:221], v[22:25]
	v_mfma_f32_16x16x32_bf16 v[14:17], v[156:159], v[218:221], v[14:17]
	v_mfma_f32_16x16x32_bf16 v[50:53], v[160:163], v[176:179], v[50:53]
	v_mfma_f32_16x16x32_bf16 v[42:45], v[168:171], v[176:179], v[42:45]
	v_mfma_f32_16x16x32_bf16 v[34:37], v[160:163], v[184:187], v[34:37]
	v_mfma_f32_16x16x32_bf16 v[26:29], v[168:171], v[184:187], v[26:29]
	v_mfma_f32_16x16x32_bf16 v[18:21], v[160:163], v[206:209], v[18:21]
	v_mfma_f32_16x16x32_bf16 v[10:13], v[168:171], v[206:209], v[10:13]
	v_mfma_f32_16x16x32_bf16 v[6:9], v[160:163], v[214:217], v[6:9]
	v_mfma_f32_16x16x32_bf16 v[2:5], v[168:171], v[214:217], v[2:5]
	v_mfma_f32_16x16x32_bf16 v[50:53], v[164:167], v[180:183], v[50:53]
	v_mfma_f32_16x16x32_bf16 v[42:45], v[172:175], v[180:183], v[42:45]
	v_mfma_f32_16x16x32_bf16 v[34:37], v[164:167], v[188:191], v[34:37]
	v_mfma_f32_16x16x32_bf16 v[26:29], v[172:175], v[188:191], v[26:29]
	v_mfma_f32_16x16x32_bf16 v[18:21], v[164:167], v[210:213], v[18:21]
	v_mfma_f32_16x16x32_bf16 v[10:13], v[172:175], v[210:213], v[10:13]
	v_mfma_f32_16x16x32_bf16 v[6:9], v[164:167], v[218:221], v[6:9]
	v_mfma_f32_16x16x32_bf16 v[2:5], v[172:175], v[218:221], v[2:5]
	s_setprio 0
	s_barrier
; #define PG8_STAGE(bufoff, gbase, voff) do { _Pragma("unroll") for (int _i = 0; _i < 2; ++_i) \
;         __builtin_amdgcn_global_load_lds((const unsigned*)((const char*)(gbase) + (voff)[_i]), (PG8_LAS unsigned*)(lds + (bufoff) + ldsw + _i * 8192), 16, 0, 0); } while (0)
; #define PG8_LDA(dst, b, h) do { _Pragma("unroll") for (int m = 0; m < 4; ++m) _Pragma("unroll") for (int k = 0; k < 2; ++k) dst[m][k] = *(const PG8_LAS bf16x8*)(lds + PG8_SA(b, h) + aoff + m * 2048 + k * 1024); } while (0)
; #define PG8_LDB(dst, b, h) do { _Pragma("unroll") for (int n = 0; n < 2; ++n) _Pragma("unroll") for (int k = 0; k < 2; ++k) dst[n][k] = *(const PG8_LAS bf16x8*)(lds + PG8_SB(b, h) + boff + n * 2048 + k * 1024); } while (0)
; #define PG8_MMA(ai, bj, At, Bt) do { __builtin_amdgcn_s_setprio(1); _Pragma("unroll") for (int m = 0; m < 4; ++m) _Pragma("unroll") for (int n = 0; n < 2; ++n) _Pragma("unroll") for (int k = 0; k < 2; ++k) \
;         acc[ai][bj][m][n] = __builtin_amdgcn_mfma_f32_16x16x32_bf16(Bt[n][k], At[m][k], acc[ai][bj][m][n], 0, 0, 0); __builtin_amdgcn_s_setprio(0); } while (0)
; #define PG8_WAIT_V(n) asm volatile("s_waitcnt vmcnt(" #n ")" ::: "memory")
; #define PG8_WAIT_L(n) asm volatile("s_waitcnt lgkmcnt(" #n ")" ::: "memory")
; #define PG8_BAR __builtin_amdgcn_s_barrier()
; #define PG8_SCHED __builtin_amdgcn_sched_barrier(0)
; template <class Epi, class Sched, bool ALIGN_EPI = false, bool SP2 = false>
; __device__ __forceinline__ void gemm_phase(PG8_LAS unsigned char* lds, const Gemm g, const Sched& S, const Epi& E) {
;     ...
;             PG8_LDB(B0, 1, 0); PG8_LDB(B1, 1, 1); PG8_SCHED; PG8_LDA(At, 1, 0); PG8_STAGE(PG8_SA(0, 1), a2 + hstepA, voffA);
;             PG8_WAIT_V(8); PG8_WAIT_L(0); PG8_BAR; PG8_MMA(0, 0, At, B0); PG8_MMA(0, 1, At, B1); PG8_BAR; PG8_SCHED;
;             PG8_LDA(At, 1, 1); PG8_STAGE(PG8_SB(1, 0), b3, voffB); PG8_STAGE(PG8_SB(1, 1), b3 + hstepB, voffB); PG8_STAGE(PG8_SA(1, 0), a3, voffA);
;             PG8_WAIT_V(8); PG8_WAIT_L(0); PG8_BAR; PG8_MMA(1, 0, At, B0); PG8_MMA(1, 1, At, B1); PG8_BAR; PG8_SCHED;
	s_add_i32 s40, 0, 0x18000
	s_add_i32 s41, 0, 0x1c000
	v_add_u32_e32 v156, s40, v153
	v_add_u32_e32 v172, s41, v153
	ds_read_b128 v[140:143], v156
	ds_read_b128 v[144:147], v156 offset:1024
	ds_read_b128 v[148:151], v156 offset:2048
	ds_read_b128 v[156:159], v156 offset:3072
	ds_read_b128 v[160:163], v172
	ds_read_b128 v[164:167], v172 offset:1024
	ds_read_b128 v[168:171], v172 offset:2048
	ds_read_b128 v[172:175], v172 offset:3072
	s_add_u32 s20, s20, 0x4000
	s_addc_u32 s21, s21, 0
	s_mov_b32 m0, s26
	ds_read_b128 v[176:179], v155 offset:32768
	ds_read_b128 v[180:183], v155 offset:33792
	ds_read_b128 v[184:187], v155 offset:34816
	ds_read_b128 v[188:191], v155 offset:35840
	ds_read_b128 v[206:209], v155 offset:36864
	ds_read_b128 v[210:213], v155 offset:37888
	ds_read_b128 v[214:217], v155 offset:38912
	ds_read_b128 v[218:221], v155 offset:39936
	global_load_lds_dwordx4 v134, s[20:21]
	v_lshl_add_u64 v[224:225], s[20:21], 0, v[132:133]
	s_mov_b32 m0, s27
	s_nop 0
	global_load_lds_dwordx4 v132, s[20:21]
	s_waitcnt vmcnt(8)
	s_waitcnt lgkmcnt(0)
	s_barrier
	s_setprio 1
	v_mfma_f32_16x16x32_bf16 v[126:129], v[140:143], v[176:179], v[126:129]
	v_mfma_f32_16x16x32_bf16 v[122:125], v[148:151], v[176:179], v[122:125]
	v_mfma_f32_16x16x32_bf16 v[118:121], v[140:143], v[184:187], v[118:121]
	v_mfma_f32_16x16x32_bf16 v[114:117], v[148:151], v[184:187], v[114:117]
	v_mfma_f32_16x16x32_bf16 v[106:109], v[140:143], v[206:209], v[106:109]
	v_mfma_f32_16x16x32_bf16 v[98:101], v[148:151], v[206:209], v[98:101]
	v_mfma_f32_16x16x32_bf16 v[90:93], v[140:143], v[214:217], v[90:93]
	v_mfma_f32_16x16x32_bf16 v[82:85], v[148:151], v[214:217], v[82:85]
	v_mfma_f32_16x16x32_bf16 v[126:129], v[144:147], v[180:183], v[126:129]
	v_mfma_f32_16x16x32_bf16 v[122:125], v[156:159], v[180:183], v[122:125]
	v_mfma_f32_16x16x32_bf16 v[118:121], v[144:147], v[188:191], v[118:121]
	v_mfma_f32_16x16x32_bf16 v[114:117], v[156:159], v[188:191], v[114:117]
	v_mfma_f32_16x16x32_bf16 v[106:109], v[144:147], v[210:213], v[106:109]
	v_mfma_f32_16x16x32_bf16 v[98:101], v[156:159], v[210:213], v[98:101]
	v_mfma_f32_16x16x32_bf16 v[90:93], v[144:147], v[218:221], v[90:93]
	v_mfma_f32_16x16x32_bf16 v[82:85], v[156:159], v[218:221], v[82:85]
	v_mfma_f32_16x16x32_bf16 v[110:113], v[160:163], v[176:179], v[110:113]
	v_mfma_f32_16x16x32_bf16 v[102:105], v[168:171], v[176:179], v[102:105]
	v_mfma_f32_16x16x32_bf16 v[94:97], v[160:163], v[184:187], v[94:97]
	v_mfma_f32_16x16x32_bf16 v[86:89], v[168:171], v[184:187], v[86:89]
	v_mfma_f32_16x16x32_bf16 v[78:81], v[160:163], v[206:209], v[78:81]
	v_mfma_f32_16x16x32_bf16 v[74:77], v[168:171], v[206:209], v[74:77]
	v_mfma_f32_16x16x32_bf16 v[70:73], v[160:163], v[214:217], v[70:73]
	v_mfma_f32_16x16x32_bf16 v[66:69], v[168:171], v[214:217], v[66:69]
	v_mfma_f32_16x16x32_bf16 v[110:113], v[164:167], v[180:183], v[110:113]
	v_mfma_f32_16x16x32_bf16 v[102:105], v[172:175], v[180:183], v[102:105]
	v_mfma_f32_16x16x32_bf16 v[94:97], v[164:167], v[188:191], v[94:97]
	v_mfma_f32_16x16x32_bf16 v[86:89], v[172:175], v[188:191], v[86:89]
	v_mfma_f32_16x16x32_bf16 v[78:81], v[164:167], v[210:213], v[78:81]
	v_mfma_f32_16x16x32_bf16 v[74:77], v[172:175], v[210:213], v[74:77]
	v_mfma_f32_16x16x32_bf16 v[70:73], v[164:167], v[218:221], v[70:73]
	v_mfma_f32_16x16x32_bf16 v[66:69], v[172:175], v[218:221], v[66:69]
	s_setprio 0
	s_barrier
	s_add_i32 s20, s40, s22
	v_lshl_add_u64 v[192:193], v[192:193], 0, s[78:79]
	s_mov_b32 m0, s20
	ds_read_b128 v[176:179], v155 offset:49152
	ds_read_b128 v[180:183], v155 offset:50176
	ds_read_b128 v[184:187], v155 offset:51200
	ds_read_b128 v[188:191], v155 offset:52224
	ds_read_b128 v[206:209], v155 offset:53248
	ds_read_b128 v[210:213], v155 offset:54272
	ds_read_b128 v[214:217], v155 offset:55296
	ds_read_b128 v[218:221], v155 offset:56320
	global_load_lds_dwordx4 v[192:193], off
	s_add_i32 m0, s20, 0x2000
	s_add_u32 s18, s18, 0xb0080
	v_lshl_add_u64 v[192:193], v[222:223], 0, s[78:79]
	s_addc_u32 s19, s19, 0
	s_add_i32 s20, s41, s22
	global_load_lds_dwordx4 v[192:193], off
	v_lshl_add_u64 v[192:193], s[18:19], 0, v[0:1]
	s_mov_b32 m0, s20
	s_nop 0
	global_load_lds_dwordx4 v[192:193], off
	s_add_i32 m0, s20, 0x2000
	s_nop 0
	global_load_lds_dwordx4 v130, s[18:19]
	s_mov_b32 m0, s28
	s_nop 0
	global_load_lds_dwordx4 v134, s[16:17]
	s_mov_b32 m0, s29
	s_nop 0
	global_load_lds_dwordx4 v132, s[16:17]
	s_waitcnt vmcnt(8)
	s_waitcnt lgkmcnt(0)
	s_barrier
	s_setprio 1
	v_mfma_f32_16x16x32_bf16 v[62:65], v[140:143], v[176:179], v[62:65]
	v_mfma_f32_16x16x32_bf16 v[58:61], v[148:151], v[176:179], v[58:61]
	v_mfma_f32_16x16x32_bf16 v[54:57], v[140:143], v[184:187], v[54:57]
	v_mfma_f32_16x16x32_bf16 v[46:49], v[148:151], v[184:187], v[46:49]
	v_mfma_f32_16x16x32_bf16 v[38:41], v[140:143], v[206:209], v[38:41]
	v_mfma_f32_16x16x32_bf16 v[30:33], v[148:151], v[206:209], v[30:33]
	v_mfma_f32_16x16x32_bf16 v[22:25], v[140:143], v[214:217], v[22:25]
	v_mfma_f32_16x16x32_bf16 v[14:17], v[148:151], v[214:217], v[14:17]
	v_mfma_f32_16x16x32_bf16 v[62:65], v[144:147], v[180:183], v[62:65]
	v_mfma_f32_16x16x32_bf16 v[58:61], v[156:159], v[180:183], v[58:61]
	v_mfma_f32_16x16x32_bf16 v[54:57], v[144:147], v[188:191], v[54:57]
	v_mfma_f32_16x16x32_bf16 v[46:49], v[156:159], v[188:191], v[46:49]
	v_mfma_f32_16x16x32_bf16 v[38:41], v[144:147], v[210:213], v[38:41]
	v_mfma_f32_16x16x32_bf16 v[30:33], v[156:159], v[210:213], v[30:33]
	v_mfma_f32_16x16x32_bf16 v[22:25], v[144:147], v[218:221], v[22:25]
	v_mfma_f32_16x16x32_bf16 v[14:17], v[156:159], v[218:221], v[14:17]
	v_mfma_f32_16x16x32_bf16 v[50:53], v[160:163], v[176:179], v[50:53]
	v_mfma_f32_16x16x32_bf16 v[42:45], v[168:171], v[176:179], v[42:45]
	v_mfma_f32_16x16x32_bf16 v[34:37], v[160:163], v[184:187], v[34:37]
	v_mfma_f32_16x16x32_bf16 v[26:29], v[168:171], v[184:187], v[26:29]
	v_mfma_f32_16x16x32_bf16 v[18:21], v[160:163], v[206:209], v[18:21]
	v_mfma_f32_16x16x32_bf16 v[10:13], v[168:171], v[206:209], v[10:13]
	v_mfma_f32_16x16x32_bf16 v[6:9], v[160:163], v[214:217], v[6:9]
	v_mfma_f32_16x16x32_bf16 v[2:5], v[168:171], v[214:217], v[2:5]
	v_mfma_f32_16x16x32_bf16 v[50:53], v[164:167], v[180:183], v[50:53]
	v_mfma_f32_16x16x32_bf16 v[42:45], v[172:175], v[180:183], v[42:45]
	v_mfma_f32_16x16x32_bf16 v[34:37], v[164:167], v[188:191], v[34:37]
	v_mfma_f32_16x16x32_bf16 v[26:29], v[172:175], v[188:191], v[26:29]
	v_mfma_f32_16x16x32_bf16 v[18:21], v[164:167], v[210:213], v[18:21]
	v_mfma_f32_16x16x32_bf16 v[10:13], v[172:175], v[210:213], v[10:13]
	v_mfma_f32_16x16x32_bf16 v[6:9], v[164:167], v[218:221], v[6:9]
	v_mfma_f32_16x16x32_bf16 v[2:5], v[172:175], v[218:221], v[2:5]
	s_setprio 0
	s_barrier
	s_add_i32 s39, s39, 2
	s_add_u32 s0, s0, 0x800000
	s_addc_u32 s1, s1, 0
	s_add_u32 s37, s37, 0x100
	s_addc_u32 s38, s38, 0
	s_cmp_gt_u32 s39, 41
	s_cbranch_scc0 .LBB0_35
	s_and_b64 vcc, exec, s[8:9]
	s_cbranch_vccz .LBB0_38
	s_barrier

; #define PG8_STAGE(bufoff, gbase, voff) do { _Pragma("unroll") for (int _i = 0; _i < 2; ++_i) \
;         __builtin_amdgcn_global_load_lds((const unsigned*)((const char*)(gbase) + (voff)[_i]), (PG8_LAS unsigned*)(lds + (bufoff) + ldsw + _i * 8192), 16, 0, 0); } while (0)
; #define PG8_LDA(dst, b, h) do { _Pragma("unroll") for (int m = 0; m < 4; ++m) _Pragma("unroll") for (int k = 0; k < 2; ++k) dst[m][k] = *(const PG8_LAS bf16x8*)(lds + PG8_SA(b, h) + aoff + m * 2048 + k * 1024); } while (0)
; #define PG8_LDB(dst, b, h) do { _Pragma("unroll") for (int n = 0; n < 2; ++n) _Pragma("unroll") for (int k = 0; k < 2; ++k) dst[n][k] = *(const PG8_LAS bf16x8*)(lds + PG8_SB(b, h) + boff + n * 2048 + k * 1024); } while (0)
; #define PG8_WAIT_V(n) asm volatile("s_waitcnt vmcnt(" #n ")" ::: "memory")
; #define PG8_WAIT_L(n) asm volatile("s_waitcnt lgkmcnt(" #n ")" ::: "memory")
; #define PG8_BAR __builtin_amdgcn_s_barrier()
; #define PG8_SCHED __builtin_amdgcn_sched_barrier(0)
; template <class Epi, class Sched, bool ALIGN_EPI = false, bool SP2 = false>
; __device__ __forceinline__ void gemm_phase(PG8_LAS unsigned char* lds, const Gemm g, const Sched& S, const Epi& E) {
;     ...
;             const bool last = (t == nt - 2);
;             const char* a1 = cA + (size_t)(t + 1) * kstepA;
;             const char* a2 = last ? nA : cA + (size_t)(t + 2) * kstepA; const char* b2 = last ? nB : cB + (size_t)(t + 2) * kstep;
;             const char* a3 = a2 + kstepA; const char* b3 = b2 + kstep;
;             if (last && has_next) S.a_ready(nxt);
;             if constexpr (SP2) {
;             PG8_LDB(B0, 0, 0); PG8_LDB(B1, 0, 1); PG8_SCHED; PG8_LDA(At, 0, 0); PG8_STAGE(PG8_SA(1, 1), a1 + hstepA, voffA);
;             PG8_WAIT_V(8); PG8_WAIT_L(0); PG8_BAR; PG8_MMA(0, 0, At, B0); PG8_MMA(0, 1, At, B1); PG8_BAR; PG8_SCHED;
;             PG8_LDA(At, 0, 1); PG8_STAGE(PG8_SB(0, 0), b2, voffB); PG8_STAGE(PG8_SB(0, 1), b2 + hstepB, voffB); PG8_STAGE(PG8_SA(0, 0), a2, voffA);
;             PG8_WAIT_V(8); PG8_WAIT_L(0); PG8_BAR; PG8_MMA(1, 0, At, B0); PG8_MMA(1, 1, At, B1); PG8_BAR; PG8_SCHED;
;             PG8_LDB(B0, 1, 0); PG8_LDB(B1, 1, 1); PG8_SCHED; PG8_LDA(At, 1, 0); PG8_STAGE(PG8_SA(0, 1), a2 + hstepA, voffA);
;             PG8_WAIT_V(8); PG8_WAIT_L(0); PG8_BAR; PG8_MMA(0, 0, At, B0); PG8_MMA(0, 1, At, B1); PG8_BAR; PG8_SCHED;
.LBB0_52:
	s_ashr_i32 s11, s10, 31
	s_lshl_b64 s[12:13], s[10:11], 15
	s_add_u32 s12, s72, s12
	s_addc_u32 s13, s73, s13
	s_and_b64 s[14:15], s[4:5], exec
	s_cselect_b32 s11, s13, s17
	s_cselect_b32 s38, s12, s16
	s_ashr_i32 s9, s8, 31
	s_lshl_b64 s[14:15], s[8:9], 19
	s_add_u32 s14, s66, s14
	s_addc_u32 s15, s67, s15
	s_and_b64 s[20:21], s[4:5], exec
	s_cselect_b32 s9, s15, s19
	s_cselect_b32 s39, s14, s18
	s_add_u32 s40, s18, 0x100
	s_addc_u32 s41, s19, 0
	s_add_u32 s16, s16, 0x404000
	s_addc_u32 s17, s17, 0
	s_mov_b32 s42, -2
	s_add_u32 s18, s16, 0x3fc000
	s_addc_u32 s19, s17, 0
	s_cmp_eq_u32 s42, 12
	s_cselect_b32 s22, s38, s18
	s_cselect_b32 s23, s11, s19
	s_cselect_b32 s20, s39, s40
	s_cselect_b32 s21, s9, s41
	s_add_u32 s18, s22, 0x400000
	s_addc_u32 s19, s23, 0
	s_add_i32 s43, 0, 0x10000
	v_add_u32_e32 v149, s43, v147
	s_add_i32 s46, 0, 0x14000
	ds_read_b128 v[142:145], v149
	ds_read_b128 v[150:153], v149 offset:1024
	ds_read_b128 v[154:157], v149 offset:2048
	ds_read_b128 v[158:161], v149 offset:3072
	v_add_u32_e32 v149, s46, v147
	ds_read_b128 v[162:165], v149
	ds_read_b128 v[166:169], v149 offset:1024
	ds_read_b128 v[170:173], v149 offset:2048
	ds_read_b128 v[174:177], v149 offset:3072
	s_add_i32 m0, s26, 0xc000
	ds_read_b128 v[178:181], v148
	ds_read_b128 v[182:185], v148 offset:1024
	ds_read_b128 v[186:189], v148 offset:2048
	ds_read_b128 v[190:193], v148 offset:3072
	ds_read_b128 v[206:209], v148 offset:4096
	ds_read_b128 v[210:213], v148 offset:5120
	ds_read_b128 v[214:217], v148 offset:6144
	ds_read_b128 v[218:221], v148 offset:7168
	global_load_lds_dwordx4 v138, s[16:17]
	s_add_i32 m0, s26, 0xe000
	s_nop 0
	global_load_lds_dwordx4 v140, s[16:17]
	s_waitcnt vmcnt(8)
	s_waitcnt lgkmcnt(0)
	s_barrier
	s_setprio 1
	v_mfma_f32_16x16x32_bf16 v[126:129], v[142:145], v[178:181], 0
	v_mfma_f32_16x16x32_bf16 v[122:125], v[154:157], v[178:181], 0
	v_mfma_f32_16x16x32_bf16 v[110:113], v[142:145], v[186:189], 0
	v_mfma_f32_16x16x32_bf16 v[106:109], v[154:157], v[186:189], 0
	v_mfma_f32_16x16x32_bf16 v[94:97], v[142:145], v[206:209], 0
	v_mfma_f32_16x16x32_bf16 v[90:93], v[154:157], v[206:209], 0
	v_mfma_f32_16x16x32_bf16 v[78:81], v[142:145], v[214:217], 0
	v_mfma_f32_16x16x32_bf16 v[74:77], v[154:157], v[214:217], 0
	v_mfma_f32_16x16x32_bf16 v[126:129], v[150:153], v[182:185], v[126:129]
	v_mfma_f32_16x16x32_bf16 v[122:125], v[158:161], v[182:185], v[122:125]
	v_mfma_f32_16x16x32_bf16 v[110:113], v[150:153], v[190:193], v[110:113]
	v_mfma_f32_16x16x32_bf16 v[106:109], v[158:161], v[190:193], v[106:109]
	v_mfma_f32_16x16x32_bf16 v[94:97], v[150:153], v[210:213], v[94:97]
	v_mfma_f32_16x16x32_bf16 v[90:93], v[158:161], v[210:213], v[90:93]
	v_mfma_f32_16x16x32_bf16 v[78:81], v[150:153], v[218:221], v[78:81]
	v_mfma_f32_16x16x32_bf16 v[74:77], v[158:161], v[218:221], v[74:77]
	v_mfma_f32_16x16x32_bf16 v[118:121], v[162:165], v[178:181], 0
	v_mfma_f32_16x16x32_bf16 v[114:117], v[170:173], v[178:181], 0
	v_mfma_f32_16x16x32_bf16 v[102:105], v[162:165], v[186:189], 0
	v_mfma_f32_16x16x32_bf16 v[98:101], v[170:173], v[186:189], 0
	v_mfma_f32_16x16x32_bf16 v[86:89], v[162:165], v[206:209], 0
	v_mfma_f32_16x16x32_bf16 v[82:85], v[170:173], v[206:209], 0
	v_mfma_f32_16x16x32_bf16 v[70:73], v[162:165], v[214:217], 0
	v_mfma_f32_16x16x32_bf16 v[66:69], v[170:173], v[214:217], 0
	v_mfma_f32_16x16x32_bf16 v[118:121], v[166:169], v[182:185], v[118:121]
	v_mfma_f32_16x16x32_bf16 v[114:117], v[174:177], v[182:185], v[114:117]
	v_mfma_f32_16x16x32_bf16 v[102:105], v[166:169], v[190:193], v[102:105]
	v_mfma_f32_16x16x32_bf16 v[98:101], v[174:177], v[190:193], v[98:101]
	v_mfma_f32_16x16x32_bf16 v[86:89], v[166:169], v[210:213], v[86:89]
	v_mfma_f32_16x16x32_bf16 v[82:85], v[174:177], v[210:213], v[82:85]
	v_mfma_f32_16x16x32_bf16 v[70:73], v[166:169], v[218:221], v[70:73]
	v_mfma_f32_16x16x32_bf16 v[66:69], v[174:177], v[218:221], v[66:69]
	s_setprio 0
	s_barrier
	s_add_i32 s43, s43, s25
	v_lshl_add_u64 v[222:223], s[20:21], 0, v[0:1]
	s_mov_b32 m0, s43
	ds_read_b128 v[178:181], v148 offset:16384
	ds_read_b128 v[182:185], v148 offset:17408
	ds_read_b128 v[186:189], v148 offset:18432
	ds_read_b128 v[190:193], v148 offset:19456
	ds_read_b128 v[206:209], v148 offset:20480
	ds_read_b128 v[210:213], v148 offset:21504
	ds_read_b128 v[214:217], v148 offset:22528
	ds_read_b128 v[218:221], v148 offset:23552
	global_load_lds_dwordx4 v[222:223], off
	s_add_i32 m0, s43, 0x2000
	s_add_u32 s44, s20, 0x40000
	v_lshl_add_u64 v[224:225], s[20:21], 0, v[130:131]
	s_addc_u32 s45, s21, 0
	s_add_i32 s43, s46, s25
	global_load_lds_dwordx4 v130, s[20:21]
	v_lshl_add_u64 v[226:227], s[44:45], 0, v[0:1]
	s_mov_b32 m0, s43
	s_nop 0
	global_load_lds_dwordx4 v[226:227], off
	s_add_i32 m0, s43, 0x2000
	s_nop 0
	global_load_lds_dwordx4 v130, s[44:45]
	s_mov_b32 m0, s26
	s_nop 0
	global_load_lds_dwordx4 v134, s[22:23]
	s_mov_b32 m0, s27
	s_nop 0
	global_load_lds_dwordx4 v132, s[22:23]
	s_waitcnt vmcnt(8)
	s_waitcnt lgkmcnt(0)
	s_barrier
; #define PG8_STAGE(bufoff, gbase, voff) do { _Pragma("unroll") for (int _i = 0; _i < 2; ++_i) \
;         __builtin_amdgcn_global_load_lds((const unsigned*)((const char*)(gbase) + (voff)[_i]), (PG8_LAS unsigned*)(lds + (bufoff) + ldsw + _i * 8192), 16, 0, 0); } while (0)
; #define PG8_LDA(dst, b, h) do { _Pragma("unroll") for (int m = 0; m < 4; ++m) _Pragma("unroll") for (int k = 0; k < 2; ++k) dst[m][k] = *(const PG8_LAS bf16x8*)(lds + PG8_SA(b, h) + aoff + m * 2048 + k * 1024); } while (0)
; #define PG8_LDB(dst, b, h) do { _Pragma("unroll") for (int n = 0; n < 2; ++n) _Pragma("unroll") for (int k = 0; k < 2; ++k) dst[n][k] = *(const PG8_LAS bf16x8*)(lds + PG8_SB(b, h) + boff + n * 2048 + k * 1024); } while (0)
; #define PG8_MMA(ai, bj, At, Bt) do { __builtin_amdgcn_s_setprio(1); _Pragma("unroll") for (int m = 0; m < 4; ++m) _Pragma("unroll") for (int n = 0; n < 2; ++n) _Pragma("unroll") for (int k = 0; k < 2; ++k) \
;         acc[ai][bj][m][n] = __builtin_amdgcn_mfma_f32_16x16x32_bf16(Bt[n][k], At[m][k], acc[ai][bj][m][n], 0, 0, 0); __builtin_amdgcn_s_setprio(0); } while (0)
; #define PG8_WAIT_V(n) asm volatile("s_waitcnt vmcnt(" #n ")" ::: "memory")
; #define PG8_WAIT_L(n) asm volatile("s_waitcnt lgkmcnt(" #n ")" ::: "memory")
; #define PG8_BAR __builtin_amdgcn_s_barrier()
; #define PG8_SCHED __builtin_amdgcn_sched_barrier(0)
; template <class Epi, class Sched, bool ALIGN_EPI = false, bool SP2 = false>
; __device__ __forceinline__ void gemm_phase(PG8_LAS unsigned char* lds, const Gemm g, const Sched& S, const Epi& E) {
;     ...
;             PG8_WAIT_V(8); PG8_WAIT_L(0); PG8_BAR; PG8_MMA(1, 0, At, B0); PG8_MMA(1, 1, At, B1); PG8_BAR; PG8_SCHED;
;             PG8_LDB(B0, 1, 0); PG8_LDB(B1, 1, 1); PG8_SCHED; PG8_LDA(At, 1, 0); PG8_STAGE(PG8_SA(0, 1), a2 + hstepA, voffA);
;             PG8_WAIT_V(8); PG8_WAIT_L(0); PG8_BAR; PG8_MMA(0, 0, At, B0); PG8_MMA(0, 1, At, B1); PG8_BAR; PG8_SCHED;
;             PG8_LDA(At, 1, 1); PG8_STAGE(PG8_SB(1, 0), b3, voffB); PG8_STAGE(PG8_SB(1, 1), b3 + hstepB, voffB); PG8_STAGE(PG8_SA(1, 0), a3, voffA);
;             PG8_WAIT_V(8); PG8_WAIT_L(0); PG8_BAR; PG8_MMA(1, 0, At, B0); PG8_MMA(1, 1, At, B1); PG8_BAR; PG8_SCHED;
	s_setprio 1
	v_mfma_f32_16x16x32_bf16 v[62:65], v[142:145], v[178:181], 0
	v_mfma_f32_16x16x32_bf16 v[58:61], v[154:157], v[178:181], 0
	v_mfma_f32_16x16x32_bf16 v[46:49], v[142:145], v[186:189], 0
	v_mfma_f32_16x16x32_bf16 v[42:45], v[154:157], v[186:189], 0
	v_mfma_f32_16x16x32_bf16 v[30:33], v[142:145], v[206:209], 0
	v_mfma_f32_16x16x32_bf16 v[26:29], v[154:157], v[206:209], 0
	v_mfma_f32_16x16x32_bf16 v[14:17], v[142:145], v[214:217], 0
	v_mfma_f32_16x16x32_bf16 v[10:13], v[154:157], v[214:217], 0
	v_mfma_f32_16x16x32_bf16 v[62:65], v[150:153], v[182:185], v[62:65]
	v_mfma_f32_16x16x32_bf16 v[58:61], v[158:161], v[182:185], v[58:61]
	v_mfma_f32_16x16x32_bf16 v[46:49], v[150:153], v[190:193], v[46:49]
	v_mfma_f32_16x16x32_bf16 v[42:45], v[158:161], v[190:193], v[42:45]
	v_mfma_f32_16x16x32_bf16 v[30:33], v[150:153], v[210:213], v[30:33]
	v_mfma_f32_16x16x32_bf16 v[26:29], v[158:161], v[210:213], v[26:29]
	v_mfma_f32_16x16x32_bf16 v[14:17], v[150:153], v[218:221], v[14:17]
	v_mfma_f32_16x16x32_bf16 v[10:13], v[158:161], v[218:221], v[10:13]
	v_mfma_f32_16x16x32_bf16 v[54:57], v[162:165], v[178:181], 0
	v_mfma_f32_16x16x32_bf16 v[50:53], v[170:173], v[178:181], 0
	v_mfma_f32_16x16x32_bf16 v[38:41], v[162:165], v[186:189], 0
	v_mfma_f32_16x16x32_bf16 v[34:37], v[170:173], v[186:189], 0
	v_mfma_f32_16x16x32_bf16 v[22:25], v[162:165], v[206:209], 0
	v_mfma_f32_16x16x32_bf16 v[18:21], v[170:173], v[206:209], 0
	v_mfma_f32_16x16x32_bf16 v[6:9], v[162:165], v[214:217], 0
	v_mfma_f32_16x16x32_bf16 v[2:5], v[170:173], v[214:217], 0
	v_mfma_f32_16x16x32_bf16 v[54:57], v[166:169], v[182:185], v[54:57]
	v_mfma_f32_16x16x32_bf16 v[50:53], v[174:177], v[182:185], v[50:53]
	v_mfma_f32_16x16x32_bf16 v[38:41], v[166:169], v[190:193], v[38:41]
	v_mfma_f32_16x16x32_bf16 v[34:37], v[174:177], v[190:193], v[34:37]
	v_mfma_f32_16x16x32_bf16 v[22:25], v[166:169], v[210:213], v[22:25]
	v_mfma_f32_16x16x32_bf16 v[18:21], v[174:177], v[210:213], v[18:21]
	v_mfma_f32_16x16x32_bf16 v[6:9], v[166:169], v[218:221], v[6:9]
	v_mfma_f32_16x16x32_bf16 v[2:5], v[174:177], v[218:221], v[2:5]
	s_setprio 0
	s_barrier
	s_add_i32 s43, 0, 0x18000
	v_add_u32_e32 v149, s43, v147
	s_add_i32 s44, 0, 0x1c000
	ds_read_b128 v[142:145], v149
	ds_read_b128 v[150:153], v149 offset:1024
	ds_read_b128 v[154:157], v149 offset:2048
	ds_read_b128 v[158:161], v149 offset:3072
	v_add_u32_e32 v149, s44, v147
	ds_read_b128 v[162:165], v149
	ds_read_b128 v[166:169], v149 offset:1024
	ds_read_b128 v[170:173], v149 offset:2048
	ds_read_b128 v[174:177], v149 offset:3072
	s_add_u32 s22, s22, 0x4000
	s_addc_u32 s23, s23, 0
	s_mov_b32 m0, s28
	ds_read_b128 v[178:181], v148 offset:32768
	ds_read_b128 v[182:185], v148 offset:33792
	ds_read_b128 v[186:189], v148 offset:34816
	ds_read_b128 v[190:193], v148 offset:35840
	ds_read_b128 v[206:209], v148 offset:36864
	ds_read_b128 v[210:213], v148 offset:37888
	ds_read_b128 v[214:217], v148 offset:38912
	ds_read_b128 v[218:221], v148 offset:39936
	global_load_lds_dwordx4 v134, s[22:23]
	s_mov_b32 m0, s29
	s_nop 0
	global_load_lds_dwordx4 v132, s[22:23]
	s_waitcnt vmcnt(8)
	s_waitcnt lgkmcnt(0)
	s_barrier
	s_setprio 1
	v_mfma_f32_16x16x32_bf16 v[126:129], v[142:145], v[178:181], v[126:129]
	v_mfma_f32_16x16x32_bf16 v[122:125], v[154:157], v[178:181], v[122:125]
	v_mfma_f32_16x16x32_bf16 v[110:113], v[142:145], v[186:189], v[110:113]
	v_mfma_f32_16x16x32_bf16 v[106:109], v[154:157], v[186:189], v[106:109]
	v_mfma_f32_16x16x32_bf16 v[94:97], v[142:145], v[206:209], v[94:97]
	v_mfma_f32_16x16x32_bf16 v[90:93], v[154:157], v[206:209], v[90:93]
	v_mfma_f32_16x16x32_bf16 v[78:81], v[142:145], v[214:217], v[78:81]
	v_mfma_f32_16x16x32_bf16 v[74:77], v[154:157], v[214:217], v[74:77]
	v_mfma_f32_16x16x32_bf16 v[126:129], v[150:153], v[182:185], v[126:129]
	v_mfma_f32_16x16x32_bf16 v[122:125], v[158:161], v[182:185], v[122:125]
	v_mfma_f32_16x16x32_bf16 v[110:113], v[150:153], v[190:193], v[110:113]
	v_mfma_f32_16x16x32_bf16 v[106:109], v[158:161], v[190:193], v[106:109]
	v_mfma_f32_16x16x32_bf16 v[94:97], v[150:153], v[210:213], v[94:97]
	v_mfma_f32_16x16x32_bf16 v[90:93], v[158:161], v[210:213], v[90:93]
	v_mfma_f32_16x16x32_bf16 v[78:81], v[150:153], v[218:221], v[78:81]
	v_mfma_f32_16x16x32_bf16 v[74:77], v[158:161], v[218:221], v[74:77]
	v_mfma_f32_16x16x32_bf16 v[118:121], v[162:165], v[178:181], v[118:121]
	v_mfma_f32_16x16x32_bf16 v[114:117], v[170:173], v[178:181], v[114:117]
	v_mfma_f32_16x16x32_bf16 v[102:105], v[162:165], v[186:189], v[102:105]
	v_mfma_f32_16x16x32_bf16 v[98:101], v[170:173], v[186:189], v[98:101]
	v_mfma_f32_16x16x32_bf16 v[86:89], v[162:165], v[206:209], v[86:89]
	v_mfma_f32_16x16x32_bf16 v[82:85], v[170:173], v[206:209], v[82:85]
	v_mfma_f32_16x16x32_bf16 v[70:73], v[162:165], v[214:217], v[70:73]
	v_mfma_f32_16x16x32_bf16 v[66:69], v[170:173], v[214:217], v[66:69]
	v_mfma_f32_16x16x32_bf16 v[118:121], v[166:169], v[182:185], v[118:121]
	v_mfma_f32_16x16x32_bf16 v[114:117], v[174:177], v[182:185], v[114:117]
	v_mfma_f32_16x16x32_bf16 v[102:105], v[166:169], v[190:193], v[102:105]
	v_mfma_f32_16x16x32_bf16 v[98:101], v[174:177], v[190:193], v[98:101]
	v_mfma_f32_16x16x32_bf16 v[86:89], v[166:169], v[210:213], v[86:89]
	v_mfma_f32_16x16x32_bf16 v[82:85], v[174:177], v[210:213], v[82:85]
	v_mfma_f32_16x16x32_bf16 v[70:73], v[166:169], v[218:221], v[70:73]
	v_mfma_f32_16x16x32_bf16 v[66:69], v[174:177], v[218:221], v[66:69]
	s_setprio 0
	s_barrier
; #define PG8_STAGE(bufoff, gbase, voff) do { _Pragma("unroll") for (int _i = 0; _i < 2; ++_i) \
;         __builtin_amdgcn_global_load_lds((const unsigned*)((const char*)(gbase) + (voff)[_i]), (PG8_LAS unsigned*)(lds + (bufoff) + ldsw + _i * 8192), 16, 0, 0); } while (0)
; #define PG8_LDA(dst, b, h) do { _Pragma("unroll") for (int m = 0; m < 4; ++m) _Pragma("unroll") for (int k = 0; k < 2; ++k) dst[m][k] = *(const PG8_LAS bf16x8*)(lds + PG8_SA(b, h) + aoff + m * 2048 + k * 1024); } while (0)
; #define PG8_LDB(dst, b, h) do { _Pragma("unroll") for (int n = 0; n < 2; ++n) _Pragma("unroll") for (int k = 0; k < 2; ++k) dst[n][k] = *(const PG8_LAS bf16x8*)(lds + PG8_SB(b, h) + boff + n * 2048 + k * 1024); } while (0)
; #define PG8_MMA(ai, bj, At, Bt) do { __builtin_amdgcn_s_setprio(1); _Pragma("unroll") for (int m = 0; m < 4; ++m) _Pragma("unroll") for (int n = 0; n < 2; ++n) _Pragma("unroll") for (int k = 0; k < 2; ++k) \
;         acc[ai][bj][m][n] = __builtin_amdgcn_mfma_f32_16x16x32_bf16(Bt[n][k], At[m][k], acc[ai][bj][m][n], 0, 0, 0); __builtin_amdgcn_s_setprio(0); } while (0)
; #define PG8_BAR __builtin_amdgcn_s_barrier()
; template <class Epi, class Sched, bool ALIGN_EPI = false, bool SP2 = false>
; __device__ __forceinline__ void gemm_phase(PG8_LAS unsigned char* lds, const Gemm g, const Sched& S, const Epi& E) {
;     ...
;             const bool last = (t == nt - 2);
;             const char* a1 = cA + (size_t)(t + 1) * kstepA;
;             const char* a2 = last ? nA : cA + (size_t)(t + 2) * kstepA; const char* b2 = last ? nB : cB + (size_t)(t + 2) * kstep;
;             const char* a3 = a2 + kstepA; const char* b3 = b2 + kstep;
;             if (last && has_next) S.a_ready(nxt);
;             if constexpr (SP2) {
;             PG8_LDB(B0, 0, 0); PG8_LDB(B1, 0, 1); PG8_SCHED; PG8_LDA(At, 0, 0); PG8_STAGE(PG8_SA(1, 1), a1 + hstepA, voffA);
;             PG8_WAIT_V(8); PG8_WAIT_L(0); PG8_BAR; PG8_MMA(0, 0, At, B0); PG8_MMA(0, 1, At, B1); PG8_BAR; PG8_SCHED;
;     ...
;             PG8_WAIT_V(8); PG8_WAIT_L(0); PG8_BAR; PG8_MMA(0, 0, At, B0); PG8_MMA(0, 1, At, B1); PG8_BAR; PG8_SCHED;
;             PG8_LDA(At, 1, 1); PG8_STAGE(PG8_SB(1, 0), b3, voffB); PG8_STAGE(PG8_SB(1, 1), b3 + hstepB, voffB); PG8_STAGE(PG8_SA(1, 0), a3, voffA);
;             PG8_WAIT_V(8); PG8_WAIT_L(0); PG8_BAR; PG8_MMA(1, 0, At, B0); PG8_MMA(1, 1, At, B1); PG8_BAR; PG8_SCHED;
	s_add_i32 s22, s43, s25
	v_lshl_add_u64 v[222:223], v[222:223], 0, s[78:79]
	s_mov_b32 m0, s22
	ds_read_b128 v[178:181], v148 offset:49152
	ds_read_b128 v[182:185], v148 offset:50176
	ds_read_b128 v[186:189], v148 offset:51200
	ds_read_b128 v[190:193], v148 offset:52224
	ds_read_b128 v[206:209], v148 offset:53248
	ds_read_b128 v[210:213], v148 offset:54272
	ds_read_b128 v[214:217], v148 offset:55296
	ds_read_b128 v[218:221], v148 offset:56320
	global_load_lds_dwordx4 v[222:223], off
	s_add_i32 m0, s22, 0x2000
	s_add_u32 s20, s20, 0x40080
	v_lshl_add_u64 v[222:223], v[224:225], 0, s[78:79]
	s_addc_u32 s21, s21, 0
	s_add_i32 s22, s44, s25
	global_load_lds_dwordx4 v[222:223], off
	v_lshl_add_u64 v[222:223], s[20:21], 0, v[0:1]
	s_mov_b32 m0, s22
	s_nop 0
	global_load_lds_dwordx4 v[222:223], off
	s_add_i32 m0, s22, 0x2000
	s_nop 0
	global_load_lds_dwordx4 v130, s[20:21]
	s_mov_b32 m0, s30
	s_nop 0
	global_load_lds_dwordx4 v134, s[18:19]
	s_mov_b32 m0, s31
	s_nop 0
	global_load_lds_dwordx4 v132, s[18:19]
	s_waitcnt vmcnt(8)
	s_waitcnt lgkmcnt(0)
	s_barrier
	s_setprio 1
	v_mfma_f32_16x16x32_bf16 v[62:65], v[142:145], v[178:181], v[62:65]
	v_mfma_f32_16x16x32_bf16 v[58:61], v[154:157], v[178:181], v[58:61]
	v_mfma_f32_16x16x32_bf16 v[46:49], v[142:145], v[186:189], v[46:49]
	v_mfma_f32_16x16x32_bf16 v[42:45], v[154:157], v[186:189], v[42:45]
	v_mfma_f32_16x16x32_bf16 v[30:33], v[142:145], v[206:209], v[30:33]
	v_mfma_f32_16x16x32_bf16 v[26:29], v[154:157], v[206:209], v[26:29]
	v_mfma_f32_16x16x32_bf16 v[14:17], v[142:145], v[214:217], v[14:17]
	v_mfma_f32_16x16x32_bf16 v[10:13], v[154:157], v[214:217], v[10:13]
	v_mfma_f32_16x16x32_bf16 v[62:65], v[150:153], v[182:185], v[62:65]
	v_mfma_f32_16x16x32_bf16 v[58:61], v[158:161], v[182:185], v[58:61]
	v_mfma_f32_16x16x32_bf16 v[46:49], v[150:153], v[190:193], v[46:49]
	v_mfma_f32_16x16x32_bf16 v[42:45], v[158:161], v[190:193], v[42:45]
	v_mfma_f32_16x16x32_bf16 v[30:33], v[150:153], v[210:213], v[30:33]
	v_mfma_f32_16x16x32_bf16 v[26:29], v[158:161], v[210:213], v[26:29]
	v_mfma_f32_16x16x32_bf16 v[14:17], v[150:153], v[218:221], v[14:17]
	v_mfma_f32_16x16x32_bf16 v[10:13], v[158:161], v[218:221], v[10:13]
	v_mfma_f32_16x16x32_bf16 v[54:57], v[162:165], v[178:181], v[54:57]
	v_mfma_f32_16x16x32_bf16 v[50:53], v[170:173], v[178:181], v[50:53]
	v_mfma_f32_16x16x32_bf16 v[38:41], v[162:165], v[186:189], v[38:41]
	v_mfma_f32_16x16x32_bf16 v[34:37], v[170:173], v[186:189], v[34:37]
	v_mfma_f32_16x16x32_bf16 v[22:25], v[162:165], v[206:209], v[22:25]
	v_mfma_f32_16x16x32_bf16 v[18:21], v[170:173], v[206:209], v[18:21]
	v_mfma_f32_16x16x32_bf16 v[6:9], v[162:165], v[214:217], v[6:9]
	v_mfma_f32_16x16x32_bf16 v[2:5], v[170:173], v[214:217], v[2:5]
	v_mfma_f32_16x16x32_bf16 v[54:57], v[166:169], v[182:185], v[54:57]
	v_mfma_f32_16x16x32_bf16 v[50:53], v[174:177], v[182:185], v[50:53]
	v_mfma_f32_16x16x32_bf16 v[38:41], v[166:169], v[190:193], v[38:41]
	v_mfma_f32_16x16x32_bf16 v[34:37], v[174:177], v[190:193], v[34:37]
	v_mfma_f32_16x16x32_bf16 v[22:25], v[166:169], v[210:213], v[22:25]
	v_mfma_f32_16x16x32_bf16 v[18:21], v[174:177], v[210:213], v[18:21]
	v_mfma_f32_16x16x32_bf16 v[6:9], v[166:169], v[218:221], v[6:9]
	v_mfma_f32_16x16x32_bf16 v[2:5], v[174:177], v[218:221], v[2:5]
	s_setprio 0
	s_barrier
	s_add_i32 s42, s42, 2
	s_add_u32 s40, s40, 0x100
	s_addc_u32 s41, s41, 0
	s_add_u32 s16, s16, 0x800000
	s_addc_u32 s17, s17, 0
.LBB0_53:
	s_add_u32 s18, s16, 0x3fc000
	s_addc_u32 s19, s17, 0
	s_cmp_eq_u32 s42, 12
	s_cselect_b32 s22, s38, s18
	s_cselect_b32 s23, s11, s19
	s_cselect_b32 s20, s39, s40
	s_cselect_b32 s21, s9, s41
	s_add_u32 s18, s22, 0x400000
	s_addc_u32 s19, s23, 0
	s_add_i32 s43, 0, 0x10000
	v_add_u32_e32 v149, s43, v147
	s_add_i32 s46, 0, 0x14000
	ds_read_b128 v[142:145], v149
	ds_read_b128 v[150:153], v149 offset:1024
	ds_read_b128 v[154:157], v149 offset:2048
	ds_read_b128 v[158:161], v149 offset:3072
	v_add_u32_e32 v149, s46, v147
	ds_read_b128 v[162:165], v149
	ds_read_b128 v[166:169], v149 offset:1024
	ds_read_b128 v[170:173], v149 offset:2048
	ds_read_b128 v[174:177], v149 offset:3072
	s_add_i32 m0, s26, 0xc000
	ds_read_b128 v[178:181], v148
	ds_read_b128 v[182:185], v148 offset:1024
	ds_read_b128 v[186:189], v148 offset:2048
	ds_read_b128 v[190:193], v148 offset:3072
	ds_read_b128 v[206:209], v148 offset:4096
	ds_read_b128 v[210:213], v148 offset:5120
	ds_read_b128 v[214:217], v148 offset:6144
	ds_read_b128 v[218:221], v148 offset:7168
	global_load_lds_dwordx4 v138, s[16:17]
	s_add_i32 m0, s26, 0xe000
	s_nop 0
	global_load_lds_dwordx4 v140, s[16:17]
	s_waitcnt vmcnt(8)
	s_waitcnt lgkmcnt(0)
	s_barrier
; #define PG8_STAGE(bufoff, gbase, voff) do { _Pragma("unroll") for (int _i = 0; _i < 2; ++_i) \
;         __builtin_amdgcn_global_load_lds((const unsigned*)((const char*)(gbase) + (voff)[_i]), (PG8_LAS unsigned*)(lds + (bufoff) + ldsw + _i * 8192), 16, 0, 0); } while (0)
; #define PG8_LDA(dst, b, h) do { _Pragma("unroll") for (int m = 0; m < 4; ++m) _Pragma("unroll") for (int k = 0; k < 2; ++k) dst[m][k] = *(const PG8_LAS bf16x8*)(lds + PG8_SA(b, h) + aoff + m * 2048 + k * 1024); } while (0)
; #define PG8_LDB(dst, b, h) do { _Pragma("unroll") for (int n = 0; n < 2; ++n) _Pragma("unroll") for (int k = 0; k < 2; ++k) dst[n][k] = *(const PG8_LAS bf16x8*)(lds + PG8_SB(b, h) + boff + n * 2048 + k * 1024); } while (0)
; #define PG8_MMA(ai, bj, At, Bt) do { __builtin_amdgcn_s_setprio(1); _Pragma("unroll") for (int m = 0; m < 4; ++m) _Pragma("unroll") for (int n = 0; n < 2; ++n) _Pragma("unroll") for (int k = 0; k < 2; ++k) \
;         acc[ai][bj][m][n] = __builtin_amdgcn_mfma_f32_16x16x32_bf16(Bt[n][k], At[m][k], acc[ai][bj][m][n], 0, 0, 0); __builtin_amdgcn_s_setprio(0); } while (0)
; #define PG8_WAIT_V(n) asm volatile("s_waitcnt vmcnt(" #n ")" ::: "memory")
; #define PG8_WAIT_L(n) asm volatile("s_waitcnt lgkmcnt(" #n ")" ::: "memory")
; #define PG8_BAR __builtin_amdgcn_s_barrier()
; #define PG8_SCHED __builtin_amdgcn_sched_barrier(0)
; template <class Epi, class Sched, bool ALIGN_EPI = false, bool SP2 = false>
; __device__ __forceinline__ void gemm_phase(PG8_LAS unsigned char* lds, const Gemm g, const Sched& S, const Epi& E) {
;     ...
;             PG8_WAIT_V(8); PG8_WAIT_L(0); PG8_BAR; PG8_MMA(0, 0, At, B0); PG8_MMA(0, 1, At, B1); PG8_BAR; PG8_SCHED;
;             PG8_LDA(At, 0, 1); PG8_STAGE(PG8_SB(0, 0), b2, voffB); PG8_STAGE(PG8_SB(0, 1), b2 + hstepB, voffB); PG8_STAGE(PG8_SA(0, 0), a2, voffA);
;             PG8_WAIT_V(8); PG8_WAIT_L(0); PG8_BAR; PG8_MMA(1, 0, At, B0); PG8_MMA(1, 1, At, B1); PG8_BAR; PG8_SCHED;
;             PG8_LDB(B0, 1, 0); PG8_LDB(B1, 1, 1); PG8_SCHED; PG8_LDA(At, 1, 0); PG8_STAGE(PG8_SA(0, 1), a2 + hstepA, voffA);
;             PG8_WAIT_V(8); PG8_WAIT_L(0); PG8_BAR; PG8_MMA(0, 0, At, B0); PG8_MMA(0, 1, At, B1); PG8_BAR; PG8_SCHED;
	s_setprio 1
	v_mfma_f32_16x16x32_bf16 v[126:129], v[142:145], v[178:181], v[126:129]
	v_mfma_f32_16x16x32_bf16 v[122:125], v[154:157], v[178:181], v[122:125]
	v_mfma_f32_16x16x32_bf16 v[110:113], v[142:145], v[186:189], v[110:113]
	v_mfma_f32_16x16x32_bf16 v[106:109], v[154:157], v[186:189], v[106:109]
	v_mfma_f32_16x16x32_bf16 v[94:97], v[142:145], v[206:209], v[94:97]
	v_mfma_f32_16x16x32_bf16 v[90:93], v[154:157], v[206:209], v[90:93]
	v_mfma_f32_16x16x32_bf16 v[78:81], v[142:145], v[214:217], v[78:81]
	v_mfma_f32_16x16x32_bf16 v[74:77], v[154:157], v[214:217], v[74:77]
	v_mfma_f32_16x16x32_bf16 v[126:129], v[150:153], v[182:185], v[126:129]
	v_mfma_f32_16x16x32_bf16 v[122:125], v[158:161], v[182:185], v[122:125]
	v_mfma_f32_16x16x32_bf16 v[110:113], v[150:153], v[190:193], v[110:113]
	v_mfma_f32_16x16x32_bf16 v[106:109], v[158:161], v[190:193], v[106:109]
	v_mfma_f32_16x16x32_bf16 v[94:97], v[150:153], v[210:213], v[94:97]
	v_mfma_f32_16x16x32_bf16 v[90:93], v[158:161], v[210:213], v[90:93]
	v_mfma_f32_16x16x32_bf16 v[78:81], v[150:153], v[218:221], v[78:81]
	v_mfma_f32_16x16x32_bf16 v[74:77], v[158:161], v[218:221], v[74:77]
	v_mfma_f32_16x16x32_bf16 v[118:121], v[162:165], v[178:181], v[118:121]
	v_mfma_f32_16x16x32_bf16 v[114:117], v[170:173], v[178:181], v[114:117]
	v_mfma_f32_16x16x32_bf16 v[102:105], v[162:165], v[186:189], v[102:105]
	v_mfma_f32_16x16x32_bf16 v[98:101], v[170:173], v[186:189], v[98:101]
	v_mfma_f32_16x16x32_bf16 v[86:89], v[162:165], v[206:209], v[86:89]
	v_mfma_f32_16x16x32_bf16 v[82:85], v[170:173], v[206:209], v[82:85]
	v_mfma_f32_16x16x32_bf16 v[70:73], v[162:165], v[214:217], v[70:73]
	v_mfma_f32_16x16x32_bf16 v[66:69], v[170:173], v[214:217], v[66:69]
	v_mfma_f32_16x16x32_bf16 v[118:121], v[166:169], v[182:185], v[118:121]
	v_mfma_f32_16x16x32_bf16 v[114:117], v[174:177], v[182:185], v[114:117]
	v_mfma_f32_16x16x32_bf16 v[102:105], v[166:169], v[190:193], v[102:105]
	v_mfma_f32_16x16x32_bf16 v[98:101], v[174:177], v[190:193], v[98:101]
	v_mfma_f32_16x16x32_bf16 v[86:89], v[166:169], v[210:213], v[86:89]
	v_mfma_f32_16x16x32_bf16 v[82:85], v[174:177], v[210:213], v[82:85]
	v_mfma_f32_16x16x32_bf16 v[70:73], v[166:169], v[218:221], v[70:73]
	v_mfma_f32_16x16x32_bf16 v[66:69], v[174:177], v[218:221], v[66:69]
	s_setprio 0
	s_barrier
	s_add_i32 s43, s43, s25
	v_lshl_add_u64 v[222:223], s[20:21], 0, v[0:1]
	s_mov_b32 m0, s43
	ds_read_b128 v[178:181], v148 offset:16384
	ds_read_b128 v[182:185], v148 offset:17408
	ds_read_b128 v[186:189], v148 offset:18432
	ds_read_b128 v[190:193], v148 offset:19456
	ds_read_b128 v[206:209], v148 offset:20480
	ds_read_b128 v[210:213], v148 offset:21504
	ds_read_b128 v[214:217], v148 offset:22528
	ds_read_b128 v[218:221], v148 offset:23552
	global_load_lds_dwordx4 v[222:223], off
	s_add_i32 m0, s43, 0x2000
	s_add_u32 s44, s20, 0x40000
	v_lshl_add_u64 v[224:225], s[20:21], 0, v[130:131]
	s_addc_u32 s45, s21, 0
	s_add_i32 s43, s46, s25
	global_load_lds_dwordx4 v130, s[20:21]
	v_lshl_add_u64 v[226:227], s[44:45], 0, v[0:1]
	s_mov_b32 m0, s43
	s_nop 0
	global_load_lds_dwordx4 v[226:227], off
	s_add_i32 m0, s43, 0x2000
	s_nop 0
	global_load_lds_dwordx4 v130, s[44:45]
	s_mov_b32 m0, s26
	s_nop 0
	global_load_lds_dwordx4 v134, s[22:23]
	s_mov_b32 m0, s27
	s_nop 0
	global_load_lds_dwordx4 v132, s[22:23]
	s_waitcnt vmcnt(8)
	s_waitcnt lgkmcnt(0)
	s_barrier
	s_setprio 1
	v_mfma_f32_16x16x32_bf16 v[62:65], v[142:145], v[178:181], v[62:65]
	v_mfma_f32_16x16x32_bf16 v[58:61], v[154:157], v[178:181], v[58:61]
	v_mfma_f32_16x16x32_bf16 v[46:49], v[142:145], v[186:189], v[46:49]
	v_mfma_f32_16x16x32_bf16 v[42:45], v[154:157], v[186:189], v[42:45]
	v_mfma_f32_16x16x32_bf16 v[30:33], v[142:145], v[206:209], v[30:33]
	v_mfma_f32_16x16x32_bf16 v[26:29], v[154:157], v[206:209], v[26:29]
	v_mfma_f32_16x16x32_bf16 v[14:17], v[142:145], v[214:217], v[14:17]
	v_mfma_f32_16x16x32_bf16 v[10:13], v[154:157], v[214:217], v[10:13]
	v_mfma_f32_16x16x32_bf16 v[62:65], v[150:153], v[182:185], v[62:65]
	v_mfma_f32_16x16x32_bf16 v[58:61], v[158:161], v[182:185], v[58:61]
	v_mfma_f32_16x16x32_bf16 v[46:49], v[150:153], v[190:193], v[46:49]
	v_mfma_f32_16x16x32_bf16 v[42:45], v[158:161], v[190:193], v[42:45]
	v_mfma_f32_16x16x32_bf16 v[30:33], v[150:153], v[210:213], v[30:33]
	v_mfma_f32_16x16x32_bf16 v[26:29], v[158:161], v[210:213], v[26:29]
	v_mfma_f32_16x16x32_bf16 v[14:17], v[150:153], v[218:221], v[14:17]
	v_mfma_f32_16x16x32_bf16 v[10:13], v[158:161], v[218:221], v[10:13]
	v_mfma_f32_16x16x32_bf16 v[54:57], v[162:165], v[178:181], v[54:57]
	v_mfma_f32_16x16x32_bf16 v[50:53], v[170:173], v[178:181], v[50:53]
	v_mfma_f32_16x16x32_bf16 v[38:41], v[162:165], v[186:189], v[38:41]
	v_mfma_f32_16x16x32_bf16 v[34:37], v[170:173], v[186:189], v[34:37]
	v_mfma_f32_16x16x32_bf16 v[22:25], v[162:165], v[206:209], v[22:25]
	v_mfma_f32_16x16x32_bf16 v[18:21], v[170:173], v[206:209], v[18:21]
	v_mfma_f32_16x16x32_bf16 v[6:9], v[162:165], v[214:217], v[6:9]
	v_mfma_f32_16x16x32_bf16 v[2:5], v[170:173], v[214:217], v[2:5]
	v_mfma_f32_16x16x32_bf16 v[54:57], v[166:169], v[182:185], v[54:57]
	v_mfma_f32_16x16x32_bf16 v[50:53], v[174:177], v[182:185], v[50:53]
	v_mfma_f32_16x16x32_bf16 v[38:41], v[166:169], v[190:193], v[38:41]
	v_mfma_f32_16x16x32_bf16 v[34:37], v[174:177], v[190:193], v[34:37]
	v_mfma_f32_16x16x32_bf16 v[22:25], v[166:169], v[210:213], v[22:25]
	v_mfma_f32_16x16x32_bf16 v[18:21], v[174:177], v[210:213], v[18:21]
	v_mfma_f32_16x16x32_bf16 v[6:9], v[166:169], v[218:221], v[6:9]
	v_mfma_f32_16x16x32_bf16 v[2:5], v[174:177], v[218:221], v[2:5]
	s_setprio 0
	s_barrier
; #define PG8_STAGE(bufoff, gbase, voff) do { _Pragma("unroll") for (int _i = 0; _i < 2; ++_i) \
;         __builtin_amdgcn_global_load_lds((const unsigned*)((const char*)(gbase) + (voff)[_i]), (PG8_LAS unsigned*)(lds + (bufoff) + ldsw + _i * 8192), 16, 0, 0); } while (0)
; #define PG8_LDA(dst, b, h) do { _Pragma("unroll") for (int m = 0; m < 4; ++m) _Pragma("unroll") for (int k = 0; k < 2; ++k) dst[m][k] = *(const PG8_LAS bf16x8*)(lds + PG8_SA(b, h) + aoff + m * 2048 + k * 1024); } while (0)
; #define PG8_LDB(dst, b, h) do { _Pragma("unroll") for (int n = 0; n < 2; ++n) _Pragma("unroll") for (int k = 0; k < 2; ++k) dst[n][k] = *(const PG8_LAS bf16x8*)(lds + PG8_SB(b, h) + boff + n * 2048 + k * 1024); } while (0)
; #define PG8_MMA(ai, bj, At, Bt) do { __builtin_amdgcn_s_setprio(1); _Pragma("unroll") for (int m = 0; m < 4; ++m) _Pragma("unroll") for (int n = 0; n < 2; ++n) _Pragma("unroll") for (int k = 0; k < 2; ++k) \
;         acc[ai][bj][m][n] = __builtin_amdgcn_mfma_f32_16x16x32_bf16(Bt[n][k], At[m][k], acc[ai][bj][m][n], 0, 0, 0); __builtin_amdgcn_s_setprio(0); } while (0)
; #define PG8_WAIT_V(n) asm volatile("s_waitcnt vmcnt(" #n ")" ::: "memory")
; #define PG8_WAIT_L(n) asm volatile("s_waitcnt lgkmcnt(" #n ")" ::: "memory")
; #define PG8_BAR __builtin_amdgcn_s_barrier()
; #define PG8_SCHED __builtin_amdgcn_sched_barrier(0)
; template <class Epi, class Sched, bool ALIGN_EPI = false, bool SP2 = false>
; __device__ __forceinline__ void gemm_phase(PG8_LAS unsigned char* lds, const Gemm g, const Sched& S, const Epi& E) {
;     ...
;             PG8_LDB(B0, 1, 0); PG8_LDB(B1, 1, 1); PG8_SCHED; PG8_LDA(At, 1, 0); PG8_STAGE(PG8_SA(0, 1), a2 + hstepA, voffA);
;             PG8_WAIT_V(8); PG8_WAIT_L(0); PG8_BAR; PG8_MMA(0, 0, At, B0); PG8_MMA(0, 1, At, B1); PG8_BAR; PG8_SCHED;
;             PG8_LDA(At, 1, 1); PG8_STAGE(PG8_SB(1, 0), b3, voffB); PG8_STAGE(PG8_SB(1, 1), b3 + hstepB, voffB); PG8_STAGE(PG8_SA(1, 0), a3, voffA);
;             PG8_WAIT_V(8); PG8_WAIT_L(0); PG8_BAR; PG8_MMA(1, 0, At, B0); PG8_MMA(1, 1, At, B1); PG8_BAR; PG8_SCHED;
	s_add_i32 s43, 0, 0x18000
	v_add_u32_e32 v149, s43, v147
	s_add_i32 s44, 0, 0x1c000
	ds_read_b128 v[142:145], v149
	ds_read_b128 v[150:153], v149 offset:1024
	ds_read_b128 v[154:157], v149 offset:2048
	ds_read_b128 v[158:161], v149 offset:3072
	v_add_u32_e32 v149, s44, v147
	ds_read_b128 v[162:165], v149
	ds_read_b128 v[166:169], v149 offset:1024
	ds_read_b128 v[170:173], v149 offset:2048
	ds_read_b128 v[174:177], v149 offset:3072
	s_add_u32 s22, s22, 0x4000
	s_addc_u32 s23, s23, 0
	s_mov_b32 m0, s28
	ds_read_b128 v[178:181], v148 offset:32768
	ds_read_b128 v[182:185], v148 offset:33792
	ds_read_b128 v[186:189], v148 offset:34816
	ds_read_b128 v[190:193], v148 offset:35840
	ds_read_b128 v[206:209], v148 offset:36864
	ds_read_b128 v[210:213], v148 offset:37888
	ds_read_b128 v[214:217], v148 offset:38912
	ds_read_b128 v[218:221], v148 offset:39936
	global_load_lds_dwordx4 v134, s[22:23]
	s_mov_b32 m0, s29
	s_nop 0
	global_load_lds_dwordx4 v132, s[22:23]
	s_waitcnt vmcnt(8)
	s_waitcnt lgkmcnt(0)
	s_barrier
	s_setprio 1
	v_mfma_f32_16x16x32_bf16 v[126:129], v[142:145], v[178:181], v[126:129]
	v_mfma_f32_16x16x32_bf16 v[122:125], v[154:157], v[178:181], v[122:125]
	v_mfma_f32_16x16x32_bf16 v[110:113], v[142:145], v[186:189], v[110:113]
	v_mfma_f32_16x16x32_bf16 v[106:109], v[154:157], v[186:189], v[106:109]
	v_mfma_f32_16x16x32_bf16 v[94:97], v[142:145], v[206:209], v[94:97]
	v_mfma_f32_16x16x32_bf16 v[90:93], v[154:157], v[206:209], v[90:93]
	v_mfma_f32_16x16x32_bf16 v[78:81], v[142:145], v[214:217], v[78:81]
	v_mfma_f32_16x16x32_bf16 v[74:77], v[154:157], v[214:217], v[74:77]
	v_mfma_f32_16x16x32_bf16 v[126:129], v[150:153], v[182:185], v[126:129]
	v_mfma_f32_16x16x32_bf16 v[122:125], v[158:161], v[182:185], v[122:125]
	v_mfma_f32_16x16x32_bf16 v[110:113], v[150:153], v[190:193], v[110:113]
	v_mfma_f32_16x16x32_bf16 v[106:109], v[158:161], v[190:193], v[106:109]
	v_mfma_f32_16x16x32_bf16 v[94:97], v[150:153], v[210:213], v[94:97]
	v_mfma_f32_16x16x32_bf16 v[90:93], v[158:161], v[210:213], v[90:93]
	v_mfma_f32_16x16x32_bf16 v[78:81], v[150:153], v[218:221], v[78:81]
	v_mfma_f32_16x16x32_bf16 v[74:77], v[158:161], v[218:221], v[74:77]
	v_mfma_f32_16x16x32_bf16 v[118:121], v[162:165], v[178:181], v[118:121]
	v_mfma_f32_16x16x32_bf16 v[114:117], v[170:173], v[178:181], v[114:117]
	v_mfma_f32_16x16x32_bf16 v[102:105], v[162:165], v[186:189], v[102:105]
	v_mfma_f32_16x16x32_bf16 v[98:101], v[170:173], v[186:189], v[98:101]
	v_mfma_f32_16x16x32_bf16 v[86:89], v[162:165], v[206:209], v[86:89]
	v_mfma_f32_16x16x32_bf16 v[82:85], v[170:173], v[206:209], v[82:85]
	v_mfma_f32_16x16x32_bf16 v[70:73], v[162:165], v[214:217], v[70:73]
	v_mfma_f32_16x16x32_bf16 v[66:69], v[170:173], v[214:217], v[66:69]
	v_mfma_f32_16x16x32_bf16 v[118:121], v[166:169], v[182:185], v[118:121]
	v_mfma_f32_16x16x32_bf16 v[114:117], v[174:177], v[182:185], v[114:117]
	v_mfma_f32_16x16x32_bf16 v[102:105], v[166:169], v[190:193], v[102:105]
	v_mfma_f32_16x16x32_bf16 v[98:101], v[174:177], v[190:193], v[98:101]
	v_mfma_f32_16x16x32_bf16 v[86:89], v[166:169], v[210:213], v[86:89]
	v_mfma_f32_16x16x32_bf16 v[82:85], v[174:177], v[210:213], v[82:85]
	v_mfma_f32_16x16x32_bf16 v[70:73], v[166:169], v[218:221], v[70:73]
	v_mfma_f32_16x16x32_bf16 v[66:69], v[174:177], v[218:221], v[66:69]
	s_setprio 0
	s_barrier
	s_add_i32 s22, s43, s25
	v_lshl_add_u64 v[222:223], v[222:223], 0, s[78:79]
	s_mov_b32 m0, s22
	ds_read_b128 v[178:181], v148 offset:49152
	ds_read_b128 v[182:185], v148 offset:50176
	ds_read_b128 v[186:189], v148 offset:51200
	ds_read_b128 v[190:193], v148 offset:52224
	ds_read_b128 v[206:209], v148 offset:53248
	ds_read_b128 v[210:213], v148 offset:54272
	ds_read_b128 v[214:217], v148 offset:55296
	ds_read_b128 v[218:221], v148 offset:56320
	global_load_lds_dwordx4 v[222:223], off
	s_add_i32 m0, s22, 0x2000
	s_add_u32 s20, s20, 0x40080
	v_lshl_add_u64 v[222:223], v[224:225], 0, s[78:79]
	s_addc_u32 s21, s21, 0
	s_add_i32 s22, s44, s25
	global_load_lds_dwordx4 v[222:223], off
	v_lshl_add_u64 v[222:223], s[20:21], 0, v[0:1]
	s_mov_b32 m0, s22
	s_nop 0
	global_load_lds_dwordx4 v[222:223], off
	s_add_i32 m0, s22, 0x2000
	s_nop 0
	global_load_lds_dwordx4 v130, s[20:21]
	s_mov_b32 m0, s30
	s_nop 0
	global_load_lds_dwordx4 v134, s[18:19]
	s_mov_b32 m0, s31
	s_nop 0
	global_load_lds_dwordx4 v132, s[18:19]
	s_waitcnt vmcnt(8)
	s_waitcnt lgkmcnt(0)
	s_barrier
	s_setprio 1
	v_mfma_f32_16x16x32_bf16 v[62:65], v[142:145], v[178:181], v[62:65]
	v_mfma_f32_16x16x32_bf16 v[58:61], v[154:157], v[178:181], v[58:61]
	v_mfma_f32_16x16x32_bf16 v[46:49], v[142:145], v[186:189], v[46:49]
	v_mfma_f32_16x16x32_bf16 v[42:45], v[154:157], v[186:189], v[42:45]
	v_mfma_f32_16x16x32_bf16 v[30:33], v[142:145], v[206:209], v[30:33]
	v_mfma_f32_16x16x32_bf16 v[26:29], v[154:157], v[206:209], v[26:29]
	v_mfma_f32_16x16x32_bf16 v[14:17], v[142:145], v[214:217], v[14:17]
	v_mfma_f32_16x16x32_bf16 v[10:13], v[154:157], v[214:217], v[10:13]
	v_mfma_f32_16x16x32_bf16 v[62:65], v[150:153], v[182:185], v[62:65]
	v_mfma_f32_16x16x32_bf16 v[58:61], v[158:161], v[182:185], v[58:61]
	v_mfma_f32_16x16x32_bf16 v[46:49], v[150:153], v[190:193], v[46:49]
	v_mfma_f32_16x16x32_bf16 v[42:45], v[158:161], v[190:193], v[42:45]
	v_mfma_f32_16x16x32_bf16 v[30:33], v[150:153], v[210:213], v[30:33]
	v_mfma_f32_16x16x32_bf16 v[26:29], v[158:161], v[210:213], v[26:29]
	v_mfma_f32_16x16x32_bf16 v[14:17], v[150:153], v[218:221], v[14:17]
	v_mfma_f32_16x16x32_bf16 v[10:13], v[158:161], v[218:221], v[10:13]
	v_mfma_f32_16x16x32_bf16 v[54:57], v[162:165], v[178:181], v[54:57]
	v_mfma_f32_16x16x32_bf16 v[50:53], v[170:173], v[178:181], v[50:53]
	v_mfma_f32_16x16x32_bf16 v[38:41], v[162:165], v[186:189], v[38:41]
	v_mfma_f32_16x16x32_bf16 v[34:37], v[170:173], v[186:189], v[34:37]
	v_mfma_f32_16x16x32_bf16 v[22:25], v[162:165], v[206:209], v[22:25]
	v_mfma_f32_16x16x32_bf16 v[18:21], v[170:173], v[206:209], v[18:21]
	v_mfma_f32_16x16x32_bf16 v[6:9], v[162:165], v[214:217], v[6:9]
	v_mfma_f32_16x16x32_bf16 v[2:5], v[170:173], v[214:217], v[2:5]
	v_mfma_f32_16x16x32_bf16 v[54:57], v[166:169], v[182:185], v[54:57]
	v_mfma_f32_16x16x32_bf16 v[50:53], v[174:177], v[182:185], v[50:53]
	v_mfma_f32_16x16x32_bf16 v[38:41], v[166:169], v[190:193], v[38:41]
	v_mfma_f32_16x16x32_bf16 v[34:37], v[174:177], v[190:193], v[34:37]
	v_mfma_f32_16x16x32_bf16 v[22:25], v[166:169], v[210:213], v[22:25]
	v_mfma_f32_16x16x32_bf16 v[18:21], v[174:177], v[210:213], v[18:21]
	v_mfma_f32_16x16x32_bf16 v[6:9], v[166:169], v[218:221], v[6:9]
	v_mfma_f32_16x16x32_bf16 v[2:5], v[174:177], v[218:221], v[2:5]
	s_setprio 0
	s_barrier
	s_add_i32 s42, s42, 2
	s_add_u32 s40, s40, 0x100
	s_addc_u32 s41, s41, 0
	s_add_u32 s16, s16, 0x800000
	s_addc_u32 s17, s17, 0
	s_cmp_gt_u32 s42, 13
	s_cbranch_scc0 .LBB0_53
	s_and_b64 vcc, exec, s[6:7]
	s_cbranch_vccz .LBB0_56
	s_barrier

; #define PG8_STAGE(bufoff, gbase, voff) do { _Pragma("unroll") for (int _i = 0; _i < 2; ++_i) \
;         __builtin_amdgcn_global_load_lds((const unsigned*)((const char*)(gbase) + (voff)[_i]), (PG8_LAS unsigned*)(lds + (bufoff) + ldsw + _i * 8192), 16, 0, 0); } while (0)
; #define PG8_LDA(dst, b, h) do { _Pragma("unroll") for (int m = 0; m < 4; ++m) _Pragma("unroll") for (int k = 0; k < 2; ++k) dst[m][k] = *(const PG8_LAS bf16x8*)(lds + PG8_SA(b, h) + aoff + m * 2048 + k * 1024); } while (0)
; #define PG8_LDB(dst, b, h) do { _Pragma("unroll") for (int n = 0; n < 2; ++n) _Pragma("unroll") for (int k = 0; k < 2; ++k) dst[n][k] = *(const PG8_LAS bf16x8*)(lds + PG8_SB(b, h) + boff + n * 2048 + k * 1024); } while (0)
; #define PG8_WAIT_V(n) asm volatile("s_waitcnt vmcnt(" #n ")" ::: "memory")
; #define PG8_WAIT_L(n) asm volatile("s_waitcnt lgkmcnt(" #n ")" ::: "memory")
; #define PG8_BAR __builtin_amdgcn_s_barrier()
; #define PG8_SCHED __builtin_amdgcn_sched_barrier(0)
; template <class Epi, class Sched, bool ALIGN_EPI = false, bool SP2 = false>
; __device__ __forceinline__ void gemm_phase(PG8_LAS unsigned char* lds, const Gemm g, const Sched& S, const Epi& E) {
;     ...
;             const bool last = (t == nt - 2);
;             const char* a1 = cA + (size_t)(t + 1) * kstepA;
;             const char* a2 = last ? nA : cA + (size_t)(t + 2) * kstepA; const char* b2 = last ? nB : cB + (size_t)(t + 2) * kstep;
;             const char* a3 = a2 + kstepA; const char* b3 = b2 + kstep;
;             if (last && has_next) S.a_ready(nxt);
;             if constexpr (SP2) {
;             PG8_LDB(B0, 0, 0); PG8_LDB(B1, 0, 1); PG8_SCHED; PG8_LDA(At, 0, 0); PG8_STAGE(PG8_SA(1, 1), a1 + hstepA, voffA);
;             PG8_WAIT_V(8); PG8_WAIT_L(0); PG8_BAR; PG8_MMA(0, 0, At, B0); PG8_MMA(0, 1, At, B1); PG8_BAR; PG8_SCHED;
;             PG8_LDA(At, 0, 1); PG8_STAGE(PG8_SB(0, 0), b2, voffB); PG8_STAGE(PG8_SB(0, 1), b2 + hstepB, voffB); PG8_STAGE(PG8_SA(0, 0), a2, voffA);
;             PG8_WAIT_V(8); PG8_WAIT_L(0); PG8_BAR; PG8_MMA(1, 0, At, B0); PG8_MMA(1, 1, At, B1); PG8_BAR; PG8_SCHED;
;             PG8_LDB(B0, 1, 0); PG8_LDB(B1, 1, 1); PG8_SCHED; PG8_LDA(At, 1, 0); PG8_STAGE(PG8_SA(0, 1), a2 + hstepA, voffA);
;             PG8_WAIT_V(8); PG8_WAIT_L(0); PG8_BAR; PG8_MMA(0, 0, At, B0); PG8_MMA(0, 1, At, B1); PG8_BAR; PG8_SCHED;
.LBB0_86:
	s_ashr_i32 s17, s16, 31
	s_lshl_b64 s[18:19], s[16:17], 15
	s_add_u32 s18, s70, s18
	s_addc_u32 s19, s71, s19
	s_and_b64 s[20:21], s[6:7], exec
	s_cselect_b32 s17, s19, s23
	s_cselect_b32 s42, s18, s22
	s_ashr_i32 s15, s14, 31
	s_lshl_b64 s[20:21], s[14:15], 19
	v_readlane_b32 s26, v253, 55
	v_readlane_b32 s27, v253, 56
	s_add_u32 s20, s26, s20
	s_addc_u32 s21, s27, s21
	s_and_b64 s[26:27], s[6:7], exec
	s_cselect_b32 s15, s21, s25
	s_cselect_b32 s43, s20, s24
	s_add_u32 s22, s22, 0x204000
	s_addc_u32 s23, s23, 0
	s_add_u32 s44, s24, 0x100
	s_addc_u32 s45, s25, 0
	s_mov_b32 s46, -2
	s_add_u32 s24, s22, 0x1fc000
	s_addc_u32 s25, s23, 0
	s_cmp_eq_u32 s46, 12
	s_cselect_b32 s28, s42, s24
	s_cselect_b32 s29, s17, s25
	s_cselect_b32 s26, s43, s44
	s_cselect_b32 s27, s15, s45
	s_add_u32 s24, s28, 0x200000
	s_addc_u32 s25, s29, 0
	s_add_i32 s47, 0, 0x10000
	s_add_i32 s50, 0, 0x14000
	v_add_u32_e32 v152, s47, v161
	v_add_u32_e32 v172, s50, v161
	ds_read_b128 v[130:133], v152
	ds_read_b128 v[134:137], v152 offset:1024
	ds_read_b128 v[138:141], v152 offset:2048
	ds_read_b128 v[152:155], v152 offset:3072
	ds_read_b128 v[156:159], v172
	ds_read_b128 v[164:167], v172 offset:1024
	ds_read_b128 v[168:171], v172 offset:2048
	ds_read_b128 v[172:175], v172 offset:3072
	s_add_i32 m0, s31, 0xc000
	ds_read_b128 v[176:179], v163
	ds_read_b128 v[180:183], v163 offset:1024
	ds_read_b128 v[184:187], v163 offset:2048
	ds_read_b128 v[188:191], v163 offset:3072
	ds_read_b128 v[206:209], v163 offset:4096
	ds_read_b128 v[210:213], v163 offset:5120
	ds_read_b128 v[214:217], v163 offset:6144
	ds_read_b128 v[218:221], v163 offset:7168
	global_load_lds_dwordx4 v148, s[22:23]
	s_add_i32 m0, s31, 0xe000
	s_nop 0
	global_load_lds_dwordx4 v150, s[22:23]
	s_waitcnt vmcnt(8)
	s_waitcnt lgkmcnt(0)
	s_barrier
	s_setprio 1
	v_mfma_f32_16x16x32_bf16 v[126:129], v[130:133], v[176:179], 0
	v_mfma_f32_16x16x32_bf16 v[122:125], v[138:141], v[176:179], 0
	v_mfma_f32_16x16x32_bf16 v[118:121], v[130:133], v[184:187], 0
	v_mfma_f32_16x16x32_bf16 v[106:109], v[138:141], v[184:187], 0
	v_mfma_f32_16x16x32_bf16 v[102:105], v[130:133], v[206:209], 0
	v_mfma_f32_16x16x32_bf16 v[90:93], v[138:141], v[206:209], 0
	v_mfma_f32_16x16x32_bf16 v[86:89], v[130:133], v[214:217], 0
	v_mfma_f32_16x16x32_bf16 v[74:77], v[138:141], v[214:217], 0
	v_mfma_f32_16x16x32_bf16 v[126:129], v[134:137], v[180:183], v[126:129]
	v_mfma_f32_16x16x32_bf16 v[122:125], v[152:155], v[180:183], v[122:125]
	v_mfma_f32_16x16x32_bf16 v[118:121], v[134:137], v[188:191], v[118:121]
	v_mfma_f32_16x16x32_bf16 v[106:109], v[152:155], v[188:191], v[106:109]
	v_mfma_f32_16x16x32_bf16 v[102:105], v[134:137], v[210:213], v[102:105]
	v_mfma_f32_16x16x32_bf16 v[90:93], v[152:155], v[210:213], v[90:93]
	v_mfma_f32_16x16x32_bf16 v[86:89], v[134:137], v[218:221], v[86:89]
	v_mfma_f32_16x16x32_bf16 v[74:77], v[152:155], v[218:221], v[74:77]
	v_mfma_f32_16x16x32_bf16 v[114:117], v[156:159], v[176:179], 0
	v_mfma_f32_16x16x32_bf16 v[110:113], v[168:171], v[176:179], 0
	v_mfma_f32_16x16x32_bf16 v[98:101], v[156:159], v[184:187], 0
	v_mfma_f32_16x16x32_bf16 v[94:97], v[168:171], v[184:187], 0
	v_mfma_f32_16x16x32_bf16 v[82:85], v[156:159], v[206:209], 0
	v_mfma_f32_16x16x32_bf16 v[78:81], v[168:171], v[206:209], 0
	v_mfma_f32_16x16x32_bf16 v[70:73], v[156:159], v[214:217], 0
	v_mfma_f32_16x16x32_bf16 v[66:69], v[168:171], v[214:217], 0
	v_mfma_f32_16x16x32_bf16 v[114:117], v[164:167], v[180:183], v[114:117]
	v_mfma_f32_16x16x32_bf16 v[110:113], v[172:175], v[180:183], v[110:113]
	v_mfma_f32_16x16x32_bf16 v[98:101], v[164:167], v[188:191], v[98:101]
	v_mfma_f32_16x16x32_bf16 v[94:97], v[172:175], v[188:191], v[94:97]
	v_mfma_f32_16x16x32_bf16 v[82:85], v[164:167], v[210:213], v[82:85]
	v_mfma_f32_16x16x32_bf16 v[78:81], v[172:175], v[210:213], v[78:81]
	v_mfma_f32_16x16x32_bf16 v[70:73], v[164:167], v[218:221], v[70:73]
	v_mfma_f32_16x16x32_bf16 v[66:69], v[172:175], v[218:221], v[66:69]
	s_setprio 0
	s_barrier
	s_add_i32 s47, s47, s30
	v_lshl_add_u64 v[192:193], s[26:27], 0, v[0:1]
	s_mov_b32 m0, s47
	ds_read_b128 v[176:179], v163 offset:16384
	ds_read_b128 v[180:183], v163 offset:17408
	ds_read_b128 v[184:187], v163 offset:18432
	ds_read_b128 v[188:191], v163 offset:19456
	ds_read_b128 v[206:209], v163 offset:20480
	ds_read_b128 v[210:213], v163 offset:21504
	ds_read_b128 v[214:217], v163 offset:22528
	ds_read_b128 v[218:221], v163 offset:23552
	global_load_lds_dwordx4 v[192:193], off
	s_add_i32 m0, s47, 0x2000
	s_add_u32 s48, s26, 0x40000
	v_lshl_add_u64 v[222:223], s[26:27], 0, v[142:143]
	s_addc_u32 s49, s27, 0
	s_add_i32 s47, s50, s30
	global_load_lds_dwordx4 v142, s[26:27]
	v_lshl_add_u64 v[224:225], s[48:49], 0, v[0:1]
	s_mov_b32 m0, s47
	s_nop 0
	global_load_lds_dwordx4 v[224:225], off
	s_add_i32 m0, s47, 0x2000
	s_nop 0
	global_load_lds_dwordx4 v142, s[48:49]
	s_mov_b32 m0, s31
	s_nop 0
	global_load_lds_dwordx4 v146, s[28:29]
	s_mov_b32 m0, s34
	s_nop 0
	global_load_lds_dwordx4 v144, s[28:29]
	s_waitcnt vmcnt(8)
	s_waitcnt lgkmcnt(0)
	s_barrier
; #define PG8_STAGE(bufoff, gbase, voff) do { _Pragma("unroll") for (int _i = 0; _i < 2; ++_i) \
;         __builtin_amdgcn_global_load_lds((const unsigned*)((const char*)(gbase) + (voff)[_i]), (PG8_LAS unsigned*)(lds + (bufoff) + ldsw + _i * 8192), 16, 0, 0); } while (0)
; #define PG8_LDA(dst, b, h) do { _Pragma("unroll") for (int m = 0; m < 4; ++m) _Pragma("unroll") for (int k = 0; k < 2; ++k) dst[m][k] = *(const PG8_LAS bf16x8*)(lds + PG8_SA(b, h) + aoff + m * 2048 + k * 1024); } while (0)
; #define PG8_LDB(dst, b, h) do { _Pragma("unroll") for (int n = 0; n < 2; ++n) _Pragma("unroll") for (int k = 0; k < 2; ++k) dst[n][k] = *(const PG8_LAS bf16x8*)(lds + PG8_SB(b, h) + boff + n * 2048 + k * 1024); } while (0)
; #define PG8_MMA(ai, bj, At, Bt) do { __builtin_amdgcn_s_setprio(1); _Pragma("unroll") for (int m = 0; m < 4; ++m) _Pragma("unroll") for (int n = 0; n < 2; ++n) _Pragma("unroll") for (int k = 0; k < 2; ++k) \
;         acc[ai][bj][m][n] = __builtin_amdgcn_mfma_f32_16x16x32_bf16(Bt[n][k], At[m][k], acc[ai][bj][m][n], 0, 0, 0); __builtin_amdgcn_s_setprio(0); } while (0)
; #define PG8_WAIT_V(n) asm volatile("s_waitcnt vmcnt(" #n ")" ::: "memory")
; #define PG8_WAIT_L(n) asm volatile("s_waitcnt lgkmcnt(" #n ")" ::: "memory")
; #define PG8_BAR __builtin_amdgcn_s_barrier()
; #define PG8_SCHED __builtin_amdgcn_sched_barrier(0)
; template <class Epi, class Sched, bool ALIGN_EPI = false, bool SP2 = false>
; __device__ __forceinline__ void gemm_phase(PG8_LAS unsigned char* lds, const Gemm g, const Sched& S, const Epi& E) {
;     ...
;             PG8_WAIT_V(8); PG8_WAIT_L(0); PG8_BAR; PG8_MMA(1, 0, At, B0); PG8_MMA(1, 1, At, B1); PG8_BAR; PG8_SCHED;
;             PG8_LDB(B0, 1, 0); PG8_LDB(B1, 1, 1); PG8_SCHED; PG8_LDA(At, 1, 0); PG8_STAGE(PG8_SA(0, 1), a2 + hstepA, voffA);
;             PG8_WAIT_V(8); PG8_WAIT_L(0); PG8_BAR; PG8_MMA(0, 0, At, B0); PG8_MMA(0, 1, At, B1); PG8_BAR; PG8_SCHED;
;             PG8_LDA(At, 1, 1); PG8_STAGE(PG8_SB(1, 0), b3, voffB); PG8_STAGE(PG8_SB(1, 1), b3 + hstepB, voffB); PG8_STAGE(PG8_SA(1, 0), a3, voffA);
;             PG8_WAIT_V(8); PG8_WAIT_L(0); PG8_BAR; PG8_MMA(1, 0, At, B0); PG8_MMA(1, 1, At, B1); PG8_BAR; PG8_SCHED;
	s_setprio 1
	v_mfma_f32_16x16x32_bf16 v[62:65], v[130:133], v[176:179], 0
	v_mfma_f32_16x16x32_bf16 v[58:61], v[138:141], v[176:179], 0
	v_mfma_f32_16x16x32_bf16 v[54:57], v[130:133], v[184:187], 0
	v_mfma_f32_16x16x32_bf16 v[42:45], v[138:141], v[184:187], 0
	v_mfma_f32_16x16x32_bf16 v[38:41], v[130:133], v[206:209], 0
	v_mfma_f32_16x16x32_bf16 v[26:29], v[138:141], v[206:209], 0
	v_mfma_f32_16x16x32_bf16 v[22:25], v[130:133], v[214:217], 0
	v_mfma_f32_16x16x32_bf16 v[10:13], v[138:141], v[214:217], 0
	v_mfma_f32_16x16x32_bf16 v[62:65], v[134:137], v[180:183], v[62:65]
	v_mfma_f32_16x16x32_bf16 v[58:61], v[152:155], v[180:183], v[58:61]
	v_mfma_f32_16x16x32_bf16 v[54:57], v[134:137], v[188:191], v[54:57]
	v_mfma_f32_16x16x32_bf16 v[42:45], v[152:155], v[188:191], v[42:45]
	v_mfma_f32_16x16x32_bf16 v[38:41], v[134:137], v[210:213], v[38:41]
	v_mfma_f32_16x16x32_bf16 v[26:29], v[152:155], v[210:213], v[26:29]
	v_mfma_f32_16x16x32_bf16 v[22:25], v[134:137], v[218:221], v[22:25]
	v_mfma_f32_16x16x32_bf16 v[10:13], v[152:155], v[218:221], v[10:13]
	v_mfma_f32_16x16x32_bf16 v[50:53], v[156:159], v[176:179], 0
	v_mfma_f32_16x16x32_bf16 v[46:49], v[168:171], v[176:179], 0
	v_mfma_f32_16x16x32_bf16 v[34:37], v[156:159], v[184:187], 0
	v_mfma_f32_16x16x32_bf16 v[30:33], v[168:171], v[184:187], 0
	v_mfma_f32_16x16x32_bf16 v[18:21], v[156:159], v[206:209], 0
	v_mfma_f32_16x16x32_bf16 v[14:17], v[168:171], v[206:209], 0
	v_mfma_f32_16x16x32_bf16 v[6:9], v[156:159], v[214:217], 0
	v_mfma_f32_16x16x32_bf16 v[2:5], v[168:171], v[214:217], 0
	v_mfma_f32_16x16x32_bf16 v[50:53], v[164:167], v[180:183], v[50:53]
	v_mfma_f32_16x16x32_bf16 v[46:49], v[172:175], v[180:183], v[46:49]
	v_mfma_f32_16x16x32_bf16 v[34:37], v[164:167], v[188:191], v[34:37]
	v_mfma_f32_16x16x32_bf16 v[30:33], v[172:175], v[188:191], v[30:33]
	v_mfma_f32_16x16x32_bf16 v[18:21], v[164:167], v[210:213], v[18:21]
	v_mfma_f32_16x16x32_bf16 v[14:17], v[172:175], v[210:213], v[14:17]
	v_mfma_f32_16x16x32_bf16 v[6:9], v[164:167], v[218:221], v[6:9]
	v_mfma_f32_16x16x32_bf16 v[2:5], v[172:175], v[218:221], v[2:5]
	s_setprio 0
	s_barrier
	s_add_i32 s47, 0, 0x18000
	s_add_i32 s48, 0, 0x1c000
	v_add_u32_e32 v152, s47, v161
	v_add_u32_e32 v172, s48, v161
	ds_read_b128 v[130:133], v152
	ds_read_b128 v[134:137], v152 offset:1024
	ds_read_b128 v[138:141], v152 offset:2048
	ds_read_b128 v[152:155], v152 offset:3072
	ds_read_b128 v[156:159], v172
	ds_read_b128 v[164:167], v172 offset:1024
	ds_read_b128 v[168:171], v172 offset:2048
	ds_read_b128 v[172:175], v172 offset:3072
	s_add_u32 s28, s28, 0x4000
	s_addc_u32 s29, s29, 0
	s_mov_b32 m0, s35
	ds_read_b128 v[176:179], v163 offset:32768
	ds_read_b128 v[180:183], v163 offset:33792
	ds_read_b128 v[184:187], v163 offset:34816
	ds_read_b128 v[188:191], v163 offset:35840
	ds_read_b128 v[206:209], v163 offset:36864
	ds_read_b128 v[210:213], v163 offset:37888
	ds_read_b128 v[214:217], v163 offset:38912
	ds_read_b128 v[218:221], v163 offset:39936
	global_load_lds_dwordx4 v146, s[28:29]
	v_lshl_add_u64 v[224:225], s[28:29], 0, v[144:145]
	s_mov_b32 m0, s36
	s_nop 0
	global_load_lds_dwordx4 v144, s[28:29]
	s_waitcnt vmcnt(8)
	s_waitcnt lgkmcnt(0)
	s_barrier
	s_setprio 1
	v_mfma_f32_16x16x32_bf16 v[126:129], v[130:133], v[176:179], v[126:129]
	v_mfma_f32_16x16x32_bf16 v[122:125], v[138:141], v[176:179], v[122:125]
	v_mfma_f32_16x16x32_bf16 v[118:121], v[130:133], v[184:187], v[118:121]
	v_mfma_f32_16x16x32_bf16 v[106:109], v[138:141], v[184:187], v[106:109]
	v_mfma_f32_16x16x32_bf16 v[102:105], v[130:133], v[206:209], v[102:105]
	v_mfma_f32_16x16x32_bf16 v[90:93], v[138:141], v[206:209], v[90:93]
	v_mfma_f32_16x16x32_bf16 v[86:89], v[130:133], v[214:217], v[86:89]
	v_mfma_f32_16x16x32_bf16 v[74:77], v[138:141], v[214:217], v[74:77]
	v_mfma_f32_16x16x32_bf16 v[126:129], v[134:137], v[180:183], v[126:129]
	v_mfma_f32_16x16x32_bf16 v[122:125], v[152:155], v[180:183], v[122:125]
	v_mfma_f32_16x16x32_bf16 v[118:121], v[134:137], v[188:191], v[118:121]
	v_mfma_f32_16x16x32_bf16 v[106:109], v[152:155], v[188:191], v[106:109]
	v_mfma_f32_16x16x32_bf16 v[102:105], v[134:137], v[210:213], v[102:105]
	v_mfma_f32_16x16x32_bf16 v[90:93], v[152:155], v[210:213], v[90:93]
	v_mfma_f32_16x16x32_bf16 v[86:89], v[134:137], v[218:221], v[86:89]
	v_mfma_f32_16x16x32_bf16 v[74:77], v[152:155], v[218:221], v[74:77]
	v_mfma_f32_16x16x32_bf16 v[114:117], v[156:159], v[176:179], v[114:117]
	v_mfma_f32_16x16x32_bf16 v[110:113], v[168:171], v[176:179], v[110:113]
	v_mfma_f32_16x16x32_bf16 v[98:101], v[156:159], v[184:187], v[98:101]
	v_mfma_f32_16x16x32_bf16 v[94:97], v[168:171], v[184:187], v[94:97]
	v_mfma_f32_16x16x32_bf16 v[82:85], v[156:159], v[206:209], v[82:85]
	v_mfma_f32_16x16x32_bf16 v[78:81], v[168:171], v[206:209], v[78:81]
	v_mfma_f32_16x16x32_bf16 v[70:73], v[156:159], v[214:217], v[70:73]
	v_mfma_f32_16x16x32_bf16 v[66:69], v[168:171], v[214:217], v[66:69]
	v_mfma_f32_16x16x32_bf16 v[114:117], v[164:167], v[180:183], v[114:117]
	v_mfma_f32_16x16x32_bf16 v[110:113], v[172:175], v[180:183], v[110:113]
	v_mfma_f32_16x16x32_bf16 v[98:101], v[164:167], v[188:191], v[98:101]
	v_mfma_f32_16x16x32_bf16 v[94:97], v[172:175], v[188:191], v[94:97]
	v_mfma_f32_16x16x32_bf16 v[82:85], v[164:167], v[210:213], v[82:85]
	v_mfma_f32_16x16x32_bf16 v[78:81], v[172:175], v[210:213], v[78:81]
	v_mfma_f32_16x16x32_bf16 v[70:73], v[164:167], v[218:221], v[70:73]
	v_mfma_f32_16x16x32_bf16 v[66:69], v[172:175], v[218:221], v[66:69]
	s_setprio 0
	s_barrier
; #define PG8_STAGE(bufoff, gbase, voff) do { _Pragma("unroll") for (int _i = 0; _i < 2; ++_i) \
;         __builtin_amdgcn_global_load_lds((const unsigned*)((const char*)(gbase) + (voff)[_i]), (PG8_LAS unsigned*)(lds + (bufoff) + ldsw + _i * 8192), 16, 0, 0); } while (0)
; #define PG8_LDA(dst, b, h) do { _Pragma("unroll") for (int m = 0; m < 4; ++m) _Pragma("unroll") for (int k = 0; k < 2; ++k) dst[m][k] = *(const PG8_LAS bf16x8*)(lds + PG8_SA(b, h) + aoff + m * 2048 + k * 1024); } while (0)
; #define PG8_LDB(dst, b, h) do { _Pragma("unroll") for (int n = 0; n < 2; ++n) _Pragma("unroll") for (int k = 0; k < 2; ++k) dst[n][k] = *(const PG8_LAS bf16x8*)(lds + PG8_SB(b, h) + boff + n * 2048 + k * 1024); } while (0)
; #define PG8_MMA(ai, bj, At, Bt) do { __builtin_amdgcn_s_setprio(1); _Pragma("unroll") for (int m = 0; m < 4; ++m) _Pragma("unroll") for (int n = 0; n < 2; ++n) _Pragma("unroll") for (int k = 0; k < 2; ++k) \
;         acc[ai][bj][m][n] = __builtin_amdgcn_mfma_f32_16x16x32_bf16(Bt[n][k], At[m][k], acc[ai][bj][m][n], 0, 0, 0); __builtin_amdgcn_s_setprio(0); } while (0)
; #define PG8_BAR __builtin_amdgcn_s_barrier()
; template <class Epi, class Sched, bool ALIGN_EPI = false, bool SP2 = false>
; __device__ __forceinline__ void gemm_phase(PG8_LAS unsigned char* lds, const Gemm g, const Sched& S, const Epi& E) {
;     ...
;             const bool last = (t == nt - 2);
;             const char* a1 = cA + (size_t)(t + 1) * kstepA;
;             const char* a2 = last ? nA : cA + (size_t)(t + 2) * kstepA; const char* b2 = last ? nB : cB + (size_t)(t + 2) * kstep;
;             const char* a3 = a2 + kstepA; const char* b3 = b2 + kstep;
;             if (last && has_next) S.a_ready(nxt);
;             if constexpr (SP2) {
;             PG8_LDB(B0, 0, 0); PG8_LDB(B1, 0, 1); PG8_SCHED; PG8_LDA(At, 0, 0); PG8_STAGE(PG8_SA(1, 1), a1 + hstepA, voffA);
;             PG8_WAIT_V(8); PG8_WAIT_L(0); PG8_BAR; PG8_MMA(0, 0, At, B0); PG8_MMA(0, 1, At, B1); PG8_BAR; PG8_SCHED;
;     ...
;             PG8_WAIT_V(8); PG8_WAIT_L(0); PG8_BAR; PG8_MMA(0, 0, At, B0); PG8_MMA(0, 1, At, B1); PG8_BAR; PG8_SCHED;
;             PG8_LDA(At, 1, 1); PG8_STAGE(PG8_SB(1, 0), b3, voffB); PG8_STAGE(PG8_SB(1, 1), b3 + hstepB, voffB); PG8_STAGE(PG8_SA(1, 0), a3, voffA);
;             PG8_WAIT_V(8); PG8_WAIT_L(0); PG8_BAR; PG8_MMA(1, 0, At, B0); PG8_MMA(1, 1, At, B1); PG8_BAR; PG8_SCHED;
	s_add_i32 s28, s47, s30
	v_lshl_add_u64 v[192:193], v[192:193], 0, s[78:79]
	s_mov_b32 m0, s28
	ds_read_b128 v[176:179], v163 offset:49152
	ds_read_b128 v[180:183], v163 offset:50176
	ds_read_b128 v[184:187], v163 offset:51200
	ds_read_b128 v[188:191], v163 offset:52224
	ds_read_b128 v[206:209], v163 offset:53248
	ds_read_b128 v[210:213], v163 offset:54272
	ds_read_b128 v[214:217], v163 offset:55296
	ds_read_b128 v[218:221], v163 offset:56320
	global_load_lds_dwordx4 v[192:193], off
	s_add_i32 m0, s28, 0x2000
	s_add_u32 s26, s26, 0x40080
	v_lshl_add_u64 v[192:193], v[222:223], 0, s[78:79]
	s_addc_u32 s27, s27, 0
	s_add_i32 s28, s48, s30
	global_load_lds_dwordx4 v[192:193], off
	v_lshl_add_u64 v[192:193], s[26:27], 0, v[0:1]
	s_mov_b32 m0, s28
	s_nop 0
	global_load_lds_dwordx4 v[192:193], off
	s_add_i32 m0, s28, 0x2000
	s_nop 0
	global_load_lds_dwordx4 v142, s[26:27]
	s_mov_b32 m0, s37
	s_nop 0
	global_load_lds_dwordx4 v146, s[24:25]
	s_mov_b32 m0, s38
	s_nop 0
	global_load_lds_dwordx4 v144, s[24:25]
	s_waitcnt vmcnt(8)
	s_waitcnt lgkmcnt(0)
	s_barrier
	s_setprio 1
	v_mfma_f32_16x16x32_bf16 v[62:65], v[130:133], v[176:179], v[62:65]
	v_mfma_f32_16x16x32_bf16 v[58:61], v[138:141], v[176:179], v[58:61]
	v_mfma_f32_16x16x32_bf16 v[54:57], v[130:133], v[184:187], v[54:57]
	v_mfma_f32_16x16x32_bf16 v[42:45], v[138:141], v[184:187], v[42:45]
	v_mfma_f32_16x16x32_bf16 v[38:41], v[130:133], v[206:209], v[38:41]
	v_mfma_f32_16x16x32_bf16 v[26:29], v[138:141], v[206:209], v[26:29]
	v_mfma_f32_16x16x32_bf16 v[22:25], v[130:133], v[214:217], v[22:25]
	v_mfma_f32_16x16x32_bf16 v[10:13], v[138:141], v[214:217], v[10:13]
	v_mfma_f32_16x16x32_bf16 v[62:65], v[134:137], v[180:183], v[62:65]
	v_mfma_f32_16x16x32_bf16 v[58:61], v[152:155], v[180:183], v[58:61]
	v_mfma_f32_16x16x32_bf16 v[54:57], v[134:137], v[188:191], v[54:57]
	v_mfma_f32_16x16x32_bf16 v[42:45], v[152:155], v[188:191], v[42:45]
	v_mfma_f32_16x16x32_bf16 v[38:41], v[134:137], v[210:213], v[38:41]
	v_mfma_f32_16x16x32_bf16 v[26:29], v[152:155], v[210:213], v[26:29]
	v_mfma_f32_16x16x32_bf16 v[22:25], v[134:137], v[218:221], v[22:25]
	v_mfma_f32_16x16x32_bf16 v[10:13], v[152:155], v[218:221], v[10:13]
	v_mfma_f32_16x16x32_bf16 v[50:53], v[156:159], v[176:179], v[50:53]
	v_mfma_f32_16x16x32_bf16 v[46:49], v[168:171], v[176:179], v[46:49]
	v_mfma_f32_16x16x32_bf16 v[34:37], v[156:159], v[184:187], v[34:37]
	v_mfma_f32_16x16x32_bf16 v[30:33], v[168:171], v[184:187], v[30:33]
	v_mfma_f32_16x16x32_bf16 v[18:21], v[156:159], v[206:209], v[18:21]
	v_mfma_f32_16x16x32_bf16 v[14:17], v[168:171], v[206:209], v[14:17]
	v_mfma_f32_16x16x32_bf16 v[6:9], v[156:159], v[214:217], v[6:9]
	v_mfma_f32_16x16x32_bf16 v[2:5], v[168:171], v[214:217], v[2:5]
	v_mfma_f32_16x16x32_bf16 v[50:53], v[164:167], v[180:183], v[50:53]
	v_mfma_f32_16x16x32_bf16 v[46:49], v[172:175], v[180:183], v[46:49]
	v_mfma_f32_16x16x32_bf16 v[34:37], v[164:167], v[188:191], v[34:37]
	v_mfma_f32_16x16x32_bf16 v[30:33], v[172:175], v[188:191], v[30:33]
	v_mfma_f32_16x16x32_bf16 v[18:21], v[164:167], v[210:213], v[18:21]
	v_mfma_f32_16x16x32_bf16 v[14:17], v[172:175], v[210:213], v[14:17]
	v_mfma_f32_16x16x32_bf16 v[6:9], v[164:167], v[218:221], v[6:9]
	v_mfma_f32_16x16x32_bf16 v[2:5], v[172:175], v[218:221], v[2:5]
	s_setprio 0
	s_barrier
	s_add_i32 s46, s46, 2
	s_add_u32 s22, s22, 0x400000
	s_addc_u32 s23, s23, 0
	s_add_u32 s44, s44, 0x100
	s_addc_u32 s45, s45, 0
.LBB0_87:
	s_add_u32 s24, s22, 0x1fc000
	s_addc_u32 s25, s23, 0
	s_cmp_eq_u32 s46, 12
	s_cselect_b32 s28, s42, s24
	s_cselect_b32 s29, s17, s25
	s_cselect_b32 s26, s43, s44
	s_cselect_b32 s27, s15, s45
	s_add_u32 s24, s28, 0x200000
	s_addc_u32 s25, s29, 0
	s_add_i32 s47, 0, 0x10000
	s_add_i32 s50, 0, 0x14000
	v_add_u32_e32 v152, s47, v161
	v_add_u32_e32 v172, s50, v161
	ds_read_b128 v[130:133], v152
	ds_read_b128 v[134:137], v152 offset:1024
	ds_read_b128 v[138:141], v152 offset:2048
	ds_read_b128 v[152:155], v152 offset:3072
	ds_read_b128 v[156:159], v172
	ds_read_b128 v[164:167], v172 offset:1024
	ds_read_b128 v[168:171], v172 offset:2048
	ds_read_b128 v[172:175], v172 offset:3072
	s_add_i32 m0, s31, 0xc000
	ds_read_b128 v[176:179], v163
	ds_read_b128 v[180:183], v163 offset:1024
	ds_read_b128 v[184:187], v163 offset:2048
	ds_read_b128 v[188:191], v163 offset:3072
	ds_read_b128 v[206:209], v163 offset:4096
	ds_read_b128 v[210:213], v163 offset:5120
	ds_read_b128 v[214:217], v163 offset:6144
	ds_read_b128 v[218:221], v163 offset:7168
	global_load_lds_dwordx4 v148, s[22:23]
	s_add_i32 m0, s31, 0xe000
	s_nop 0
	global_load_lds_dwordx4 v150, s[22:23]
	s_waitcnt vmcnt(8)
	s_waitcnt lgkmcnt(0)
	s_barrier
; #define PG8_STAGE(bufoff, gbase, voff) do { _Pragma("unroll") for (int _i = 0; _i < 2; ++_i) \
;         __builtin_amdgcn_global_load_lds((const unsigned*)((const char*)(gbase) + (voff)[_i]), (PG8_LAS unsigned*)(lds + (bufoff) + ldsw + _i * 8192), 16, 0, 0); } while (0)
; #define PG8_LDA(dst, b, h) do { _Pragma("unroll") for (int m = 0; m < 4; ++m) _Pragma("unroll") for (int k = 0; k < 2; ++k) dst[m][k] = *(const PG8_LAS bf16x8*)(lds + PG8_SA(b, h) + aoff + m * 2048 + k * 1024); } while (0)
; #define PG8_LDB(dst, b, h) do { _Pragma("unroll") for (int n = 0; n < 2; ++n) _Pragma("unroll") for (int k = 0; k < 2; ++k) dst[n][k] = *(const PG8_LAS bf16x8*)(lds + PG8_SB(b, h) + boff + n * 2048 + k * 1024); } while (0)
; #define PG8_MMA(ai, bj, At, Bt) do { __builtin_amdgcn_s_setprio(1); _Pragma("unroll") for (int m = 0; m < 4; ++m) _Pragma("unroll") for (int n = 0; n < 2; ++n) _Pragma("unroll") for (int k = 0; k < 2; ++k) \
;         acc[ai][bj][m][n] = __builtin_amdgcn_mfma_f32_16x16x32_bf16(Bt[n][k], At[m][k], acc[ai][bj][m][n], 0, 0, 0); __builtin_amdgcn_s_setprio(0); } while (0)
; #define PG8_WAIT_V(n) asm volatile("s_waitcnt vmcnt(" #n ")" ::: "memory")
; #define PG8_WAIT_L(n) asm volatile("s_waitcnt lgkmcnt(" #n ")" ::: "memory")
; #define PG8_BAR __builtin_amdgcn_s_barrier()
; #define PG8_SCHED __builtin_amdgcn_sched_barrier(0)
; template <class Epi, class Sched, bool ALIGN_EPI = false, bool SP2 = false>
; __device__ __forceinline__ void gemm_phase(PG8_LAS unsigned char* lds, const Gemm g, const Sched& S, const Epi& E) {
;     ...
;             PG8_WAIT_V(8); PG8_WAIT_L(0); PG8_BAR; PG8_MMA(0, 0, At, B0); PG8_MMA(0, 1, At, B1); PG8_BAR; PG8_SCHED;
;             PG8_LDA(At, 0, 1); PG8_STAGE(PG8_SB(0, 0), b2, voffB); PG8_STAGE(PG8_SB(0, 1), b2 + hstepB, voffB); PG8_STAGE(PG8_SA(0, 0), a2, voffA);
;             PG8_WAIT_V(8); PG8_WAIT_L(0); PG8_BAR; PG8_MMA(1, 0, At, B0); PG8_MMA(1, 1, At, B1); PG8_BAR; PG8_SCHED;
;             PG8_LDB(B0, 1, 0); PG8_LDB(B1, 1, 1); PG8_SCHED; PG8_LDA(At, 1, 0); PG8_STAGE(PG8_SA(0, 1), a2 + hstepA, voffA);
;             PG8_WAIT_V(8); PG8_WAIT_L(0); PG8_BAR; PG8_MMA(0, 0, At, B0); PG8_MMA(0, 1, At, B1); PG8_BAR; PG8_SCHED;
	s_setprio 1
	v_mfma_f32_16x16x32_bf16 v[126:129], v[130:133], v[176:179], v[126:129]
	v_mfma_f32_16x16x32_bf16 v[122:125], v[138:141], v[176:179], v[122:125]
	v_mfma_f32_16x16x32_bf16 v[118:121], v[130:133], v[184:187], v[118:121]
	v_mfma_f32_16x16x32_bf16 v[106:109], v[138:141], v[184:187], v[106:109]
	v_mfma_f32_16x16x32_bf16 v[102:105], v[130:133], v[206:209], v[102:105]
	v_mfma_f32_16x16x32_bf16 v[90:93], v[138:141], v[206:209], v[90:93]
	v_mfma_f32_16x16x32_bf16 v[86:89], v[130:133], v[214:217], v[86:89]
	v_mfma_f32_16x16x32_bf16 v[74:77], v[138:141], v[214:217], v[74:77]
	v_mfma_f32_16x16x32_bf16 v[126:129], v[134:137], v[180:183], v[126:129]
	v_mfma_f32_16x16x32_bf16 v[122:125], v[152:155], v[180:183], v[122:125]
	v_mfma_f32_16x16x32_bf16 v[118:121], v[134:137], v[188:191], v[118:121]
	v_mfma_f32_16x16x32_bf16 v[106:109], v[152:155], v[188:191], v[106:109]
	v_mfma_f32_16x16x32_bf16 v[102:105], v[134:137], v[210:213], v[102:105]
	v_mfma_f32_16x16x32_bf16 v[90:93], v[152:155], v[210:213], v[90:93]
	v_mfma_f32_16x16x32_bf16 v[86:89], v[134:137], v[218:221], v[86:89]
	v_mfma_f32_16x16x32_bf16 v[74:77], v[152:155], v[218:221], v[74:77]
	v_mfma_f32_16x16x32_bf16 v[114:117], v[156:159], v[176:179], v[114:117]
	v_mfma_f32_16x16x32_bf16 v[110:113], v[168:171], v[176:179], v[110:113]
	v_mfma_f32_16x16x32_bf16 v[98:101], v[156:159], v[184:187], v[98:101]
	v_mfma_f32_16x16x32_bf16 v[94:97], v[168:171], v[184:187], v[94:97]
	v_mfma_f32_16x16x32_bf16 v[82:85], v[156:159], v[206:209], v[82:85]
	v_mfma_f32_16x16x32_bf16 v[78:81], v[168:171], v[206:209], v[78:81]
	v_mfma_f32_16x16x32_bf16 v[70:73], v[156:159], v[214:217], v[70:73]
	v_mfma_f32_16x16x32_bf16 v[66:69], v[168:171], v[214:217], v[66:69]
	v_mfma_f32_16x16x32_bf16 v[114:117], v[164:167], v[180:183], v[114:117]
	v_mfma_f32_16x16x32_bf16 v[110:113], v[172:175], v[180:183], v[110:113]
	v_mfma_f32_16x16x32_bf16 v[98:101], v[164:167], v[188:191], v[98:101]
	v_mfma_f32_16x16x32_bf16 v[94:97], v[172:175], v[188:191], v[94:97]
	v_mfma_f32_16x16x32_bf16 v[82:85], v[164:167], v[210:213], v[82:85]
	v_mfma_f32_16x16x32_bf16 v[78:81], v[172:175], v[210:213], v[78:81]
	v_mfma_f32_16x16x32_bf16 v[70:73], v[164:167], v[218:221], v[70:73]
	v_mfma_f32_16x16x32_bf16 v[66:69], v[172:175], v[218:221], v[66:69]
	s_setprio 0
	s_barrier
	s_add_i32 s47, s47, s30
	v_lshl_add_u64 v[192:193], s[26:27], 0, v[0:1]
	s_mov_b32 m0, s47
	ds_read_b128 v[176:179], v163 offset:16384
	ds_read_b128 v[180:183], v163 offset:17408
	ds_read_b128 v[184:187], v163 offset:18432
	ds_read_b128 v[188:191], v163 offset:19456
	ds_read_b128 v[206:209], v163 offset:20480
	ds_read_b128 v[210:213], v163 offset:21504
	ds_read_b128 v[214:217], v163 offset:22528
	ds_read_b128 v[218:221], v163 offset:23552
	global_load_lds_dwordx4 v[192:193], off
	s_add_i32 m0, s47, 0x2000
	s_add_u32 s48, s26, 0x40000
	v_lshl_add_u64 v[222:223], s[26:27], 0, v[142:143]
	s_addc_u32 s49, s27, 0
	s_add_i32 s47, s50, s30
	global_load_lds_dwordx4 v142, s[26:27]
	v_lshl_add_u64 v[224:225], s[48:49], 0, v[0:1]
	s_mov_b32 m0, s47
	s_nop 0
	global_load_lds_dwordx4 v[224:225], off
	s_add_i32 m0, s47, 0x2000
	s_nop 0
	global_load_lds_dwordx4 v142, s[48:49]
	s_mov_b32 m0, s31
	s_nop 0
	global_load_lds_dwordx4 v146, s[28:29]
	s_mov_b32 m0, s34
	s_nop 0
	global_load_lds_dwordx4 v144, s[28:29]
	s_waitcnt vmcnt(8)
	s_waitcnt lgkmcnt(0)
	s_barrier
	s_setprio 1
	v_mfma_f32_16x16x32_bf16 v[62:65], v[130:133], v[176:179], v[62:65]
	v_mfma_f32_16x16x32_bf16 v[58:61], v[138:141], v[176:179], v[58:61]
	v_mfma_f32_16x16x32_bf16 v[54:57], v[130:133], v[184:187], v[54:57]
	v_mfma_f32_16x16x32_bf16 v[42:45], v[138:141], v[184:187], v[42:45]
	v_mfma_f32_16x16x32_bf16 v[38:41], v[130:133], v[206:209], v[38:41]
	v_mfma_f32_16x16x32_bf16 v[26:29], v[138:141], v[206:209], v[26:29]
	v_mfma_f32_16x16x32_bf16 v[22:25], v[130:133], v[214:217], v[22:25]
	v_mfma_f32_16x16x32_bf16 v[10:13], v[138:141], v[214:217], v[10:13]
	v_mfma_f32_16x16x32_bf16 v[62:65], v[134:137], v[180:183], v[62:65]
	v_mfma_f32_16x16x32_bf16 v[58:61], v[152:155], v[180:183], v[58:61]
	v_mfma_f32_16x16x32_bf16 v[54:57], v[134:137], v[188:191], v[54:57]
	v_mfma_f32_16x16x32_bf16 v[42:45], v[152:155], v[188:191], v[42:45]
	v_mfma_f32_16x16x32_bf16 v[38:41], v[134:137], v[210:213], v[38:41]
	v_mfma_f32_16x16x32_bf16 v[26:29], v[152:155], v[210:213], v[26:29]
	v_mfma_f32_16x16x32_bf16 v[22:25], v[134:137], v[218:221], v[22:25]
	v_mfma_f32_16x16x32_bf16 v[10:13], v[152:155], v[218:221], v[10:13]
	v_mfma_f32_16x16x32_bf16 v[50:53], v[156:159], v[176:179], v[50:53]
	v_mfma_f32_16x16x32_bf16 v[46:49], v[168:171], v[176:179], v[46:49]
	v_mfma_f32_16x16x32_bf16 v[34:37], v[156:159], v[184:187], v[34:37]
	v_mfma_f32_16x16x32_bf16 v[30:33], v[168:171], v[184:187], v[30:33]
	v_mfma_f32_16x16x32_bf16 v[18:21], v[156:159], v[206:209], v[18:21]
	v_mfma_f32_16x16x32_bf16 v[14:17], v[168:171], v[206:209], v[14:17]
	v_mfma_f32_16x16x32_bf16 v[6:9], v[156:159], v[214:217], v[6:9]
	v_mfma_f32_16x16x32_bf16 v[2:5], v[168:171], v[214:217], v[2:5]
	v_mfma_f32_16x16x32_bf16 v[50:53], v[164:167], v[180:183], v[50:53]
	v_mfma_f32_16x16x32_bf16 v[46:49], v[172:175], v[180:183], v[46:49]
	v_mfma_f32_16x16x32_bf16 v[34:37], v[164:167], v[188:191], v[34:37]
	v_mfma_f32_16x16x32_bf16 v[30:33], v[172:175], v[188:191], v[30:33]
	v_mfma_f32_16x16x32_bf16 v[18:21], v[164:167], v[210:213], v[18:21]
	v_mfma_f32_16x16x32_bf16 v[14:17], v[172:175], v[210:213], v[14:17]
	v_mfma_f32_16x16x32_bf16 v[6:9], v[164:167], v[218:221], v[6:9]
	v_mfma_f32_16x16x32_bf16 v[2:5], v[172:175], v[218:221], v[2:5]
	s_setprio 0
	s_barrier
; #define PG8_STAGE(bufoff, gbase, voff) do { _Pragma("unroll") for (int _i = 0; _i < 2; ++_i) \
;         __builtin_amdgcn_global_load_lds((const unsigned*)((const char*)(gbase) + (voff)[_i]), (PG8_LAS unsigned*)(lds + (bufoff) + ldsw + _i * 8192), 16, 0, 0); } while (0)
; #define PG8_LDA(dst, b, h) do { _Pragma("unroll") for (int m = 0; m < 4; ++m) _Pragma("unroll") for (int k = 0; k < 2; ++k) dst[m][k] = *(const PG8_LAS bf16x8*)(lds + PG8_SA(b, h) + aoff + m * 2048 + k * 1024); } while (0)
; #define PG8_LDB(dst, b, h) do { _Pragma("unroll") for (int n = 0; n < 2; ++n) _Pragma("unroll") for (int k = 0; k < 2; ++k) dst[n][k] = *(const PG8_LAS bf16x8*)(lds + PG8_SB(b, h) + boff + n * 2048 + k * 1024); } while (0)
; #define PG8_MMA(ai, bj, At, Bt) do { __builtin_amdgcn_s_setprio(1); _Pragma("unroll") for (int m = 0; m < 4; ++m) _Pragma("unroll") for (int n = 0; n < 2; ++n) _Pragma("unroll") for (int k = 0; k < 2; ++k) \
;         acc[ai][bj][m][n] = __builtin_amdgcn_mfma_f32_16x16x32_bf16(Bt[n][k], At[m][k], acc[ai][bj][m][n], 0, 0, 0); __builtin_amdgcn_s_setprio(0); } while (0)
; #define PG8_WAIT_V(n) asm volatile("s_waitcnt vmcnt(" #n ")" ::: "memory")
; #define PG8_WAIT_L(n) asm volatile("s_waitcnt lgkmcnt(" #n ")" ::: "memory")
; #define PG8_BAR __builtin_amdgcn_s_barrier()
; #define PG8_SCHED __builtin_amdgcn_sched_barrier(0)
; template <class Epi, class Sched, bool ALIGN_EPI = false, bool SP2 = false>
; __device__ __forceinline__ void gemm_phase(PG8_LAS unsigned char* lds, const Gemm g, const Sched& S, const Epi& E) {
;     ...
;             PG8_LDB(B0, 1, 0); PG8_LDB(B1, 1, 1); PG8_SCHED; PG8_LDA(At, 1, 0); PG8_STAGE(PG8_SA(0, 1), a2 + hstepA, voffA);
;             PG8_WAIT_V(8); PG8_WAIT_L(0); PG8_BAR; PG8_MMA(0, 0, At, B0); PG8_MMA(0, 1, At, B1); PG8_BAR; PG8_SCHED;
;             PG8_LDA(At, 1, 1); PG8_STAGE(PG8_SB(1, 0), b3, voffB); PG8_STAGE(PG8_SB(1, 1), b3 + hstepB, voffB); PG8_STAGE(PG8_SA(1, 0), a3, voffA);
;             PG8_WAIT_V(8); PG8_WAIT_L(0); PG8_BAR; PG8_MMA(1, 0, At, B0); PG8_MMA(1, 1, At, B1); PG8_BAR; PG8_SCHED;
	s_add_i32 s47, 0, 0x18000
	s_add_i32 s48, 0, 0x1c000
	v_add_u32_e32 v152, s47, v161
	v_add_u32_e32 v172, s48, v161
	ds_read_b128 v[130:133], v152
	ds_read_b128 v[134:137], v152 offset:1024
	ds_read_b128 v[138:141], v152 offset:2048
	ds_read_b128 v[152:155], v152 offset:3072
	ds_read_b128 v[156:159], v172
	ds_read_b128 v[164:167], v172 offset:1024
	ds_read_b128 v[168:171], v172 offset:2048
	ds_read_b128 v[172:175], v172 offset:3072
	s_add_u32 s28, s28, 0x4000
	s_addc_u32 s29, s29, 0
	s_mov_b32 m0, s35
	ds_read_b128 v[176:179], v163 offset:32768
	ds_read_b128 v[180:183], v163 offset:33792
	ds_read_b128 v[184:187], v163 offset:34816
	ds_read_b128 v[188:191], v163 offset:35840
	ds_read_b128 v[206:209], v163 offset:36864
	ds_read_b128 v[210:213], v163 offset:37888
	ds_read_b128 v[214:217], v163 offset:38912
	ds_read_b128 v[218:221], v163 offset:39936
	global_load_lds_dwordx4 v146, s[28:29]
	v_lshl_add_u64 v[224:225], s[28:29], 0, v[144:145]
	s_mov_b32 m0, s36
	s_nop 0
	global_load_lds_dwordx4 v144, s[28:29]
	s_waitcnt vmcnt(8)
	s_waitcnt lgkmcnt(0)
	s_barrier
	s_setprio 1
	v_mfma_f32_16x16x32_bf16 v[126:129], v[130:133], v[176:179], v[126:129]
	v_mfma_f32_16x16x32_bf16 v[122:125], v[138:141], v[176:179], v[122:125]
	v_mfma_f32_16x16x32_bf16 v[118:121], v[130:133], v[184:187], v[118:121]
	v_mfma_f32_16x16x32_bf16 v[106:109], v[138:141], v[184:187], v[106:109]
	v_mfma_f32_16x16x32_bf16 v[102:105], v[130:133], v[206:209], v[102:105]
	v_mfma_f32_16x16x32_bf16 v[90:93], v[138:141], v[206:209], v[90:93]
	v_mfma_f32_16x16x32_bf16 v[86:89], v[130:133], v[214:217], v[86:89]
	v_mfma_f32_16x16x32_bf16 v[74:77], v[138:141], v[214:217], v[74:77]
	v_mfma_f32_16x16x32_bf16 v[126:129], v[134:137], v[180:183], v[126:129]
	v_mfma_f32_16x16x32_bf16 v[122:125], v[152:155], v[180:183], v[122:125]
	v_mfma_f32_16x16x32_bf16 v[118:121], v[134:137], v[188:191], v[118:121]
	v_mfma_f32_16x16x32_bf16 v[106:109], v[152:155], v[188:191], v[106:109]
	v_mfma_f32_16x16x32_bf16 v[102:105], v[134:137], v[210:213], v[102:105]
	v_mfma_f32_16x16x32_bf16 v[90:93], v[152:155], v[210:213], v[90:93]
	v_mfma_f32_16x16x32_bf16 v[86:89], v[134:137], v[218:221], v[86:89]
	v_mfma_f32_16x16x32_bf16 v[74:77], v[152:155], v[218:221], v[74:77]
	v_mfma_f32_16x16x32_bf16 v[114:117], v[156:159], v[176:179], v[114:117]
	v_mfma_f32_16x16x32_bf16 v[110:113], v[168:171], v[176:179], v[110:113]
	v_mfma_f32_16x16x32_bf16 v[98:101], v[156:159], v[184:187], v[98:101]
	v_mfma_f32_16x16x32_bf16 v[94:97], v[168:171], v[184:187], v[94:97]
	v_mfma_f32_16x16x32_bf16 v[82:85], v[156:159], v[206:209], v[82:85]
	v_mfma_f32_16x16x32_bf16 v[78:81], v[168:171], v[206:209], v[78:81]
	v_mfma_f32_16x16x32_bf16 v[70:73], v[156:159], v[214:217], v[70:73]
	v_mfma_f32_16x16x32_bf16 v[66:69], v[168:171], v[214:217], v[66:69]
	v_mfma_f32_16x16x32_bf16 v[114:117], v[164:167], v[180:183], v[114:117]
	v_mfma_f32_16x16x32_bf16 v[110:113], v[172:175], v[180:183], v[110:113]
	v_mfma_f32_16x16x32_bf16 v[98:101], v[164:167], v[188:191], v[98:101]
	v_mfma_f32_16x16x32_bf16 v[94:97], v[172:175], v[188:191], v[94:97]
	v_mfma_f32_16x16x32_bf16 v[82:85], v[164:167], v[210:213], v[82:85]
	v_mfma_f32_16x16x32_bf16 v[78:81], v[172:175], v[210:213], v[78:81]
	v_mfma_f32_16x16x32_bf16 v[70:73], v[164:167], v[218:221], v[70:73]
	v_mfma_f32_16x16x32_bf16 v[66:69], v[172:175], v[218:221], v[66:69]
	s_setprio 0
	s_barrier
	s_add_i32 s28, s47, s30
	v_lshl_add_u64 v[192:193], v[192:193], 0, s[78:79]
	s_mov_b32 m0, s28
	ds_read_b128 v[176:179], v163 offset:49152
	ds_read_b128 v[180:183], v163 offset:50176
	ds_read_b128 v[184:187], v163 offset:51200
	ds_read_b128 v[188:191], v163 offset:52224
	ds_read_b128 v[206:209], v163 offset:53248
	ds_read_b128 v[210:213], v163 offset:54272
	ds_read_b128 v[214:217], v163 offset:55296
	ds_read_b128 v[218:221], v163 offset:56320
	global_load_lds_dwordx4 v[192:193], off
	s_add_i32 m0, s28, 0x2000
	s_add_u32 s26, s26, 0x40080
	v_lshl_add_u64 v[192:193], v[222:223], 0, s[78:79]
	s_addc_u32 s27, s27, 0
	s_add_i32 s28, s48, s30
	global_load_lds_dwordx4 v[192:193], off
	v_lshl_add_u64 v[192:193], s[26:27], 0, v[0:1]
	s_mov_b32 m0, s28
	s_nop 0
	global_load_lds_dwordx4 v[192:193], off
	s_add_i32 m0, s28, 0x2000
	s_nop 0
	global_load_lds_dwordx4 v142, s[26:27]
	s_mov_b32 m0, s37
	s_nop 0
	global_load_lds_dwordx4 v146, s[24:25]
	s_mov_b32 m0, s38
	s_nop 0
	global_load_lds_dwordx4 v144, s[24:25]
	s_waitcnt vmcnt(8)
	s_waitcnt lgkmcnt(0)
	s_barrier
	s_setprio 1
	v_mfma_f32_16x16x32_bf16 v[62:65], v[130:133], v[176:179], v[62:65]
	v_mfma_f32_16x16x32_bf16 v[58:61], v[138:141], v[176:179], v[58:61]
	v_mfma_f32_16x16x32_bf16 v[54:57], v[130:133], v[184:187], v[54:57]
	v_mfma_f32_16x16x32_bf16 v[42:45], v[138:141], v[184:187], v[42:45]
	v_mfma_f32_16x16x32_bf16 v[38:41], v[130:133], v[206:209], v[38:41]
	v_mfma_f32_16x16x32_bf16 v[26:29], v[138:141], v[206:209], v[26:29]
	v_mfma_f32_16x16x32_bf16 v[22:25], v[130:133], v[214:217], v[22:25]
	v_mfma_f32_16x16x32_bf16 v[10:13], v[138:141], v[214:217], v[10:13]
	v_mfma_f32_16x16x32_bf16 v[62:65], v[134:137], v[180:183], v[62:65]
	v_mfma_f32_16x16x32_bf16 v[58:61], v[152:155], v[180:183], v[58:61]
	v_mfma_f32_16x16x32_bf16 v[54:57], v[134:137], v[188:191], v[54:57]
	v_mfma_f32_16x16x32_bf16 v[42:45], v[152:155], v[188:191], v[42:45]
	v_mfma_f32_16x16x32_bf16 v[38:41], v[134:137], v[210:213], v[38:41]
	v_mfma_f32_16x16x32_bf16 v[26:29], v[152:155], v[210:213], v[26:29]
	v_mfma_f32_16x16x32_bf16 v[22:25], v[134:137], v[218:221], v[22:25]
	v_mfma_f32_16x16x32_bf16 v[10:13], v[152:155], v[218:221], v[10:13]
	v_mfma_f32_16x16x32_bf16 v[50:53], v[156:159], v[176:179], v[50:53]
	v_mfma_f32_16x16x32_bf16 v[46:49], v[168:171], v[176:179], v[46:49]
	v_mfma_f32_16x16x32_bf16 v[34:37], v[156:159], v[184:187], v[34:37]
	v_mfma_f32_16x16x32_bf16 v[30:33], v[168:171], v[184:187], v[30:33]
	v_mfma_f32_16x16x32_bf16 v[18:21], v[156:159], v[206:209], v[18:21]
	v_mfma_f32_16x16x32_bf16 v[14:17], v[168:171], v[206:209], v[14:17]
	v_mfma_f32_16x16x32_bf16 v[6:9], v[156:159], v[214:217], v[6:9]
	v_mfma_f32_16x16x32_bf16 v[2:5], v[168:171], v[214:217], v[2:5]
	v_mfma_f32_16x16x32_bf16 v[50:53], v[164:167], v[180:183], v[50:53]
	v_mfma_f32_16x16x32_bf16 v[46:49], v[172:175], v[180:183], v[46:49]
	v_mfma_f32_16x16x32_bf16 v[34:37], v[164:167], v[188:191], v[34:37]
	v_mfma_f32_16x16x32_bf16 v[30:33], v[172:175], v[188:191], v[30:33]
	v_mfma_f32_16x16x32_bf16 v[18:21], v[164:167], v[210:213], v[18:21]
	v_mfma_f32_16x16x32_bf16 v[14:17], v[172:175], v[210:213], v[14:17]
	v_mfma_f32_16x16x32_bf16 v[6:9], v[164:167], v[218:221], v[6:9]
	v_mfma_f32_16x16x32_bf16 v[2:5], v[172:175], v[218:221], v[2:5]
	s_setprio 0
	s_barrier
	s_add_i32 s46, s46, 2
	s_add_u32 s22, s22, 0x400000
	s_addc_u32 s23, s23, 0
	s_add_u32 s44, s44, 0x100
	s_addc_u32 s45, s45, 0
	s_cmp_gt_u32 s46, 13
	s_cbranch_scc0 .LBB0_87
	s_and_b64 vcc, exec, s[12:13]
	s_cbranch_vccz .LBB0_90
	s_barrier

; #define PG8_STAGE(bufoff, gbase, voff) do { _Pragma("unroll") for (int _i = 0; _i < 2; ++_i) \
;         __builtin_amdgcn_global_load_lds((const unsigned*)((const char*)(gbase) + (voff)[_i]), (PG8_LAS unsigned*)(lds + (bufoff) + ldsw + _i * 8192), 16, 0, 0); } while (0)
; #define PG8_LDA(dst, b, h) do { _Pragma("unroll") for (int m = 0; m < 4; ++m) _Pragma("unroll") for (int k = 0; k < 2; ++k) dst[m][k] = *(const PG8_LAS bf16x8*)(lds + PG8_SA(b, h) + aoff + m * 2048 + k * 1024); } while (0)
; #define PG8_LDB(dst, b, h) do { _Pragma("unroll") for (int n = 0; n < 2; ++n) _Pragma("unroll") for (int k = 0; k < 2; ++k) dst[n][k] = *(const PG8_LAS bf16x8*)(lds + PG8_SB(b, h) + boff + n * 2048 + k * 1024); } while (0)
; #define PG8_MMA(ai, bj, At, Bt) do { __builtin_amdgcn_s_setprio(1); _Pragma("unroll") for (int m = 0; m < 4; ++m) _Pragma("unroll") for (int n = 0; n < 2; ++n) _Pragma("unroll") for (int k = 0; k < 2; ++k) \
;         acc[ai][bj][m][n] = __builtin_amdgcn_mfma_f32_16x16x32_bf16(Bt[n][k], At[m][k], acc[ai][bj][m][n], 0, 0, 0); __builtin_amdgcn_s_setprio(0); } while (0)
; #define PG8_BAR __builtin_amdgcn_s_barrier()
; template <class Epi, class Sched, bool ALIGN_EPI = false, bool SP2 = false>
; __device__ __forceinline__ void gemm_phase(PG8_LAS unsigned char* lds, const Gemm g, const Sched& S, const Epi& E) {
;     ...
;         const char* nA = has_next ? (const char*)g.A + (size_t)nxt.pm * tstepA + (size_t)nxt.pn * pnoffA : cA; const char* nB = has_next ? (const char*)g.Bt + (size_t)nxt.pn * tstepB : cB;
;         for (int t = 0; t < nt; t += 2) {
;             const bool last = (t == nt - 2);
;             const char* a1 = cA + (size_t)(t + 1) * kstepA;
;             const char* a2 = last ? nA : cA + (size_t)(t + 2) * kstepA; const char* b2 = last ? nB : cB + (size_t)(t + 2) * kstep;
;             const char* a3 = a2 + kstepA; const char* b3 = b2 + kstep;
;             if (last && has_next) S.a_ready(nxt);
;             if constexpr (SP2) {
;             PG8_LDB(B0, 0, 0); PG8_LDB(B1, 0, 1); PG8_SCHED; PG8_LDA(At, 0, 0); PG8_STAGE(PG8_SA(1, 1), a1 + hstepA, voffA);
;             PG8_WAIT_V(8); PG8_WAIT_L(0); PG8_BAR; PG8_MMA(0, 0, At, B0); PG8_MMA(0, 1, At, B1); PG8_BAR; PG8_SCHED;
;             PG8_LDA(At, 0, 1); PG8_STAGE(PG8_SB(0, 0), b2, voffB); PG8_STAGE(PG8_SB(0, 1), b2 + hstepB, voffB); PG8_STAGE(PG8_SA(0, 0), a2, voffA);
.LBB0_332:
	s_ashr_i32 s13, s12, 31
	s_lshl_b64 s[14:15], s[12:13], 15
	s_add_u32 s14, s72, s14
	s_addc_u32 s15, s73, s15
	s_and_b64 s[16:17], s[4:5], exec
	s_cselect_b32 s13, s15, s7
	s_cselect_b32 s36, s14, s6
	s_ashr_i32 s11, s10, 31
	s_lshl_b64 s[16:17], s[10:11], 19
	v_readlane_b32 s20, v254, 7
	v_readlane_b32 s21, v254, 8
	s_add_u32 s16, s20, s16
	s_addc_u32 s17, s21, s17
	s_and_b64 s[20:21], s[4:5], exec
	s_cselect_b32 s11, s17, s19
	s_cselect_b32 s37, s16, s18
	s_add_u32 s38, s18, 0x100
	s_addc_u32 s39, s19, 0
	s_add_u32 s6, s6, 0x204000
	s_addc_u32 s7, s7, 0
	s_mov_b32 s40, -2
	s_add_u32 s18, s6, 0x1fc000
	s_addc_u32 s19, s7, 0
	s_cmp_eq_u32 s40, 12
	s_cselect_b32 s22, s36, s18
	s_cselect_b32 s23, s13, s19
	s_cselect_b32 s20, s37, s38
	s_cselect_b32 s21, s11, s39
	s_add_u32 s18, s22, 0x200000
	s_addc_u32 s19, s23, 0
	s_add_i32 s41, 0, 0x10000
	v_add_u32_e32 v0, s41, v149
	s_add_i32 s44, 0, 0x14000
	ds_read_b128 v[142:145], v0
	ds_read_b128 v[152:155], v0 offset:1024
	ds_read_b128 v[156:159], v0 offset:2048
	ds_read_b128 v[160:163], v0 offset:3072
	v_add_u32_e32 v0, s44, v149
	ds_read_b128 v[164:167], v0
	ds_read_b128 v[168:171], v0 offset:1024
	ds_read_b128 v[172:175], v0 offset:2048
	ds_read_b128 v[176:179], v0 offset:3072
	s_add_i32 m0, s25, 0xc000
	ds_read_b128 v[180:183], v151
	ds_read_b128 v[184:187], v151 offset:1024
	ds_read_b128 v[188:191], v151 offset:2048
	ds_read_b128 v[206:209], v151 offset:3072
	ds_read_b128 v[210:213], v151 offset:4096
	ds_read_b128 v[214:217], v151 offset:5120
	ds_read_b128 v[218:221], v151 offset:6144
	ds_read_b128 v[222:225], v151 offset:7168
	global_load_lds_dwordx4 v138, s[6:7]
	s_add_i32 m0, s25, 0xe000
	s_nop 0
	global_load_lds_dwordx4 v140, s[6:7]
	s_waitcnt vmcnt(8)
	s_waitcnt lgkmcnt(0)
	s_barrier
	s_setprio 1
	v_mfma_f32_16x16x32_bf16 v[126:129], v[142:145], v[180:183], 0
	v_mfma_f32_16x16x32_bf16 v[122:125], v[156:159], v[180:183], 0
	v_mfma_f32_16x16x32_bf16 v[110:113], v[142:145], v[188:191], 0
	v_mfma_f32_16x16x32_bf16 v[106:109], v[156:159], v[188:191], 0
	v_mfma_f32_16x16x32_bf16 v[94:97], v[142:145], v[210:213], 0
	v_mfma_f32_16x16x32_bf16 v[90:93], v[156:159], v[210:213], 0
	v_mfma_f32_16x16x32_bf16 v[78:81], v[142:145], v[218:221], 0
	v_mfma_f32_16x16x32_bf16 v[74:77], v[156:159], v[218:221], 0
	v_mfma_f32_16x16x32_bf16 v[126:129], v[152:155], v[184:187], v[126:129]
	v_mfma_f32_16x16x32_bf16 v[122:125], v[160:163], v[184:187], v[122:125]
	v_mfma_f32_16x16x32_bf16 v[110:113], v[152:155], v[206:209], v[110:113]
	v_mfma_f32_16x16x32_bf16 v[106:109], v[160:163], v[206:209], v[106:109]
	v_mfma_f32_16x16x32_bf16 v[94:97], v[152:155], v[214:217], v[94:97]
	v_mfma_f32_16x16x32_bf16 v[90:93], v[160:163], v[214:217], v[90:93]
	v_mfma_f32_16x16x32_bf16 v[78:81], v[152:155], v[222:225], v[78:81]
	v_mfma_f32_16x16x32_bf16 v[74:77], v[160:163], v[222:225], v[74:77]
	v_mfma_f32_16x16x32_bf16 v[118:121], v[164:167], v[180:183], 0
	v_mfma_f32_16x16x32_bf16 v[114:117], v[172:175], v[180:183], 0
	v_mfma_f32_16x16x32_bf16 v[102:105], v[164:167], v[188:191], 0
	v_mfma_f32_16x16x32_bf16 v[98:101], v[172:175], v[188:191], 0
	v_mfma_f32_16x16x32_bf16 v[86:89], v[164:167], v[210:213], 0
	v_mfma_f32_16x16x32_bf16 v[82:85], v[172:175], v[210:213], 0
	v_mfma_f32_16x16x32_bf16 v[70:73], v[164:167], v[218:221], 0
	v_mfma_f32_16x16x32_bf16 v[66:69], v[172:175], v[218:221], 0
	v_mfma_f32_16x16x32_bf16 v[118:121], v[168:171], v[184:187], v[118:121]
	v_mfma_f32_16x16x32_bf16 v[114:117], v[176:179], v[184:187], v[114:117]
	v_mfma_f32_16x16x32_bf16 v[102:105], v[168:171], v[206:209], v[102:105]
	v_mfma_f32_16x16x32_bf16 v[98:101], v[176:179], v[206:209], v[98:101]
	v_mfma_f32_16x16x32_bf16 v[86:89], v[168:171], v[214:217], v[86:89]
	v_mfma_f32_16x16x32_bf16 v[82:85], v[176:179], v[214:217], v[82:85]
	v_mfma_f32_16x16x32_bf16 v[70:73], v[168:171], v[222:225], v[70:73]
	v_mfma_f32_16x16x32_bf16 v[66:69], v[176:179], v[222:225], v[66:69]
	s_setprio 0
	s_barrier
	s_add_i32 s41, s41, s24
	v_lshl_add_u64 v[146:147], s[20:21], 0, v[134:135]
	s_mov_b32 m0, s41
	ds_read_b128 v[180:183], v151 offset:16384
	ds_read_b128 v[184:187], v151 offset:17408
	ds_read_b128 v[188:191], v151 offset:18432
	ds_read_b128 v[206:209], v151 offset:19456
	ds_read_b128 v[210:213], v151 offset:20480
	ds_read_b128 v[214:217], v151 offset:21504
	ds_read_b128 v[218:221], v151 offset:22528
	ds_read_b128 v[222:225], v151 offset:23552
	global_load_lds_dwordx4 v134, s[20:21]
	s_add_i32 m0, s41, 0x2000
	s_add_u32 s42, s20, 0x40000
	v_lshl_add_u64 v[192:193], s[20:21], 0, v[130:131]
	s_addc_u32 s43, s21, 0
	s_add_i32 s41, s44, s24
	global_load_lds_dwordx4 v130, s[20:21]
	s_mov_b32 m0, s41
	s_nop 0
	global_load_lds_dwordx4 v134, s[42:43]
	s_add_i32 m0, s41, 0x2000
	s_nop 0
	global_load_lds_dwordx4 v130, s[42:43]
	s_mov_b32 m0, s25
	s_nop 0
	global_load_lds_dwordx4 v136, s[22:23]
	s_mov_b32 m0, s26
	s_nop 0
	global_load_lds_dwordx4 v132, s[22:23]
	s_waitcnt vmcnt(8)
	s_waitcnt lgkmcnt(0)
	s_barrier
; #define PG8_STAGE(bufoff, gbase, voff) do { _Pragma("unroll") for (int _i = 0; _i < 2; ++_i) \
;         __builtin_amdgcn_global_load_lds((const unsigned*)((const char*)(gbase) + (voff)[_i]), (PG8_LAS unsigned*)(lds + (bufoff) + ldsw + _i * 8192), 16, 0, 0); } while (0)
; #define PG8_LDA(dst, b, h) do { _Pragma("unroll") for (int m = 0; m < 4; ++m) _Pragma("unroll") for (int k = 0; k < 2; ++k) dst[m][k] = *(const PG8_LAS bf16x8*)(lds + PG8_SA(b, h) + aoff + m * 2048 + k * 1024); } while (0)
; #define PG8_LDB(dst, b, h) do { _Pragma("unroll") for (int n = 0; n < 2; ++n) _Pragma("unroll") for (int k = 0; k < 2; ++k) dst[n][k] = *(const PG8_LAS bf16x8*)(lds + PG8_SB(b, h) + boff + n * 2048 + k * 1024); } while (0)
; #define PG8_MMA(ai, bj, At, Bt) do { __builtin_amdgcn_s_setprio(1); _Pragma("unroll") for (int m = 0; m < 4; ++m) _Pragma("unroll") for (int n = 0; n < 2; ++n) _Pragma("unroll") for (int k = 0; k < 2; ++k) \
;         acc[ai][bj][m][n] = __builtin_amdgcn_mfma_f32_16x16x32_bf16(Bt[n][k], At[m][k], acc[ai][bj][m][n], 0, 0, 0); __builtin_amdgcn_s_setprio(0); } while (0)
; #define PG8_WAIT_V(n) asm volatile("s_waitcnt vmcnt(" #n ")" ::: "memory")
; #define PG8_WAIT_L(n) asm volatile("s_waitcnt lgkmcnt(" #n ")" ::: "memory")
; #define PG8_BAR __builtin_amdgcn_s_barrier()
; #define PG8_SCHED __builtin_amdgcn_sched_barrier(0)
; template <class Epi, class Sched, bool ALIGN_EPI = false, bool SP2 = false>
; __device__ __forceinline__ void gemm_phase(PG8_LAS unsigned char* lds, const Gemm g, const Sched& S, const Epi& E) {
;     ...
;             PG8_WAIT_V(8); PG8_WAIT_L(0); PG8_BAR; PG8_MMA(1, 0, At, B0); PG8_MMA(1, 1, At, B1); PG8_BAR; PG8_SCHED;
;             PG8_LDB(B0, 1, 0); PG8_LDB(B1, 1, 1); PG8_SCHED; PG8_LDA(At, 1, 0); PG8_STAGE(PG8_SA(0, 1), a2 + hstepA, voffA);
;             PG8_WAIT_V(8); PG8_WAIT_L(0); PG8_BAR; PG8_MMA(0, 0, At, B0); PG8_MMA(0, 1, At, B1); PG8_BAR; PG8_SCHED;
	s_setprio 1
	v_mfma_f32_16x16x32_bf16 v[62:65], v[142:145], v[180:183], 0
	v_mfma_f32_16x16x32_bf16 v[58:61], v[156:159], v[180:183], 0
	v_mfma_f32_16x16x32_bf16 v[46:49], v[142:145], v[188:191], 0
	v_mfma_f32_16x16x32_bf16 v[42:45], v[156:159], v[188:191], 0
	v_mfma_f32_16x16x32_bf16 v[30:33], v[142:145], v[210:213], 0
	v_mfma_f32_16x16x32_bf16 v[26:29], v[156:159], v[210:213], 0
	v_mfma_f32_16x16x32_bf16 v[14:17], v[142:145], v[218:221], 0
	v_mfma_f32_16x16x32_bf16 v[10:13], v[156:159], v[218:221], 0
	v_mfma_f32_16x16x32_bf16 v[62:65], v[152:155], v[184:187], v[62:65]
	v_mfma_f32_16x16x32_bf16 v[58:61], v[160:163], v[184:187], v[58:61]
	v_mfma_f32_16x16x32_bf16 v[46:49], v[152:155], v[206:209], v[46:49]
	v_mfma_f32_16x16x32_bf16 v[42:45], v[160:163], v[206:209], v[42:45]
	v_mfma_f32_16x16x32_bf16 v[30:33], v[152:155], v[214:217], v[30:33]
	v_mfma_f32_16x16x32_bf16 v[26:29], v[160:163], v[214:217], v[26:29]
	v_mfma_f32_16x16x32_bf16 v[14:17], v[152:155], v[222:225], v[14:17]
	v_mfma_f32_16x16x32_bf16 v[10:13], v[160:163], v[222:225], v[10:13]
	v_mfma_f32_16x16x32_bf16 v[54:57], v[164:167], v[180:183], 0
	v_mfma_f32_16x16x32_bf16 v[50:53], v[172:175], v[180:183], 0
	v_mfma_f32_16x16x32_bf16 v[38:41], v[164:167], v[188:191], 0
	v_mfma_f32_16x16x32_bf16 v[34:37], v[172:175], v[188:191], 0
	v_mfma_f32_16x16x32_bf16 v[22:25], v[164:167], v[210:213], 0
	v_mfma_f32_16x16x32_bf16 v[18:21], v[172:175], v[210:213], 0
	v_mfma_f32_16x16x32_bf16 v[6:9], v[164:167], v[218:221], 0
	v_mfma_f32_16x16x32_bf16 v[2:5], v[172:175], v[218:221], 0
	v_mfma_f32_16x16x32_bf16 v[54:57], v[168:171], v[184:187], v[54:57]
	v_mfma_f32_16x16x32_bf16 v[50:53], v[176:179], v[184:187], v[50:53]
	v_mfma_f32_16x16x32_bf16 v[38:41], v[168:171], v[206:209], v[38:41]
	v_mfma_f32_16x16x32_bf16 v[34:37], v[176:179], v[206:209], v[34:37]
	v_mfma_f32_16x16x32_bf16 v[22:25], v[168:171], v[214:217], v[22:25]
	v_mfma_f32_16x16x32_bf16 v[18:21], v[176:179], v[214:217], v[18:21]
	v_mfma_f32_16x16x32_bf16 v[6:9], v[168:171], v[222:225], v[6:9]
	v_mfma_f32_16x16x32_bf16 v[2:5], v[176:179], v[222:225], v[2:5]
	s_setprio 0
	s_barrier
	s_add_i32 s41, 0, 0x18000
	v_add_u32_e32 v0, s41, v149
	s_add_i32 s42, 0, 0x1c000
	ds_read_b128 v[142:145], v0
	ds_read_b128 v[152:155], v0 offset:1024
	ds_read_b128 v[156:159], v0 offset:2048
	ds_read_b128 v[160:163], v0 offset:3072
	v_add_u32_e32 v0, s42, v149
	ds_read_b128 v[164:167], v0
	ds_read_b128 v[168:171], v0 offset:1024
	ds_read_b128 v[172:175], v0 offset:2048
	ds_read_b128 v[176:179], v0 offset:3072
	s_add_u32 s22, s22, 0x4000
	s_addc_u32 s23, s23, 0
	s_mov_b32 m0, s27
	ds_read_b128 v[180:183], v151 offset:32768
	ds_read_b128 v[184:187], v151 offset:33792
	ds_read_b128 v[188:191], v151 offset:34816
	ds_read_b128 v[206:209], v151 offset:35840
	ds_read_b128 v[210:213], v151 offset:36864
	ds_read_b128 v[214:217], v151 offset:37888
	ds_read_b128 v[218:221], v151 offset:38912
	ds_read_b128 v[222:225], v151 offset:39936
	global_load_lds_dwordx4 v136, s[22:23]
	s_mov_b32 m0, s28
	s_nop 0
	global_load_lds_dwordx4 v132, s[22:23]
	s_waitcnt vmcnt(8)
	s_waitcnt lgkmcnt(0)
	s_barrier
	s_setprio 1
	v_mfma_f32_16x16x32_bf16 v[126:129], v[142:145], v[180:183], v[126:129]
	v_mfma_f32_16x16x32_bf16 v[122:125], v[156:159], v[180:183], v[122:125]
	v_mfma_f32_16x16x32_bf16 v[110:113], v[142:145], v[188:191], v[110:113]
	v_mfma_f32_16x16x32_bf16 v[106:109], v[156:159], v[188:191], v[106:109]
	v_mfma_f32_16x16x32_bf16 v[94:97], v[142:145], v[210:213], v[94:97]
	v_mfma_f32_16x16x32_bf16 v[90:93], v[156:159], v[210:213], v[90:93]
	v_mfma_f32_16x16x32_bf16 v[78:81], v[142:145], v[218:221], v[78:81]
	v_mfma_f32_16x16x32_bf16 v[74:77], v[156:159], v[218:221], v[74:77]
	v_mfma_f32_16x16x32_bf16 v[126:129], v[152:155], v[184:187], v[126:129]
	v_mfma_f32_16x16x32_bf16 v[122:125], v[160:163], v[184:187], v[122:125]
	v_mfma_f32_16x16x32_bf16 v[110:113], v[152:155], v[206:209], v[110:113]
	v_mfma_f32_16x16x32_bf16 v[106:109], v[160:163], v[206:209], v[106:109]
	v_mfma_f32_16x16x32_bf16 v[94:97], v[152:155], v[214:217], v[94:97]
	v_mfma_f32_16x16x32_bf16 v[90:93], v[160:163], v[214:217], v[90:93]
	v_mfma_f32_16x16x32_bf16 v[78:81], v[152:155], v[222:225], v[78:81]
	v_mfma_f32_16x16x32_bf16 v[74:77], v[160:163], v[222:225], v[74:77]
	v_mfma_f32_16x16x32_bf16 v[118:121], v[164:167], v[180:183], v[118:121]
	v_mfma_f32_16x16x32_bf16 v[114:117], v[172:175], v[180:183], v[114:117]
	v_mfma_f32_16x16x32_bf16 v[102:105], v[164:167], v[188:191], v[102:105]
	v_mfma_f32_16x16x32_bf16 v[98:101], v[172:175], v[188:191], v[98:101]
	v_mfma_f32_16x16x32_bf16 v[86:89], v[164:167], v[210:213], v[86:89]
	v_mfma_f32_16x16x32_bf16 v[82:85], v[172:175], v[210:213], v[82:85]
	v_mfma_f32_16x16x32_bf16 v[70:73], v[164:167], v[218:221], v[70:73]
	v_mfma_f32_16x16x32_bf16 v[66:69], v[172:175], v[218:221], v[66:69]
	v_mfma_f32_16x16x32_bf16 v[118:121], v[168:171], v[184:187], v[118:121]
	v_mfma_f32_16x16x32_bf16 v[114:117], v[176:179], v[184:187], v[114:117]
	v_mfma_f32_16x16x32_bf16 v[102:105], v[168:171], v[206:209], v[102:105]
	v_mfma_f32_16x16x32_bf16 v[98:101], v[176:179], v[206:209], v[98:101]
	v_mfma_f32_16x16x32_bf16 v[86:89], v[168:171], v[214:217], v[86:89]
	v_mfma_f32_16x16x32_bf16 v[82:85], v[176:179], v[214:217], v[82:85]
	v_mfma_f32_16x16x32_bf16 v[70:73], v[168:171], v[222:225], v[70:73]
	v_mfma_f32_16x16x32_bf16 v[66:69], v[176:179], v[222:225], v[66:69]
	s_setprio 0
	s_barrier
; #define PG8_STAGE(bufoff, gbase, voff) do { _Pragma("unroll") for (int _i = 0; _i < 2; ++_i) \
;         __builtin_amdgcn_global_load_lds((const unsigned*)((const char*)(gbase) + (voff)[_i]), (PG8_LAS unsigned*)(lds + (bufoff) + ldsw + _i * 8192), 16, 0, 0); } while (0)
; #define PG8_LDA(dst, b, h) do { _Pragma("unroll") for (int m = 0; m < 4; ++m) _Pragma("unroll") for (int k = 0; k < 2; ++k) dst[m][k] = *(const PG8_LAS bf16x8*)(lds + PG8_SA(b, h) + aoff + m * 2048 + k * 1024); } while (0)
; #define PG8_LDB(dst, b, h) do { _Pragma("unroll") for (int n = 0; n < 2; ++n) _Pragma("unroll") for (int k = 0; k < 2; ++k) dst[n][k] = *(const PG8_LAS bf16x8*)(lds + PG8_SB(b, h) + boff + n * 2048 + k * 1024); } while (0)
; #define PG8_MMA(ai, bj, At, Bt) do { __builtin_amdgcn_s_setprio(1); _Pragma("unroll") for (int m = 0; m < 4; ++m) _Pragma("unroll") for (int n = 0; n < 2; ++n) _Pragma("unroll") for (int k = 0; k < 2; ++k) \
;         acc[ai][bj][m][n] = __builtin_amdgcn_mfma_f32_16x16x32_bf16(Bt[n][k], At[m][k], acc[ai][bj][m][n], 0, 0, 0); __builtin_amdgcn_s_setprio(0); } while (0)
; #define PG8_WAIT_V(n) asm volatile("s_waitcnt vmcnt(" #n ")" ::: "memory")
; #define PG8_BAR __builtin_amdgcn_s_barrier()
; template <class Epi, class Sched, bool ALIGN_EPI = false, bool SP2 = false>
; __device__ __forceinline__ void gemm_phase(PG8_LAS unsigned char* lds, const Gemm g, const Sched& S, const Epi& E) {
;     ...
;         for (int t = 0; t < nt; t += 2) {
;             const bool last = (t == nt - 2);
;             const char* a1 = cA + (size_t)(t + 1) * kstepA;
;             const char* a2 = last ? nA : cA + (size_t)(t + 2) * kstepA; const char* b2 = last ? nB : cB + (size_t)(t + 2) * kstep;
;             const char* a3 = a2 + kstepA; const char* b3 = b2 + kstep;
;             if (last && has_next) S.a_ready(nxt);
;             if constexpr (SP2) {
;             PG8_LDB(B0, 0, 0); PG8_LDB(B1, 0, 1); PG8_SCHED; PG8_LDA(At, 0, 0); PG8_STAGE(PG8_SA(1, 1), a1 + hstepA, voffA);
;             PG8_WAIT_V(8); PG8_WAIT_L(0); PG8_BAR; PG8_MMA(0, 0, At, B0); PG8_MMA(0, 1, At, B1); PG8_BAR; PG8_SCHED;
;     ...
;             PG8_LDA(At, 1, 1); PG8_STAGE(PG8_SB(1, 0), b3, voffB); PG8_STAGE(PG8_SB(1, 1), b3 + hstepB, voffB); PG8_STAGE(PG8_SA(1, 0), a3, voffA);
;             PG8_WAIT_V(8); PG8_WAIT_L(0); PG8_BAR; PG8_MMA(1, 0, At, B0); PG8_MMA(1, 1, At, B1); PG8_BAR; PG8_SCHED;
	s_add_i32 s22, s41, s24
	v_lshl_add_u64 v[146:147], v[146:147], 0, s[78:79]
	s_mov_b32 m0, s22
	ds_read_b128 v[180:183], v151 offset:49152
	ds_read_b128 v[184:187], v151 offset:50176
	ds_read_b128 v[188:191], v151 offset:51200
	ds_read_b128 v[206:209], v151 offset:52224
	ds_read_b128 v[210:213], v151 offset:53248
	ds_read_b128 v[214:217], v151 offset:54272
	ds_read_b128 v[218:221], v151 offset:55296
	ds_read_b128 v[222:225], v151 offset:56320
	global_load_lds_dwordx4 v[146:147], off
	s_add_i32 m0, s22, 0x2000
	s_add_u32 s20, s20, 0x40080
	v_lshl_add_u64 v[146:147], v[192:193], 0, s[78:79]
	s_addc_u32 s21, s21, 0
	s_add_i32 s22, s42, s24
	global_load_lds_dwordx4 v[146:147], off
	s_mov_b32 m0, s22
	s_nop 0
	global_load_lds_dwordx4 v134, s[20:21]
	s_add_i32 m0, s22, 0x2000
	s_nop 0
	global_load_lds_dwordx4 v130, s[20:21]
	s_mov_b32 m0, s29
	s_nop 0
	global_load_lds_dwordx4 v136, s[18:19]
	s_mov_b32 m0, s30
	s_nop 0
	global_load_lds_dwordx4 v132, s[18:19]
	s_waitcnt vmcnt(8)
	s_waitcnt lgkmcnt(0)
	s_barrier
	s_setprio 1
	v_mfma_f32_16x16x32_bf16 v[62:65], v[142:145], v[180:183], v[62:65]
	v_mfma_f32_16x16x32_bf16 v[58:61], v[156:159], v[180:183], v[58:61]
	v_mfma_f32_16x16x32_bf16 v[46:49], v[142:145], v[188:191], v[46:49]
	v_mfma_f32_16x16x32_bf16 v[42:45], v[156:159], v[188:191], v[42:45]
	v_mfma_f32_16x16x32_bf16 v[30:33], v[142:145], v[210:213], v[30:33]
	v_mfma_f32_16x16x32_bf16 v[26:29], v[156:159], v[210:213], v[26:29]
	v_mfma_f32_16x16x32_bf16 v[14:17], v[142:145], v[218:221], v[14:17]
	v_mfma_f32_16x16x32_bf16 v[10:13], v[156:159], v[218:221], v[10:13]
	v_mfma_f32_16x16x32_bf16 v[62:65], v[152:155], v[184:187], v[62:65]
	v_mfma_f32_16x16x32_bf16 v[58:61], v[160:163], v[184:187], v[58:61]
	v_mfma_f32_16x16x32_bf16 v[46:49], v[152:155], v[206:209], v[46:49]
	v_mfma_f32_16x16x32_bf16 v[42:45], v[160:163], v[206:209], v[42:45]
	v_mfma_f32_16x16x32_bf16 v[30:33], v[152:155], v[214:217], v[30:33]
	v_mfma_f32_16x16x32_bf16 v[26:29], v[160:163], v[214:217], v[26:29]
	v_mfma_f32_16x16x32_bf16 v[14:17], v[152:155], v[222:225], v[14:17]
	v_mfma_f32_16x16x32_bf16 v[10:13], v[160:163], v[222:225], v[10:13]
	v_mfma_f32_16x16x32_bf16 v[54:57], v[164:167], v[180:183], v[54:57]
	v_mfma_f32_16x16x32_bf16 v[50:53], v[172:175], v[180:183], v[50:53]
	v_mfma_f32_16x16x32_bf16 v[38:41], v[164:167], v[188:191], v[38:41]
	v_mfma_f32_16x16x32_bf16 v[34:37], v[172:175], v[188:191], v[34:37]
	v_mfma_f32_16x16x32_bf16 v[22:25], v[164:167], v[210:213], v[22:25]
	v_mfma_f32_16x16x32_bf16 v[18:21], v[172:175], v[210:213], v[18:21]
	v_mfma_f32_16x16x32_bf16 v[6:9], v[164:167], v[218:221], v[6:9]
	v_mfma_f32_16x16x32_bf16 v[2:5], v[172:175], v[218:221], v[2:5]
	v_mfma_f32_16x16x32_bf16 v[54:57], v[168:171], v[184:187], v[54:57]
	v_mfma_f32_16x16x32_bf16 v[50:53], v[176:179], v[184:187], v[50:53]
	v_mfma_f32_16x16x32_bf16 v[38:41], v[168:171], v[206:209], v[38:41]
	v_mfma_f32_16x16x32_bf16 v[34:37], v[176:179], v[206:209], v[34:37]
	v_mfma_f32_16x16x32_bf16 v[22:25], v[168:171], v[214:217], v[22:25]
	v_mfma_f32_16x16x32_bf16 v[18:21], v[176:179], v[214:217], v[18:21]
	v_mfma_f32_16x16x32_bf16 v[6:9], v[168:171], v[222:225], v[6:9]
	v_mfma_f32_16x16x32_bf16 v[2:5], v[176:179], v[222:225], v[2:5]
	s_setprio 0
	s_barrier
	s_add_i32 s40, s40, 2
	s_add_u32 s38, s38, 0x100
	s_addc_u32 s39, s39, 0
	s_add_u32 s6, s6, 0x400000
	s_addc_u32 s7, s7, 0
.LBB0_333:
	s_add_u32 s18, s6, 0x1fc000
	s_addc_u32 s19, s7, 0
	s_cmp_eq_u32 s40, 12
	s_cselect_b32 s22, s36, s18
	s_cselect_b32 s23, s13, s19
	s_cselect_b32 s20, s37, s38
	s_cselect_b32 s21, s11, s39
	s_add_u32 s18, s22, 0x200000
	s_addc_u32 s19, s23, 0
	s_add_i32 s41, 0, 0x10000
	v_add_u32_e32 v0, s41, v149
	s_add_i32 s44, 0, 0x14000
	ds_read_b128 v[142:145], v0
	ds_read_b128 v[152:155], v0 offset:1024
	ds_read_b128 v[156:159], v0 offset:2048
	ds_read_b128 v[160:163], v0 offset:3072
	v_add_u32_e32 v0, s44, v149
	ds_read_b128 v[164:167], v0
	ds_read_b128 v[168:171], v0 offset:1024
	ds_read_b128 v[172:175], v0 offset:2048
	ds_read_b128 v[176:179], v0 offset:3072
	s_add_i32 m0, s25, 0xc000
	ds_read_b128 v[180:183], v151
	ds_read_b128 v[184:187], v151 offset:1024
	ds_read_b128 v[188:191], v151 offset:2048
	ds_read_b128 v[206:209], v151 offset:3072
	ds_read_b128 v[210:213], v151 offset:4096
	ds_read_b128 v[214:217], v151 offset:5120
	ds_read_b128 v[218:221], v151 offset:6144
	ds_read_b128 v[222:225], v151 offset:7168
	global_load_lds_dwordx4 v138, s[6:7]
	s_add_i32 m0, s25, 0xe000
	s_nop 0
	global_load_lds_dwordx4 v140, s[6:7]
	s_waitcnt vmcnt(8)
	s_waitcnt lgkmcnt(0)
	s_barrier
; #define PG8_STAGE(bufoff, gbase, voff) do { _Pragma("unroll") for (int _i = 0; _i < 2; ++_i) \
;         __builtin_amdgcn_global_load_lds((const unsigned*)((const char*)(gbase) + (voff)[_i]), (PG8_LAS unsigned*)(lds + (bufoff) + ldsw + _i * 8192), 16, 0, 0); } while (0)
; #define PG8_LDA(dst, b, h) do { _Pragma("unroll") for (int m = 0; m < 4; ++m) _Pragma("unroll") for (int k = 0; k < 2; ++k) dst[m][k] = *(const PG8_LAS bf16x8*)(lds + PG8_SA(b, h) + aoff + m * 2048 + k * 1024); } while (0)
; #define PG8_MMA(ai, bj, At, Bt) do { __builtin_amdgcn_s_setprio(1); _Pragma("unroll") for (int m = 0; m < 4; ++m) _Pragma("unroll") for (int n = 0; n < 2; ++n) _Pragma("unroll") for (int k = 0; k < 2; ++k) \
;         acc[ai][bj][m][n] = __builtin_amdgcn_mfma_f32_16x16x32_bf16(Bt[n][k], At[m][k], acc[ai][bj][m][n], 0, 0, 0); __builtin_amdgcn_s_setprio(0); } while (0)
; #define PG8_WAIT_V(n) asm volatile("s_waitcnt vmcnt(" #n ")" ::: "memory")
; #define PG8_WAIT_L(n) asm volatile("s_waitcnt lgkmcnt(" #n ")" ::: "memory")
; #define PG8_BAR __builtin_amdgcn_s_barrier()
; #define PG8_SCHED __builtin_amdgcn_sched_barrier(0)
; template <class Epi, class Sched, bool ALIGN_EPI = false, bool SP2 = false>
; __device__ __forceinline__ void gemm_phase(PG8_LAS unsigned char* lds, const Gemm g, const Sched& S, const Epi& E) {
;     ...
;             PG8_WAIT_V(8); PG8_WAIT_L(0); PG8_BAR; PG8_MMA(0, 0, At, B0); PG8_MMA(0, 1, At, B1); PG8_BAR; PG8_SCHED;
;             PG8_LDA(At, 0, 1); PG8_STAGE(PG8_SB(0, 0), b2, voffB); PG8_STAGE(PG8_SB(0, 1), b2 + hstepB, voffB); PG8_STAGE(PG8_SA(0, 0), a2, voffA);
;             PG8_WAIT_V(8); PG8_WAIT_L(0); PG8_BAR; PG8_MMA(1, 0, At, B0); PG8_MMA(1, 1, At, B1); PG8_BAR; PG8_SCHED;
	s_setprio 1
	v_mfma_f32_16x16x32_bf16 v[126:129], v[142:145], v[180:183], v[126:129]
	v_mfma_f32_16x16x32_bf16 v[122:125], v[156:159], v[180:183], v[122:125]
	v_mfma_f32_16x16x32_bf16 v[110:113], v[142:145], v[188:191], v[110:113]
	v_mfma_f32_16x16x32_bf16 v[106:109], v[156:159], v[188:191], v[106:109]
	v_mfma_f32_16x16x32_bf16 v[94:97], v[142:145], v[210:213], v[94:97]
	v_mfma_f32_16x16x32_bf16 v[90:93], v[156:159], v[210:213], v[90:93]
	v_mfma_f32_16x16x32_bf16 v[78:81], v[142:145], v[218:221], v[78:81]
	v_mfma_f32_16x16x32_bf16 v[74:77], v[156:159], v[218:221], v[74:77]
	v_mfma_f32_16x16x32_bf16 v[126:129], v[152:155], v[184:187], v[126:129]
	v_mfma_f32_16x16x32_bf16 v[122:125], v[160:163], v[184:187], v[122:125]
	v_mfma_f32_16x16x32_bf16 v[110:113], v[152:155], v[206:209], v[110:113]
	v_mfma_f32_16x16x32_bf16 v[106:109], v[160:163], v[206:209], v[106:109]
	v_mfma_f32_16x16x32_bf16 v[94:97], v[152:155], v[214:217], v[94:97]
	v_mfma_f32_16x16x32_bf16 v[90:93], v[160:163], v[214:217], v[90:93]
	v_mfma_f32_16x16x32_bf16 v[78:81], v[152:155], v[222:225], v[78:81]
	v_mfma_f32_16x16x32_bf16 v[74:77], v[160:163], v[222:225], v[74:77]
	v_mfma_f32_16x16x32_bf16 v[118:121], v[164:167], v[180:183], v[118:121]
	v_mfma_f32_16x16x32_bf16 v[114:117], v[172:175], v[180:183], v[114:117]
	v_mfma_f32_16x16x32_bf16 v[102:105], v[164:167], v[188:191], v[102:105]
	v_mfma_f32_16x16x32_bf16 v[98:101], v[172:175], v[188:191], v[98:101]
	v_mfma_f32_16x16x32_bf16 v[86:89], v[164:167], v[210:213], v[86:89]
	v_mfma_f32_16x16x32_bf16 v[82:85], v[172:175], v[210:213], v[82:85]
	v_mfma_f32_16x16x32_bf16 v[70:73], v[164:167], v[218:221], v[70:73]
	v_mfma_f32_16x16x32_bf16 v[66:69], v[172:175], v[218:221], v[66:69]
	v_mfma_f32_16x16x32_bf16 v[118:121], v[168:171], v[184:187], v[118:121]
	v_mfma_f32_16x16x32_bf16 v[114:117], v[176:179], v[184:187], v[114:117]
	v_mfma_f32_16x16x32_bf16 v[102:105], v[168:171], v[206:209], v[102:105]
	v_mfma_f32_16x16x32_bf16 v[98:101], v[176:179], v[206:209], v[98:101]
	v_mfma_f32_16x16x32_bf16 v[86:89], v[168:171], v[214:217], v[86:89]
	v_mfma_f32_16x16x32_bf16 v[82:85], v[176:179], v[214:217], v[82:85]
	v_mfma_f32_16x16x32_bf16 v[70:73], v[168:171], v[222:225], v[70:73]
	v_mfma_f32_16x16x32_bf16 v[66:69], v[176:179], v[222:225], v[66:69]
	s_setprio 0
	s_barrier
	s_add_i32 s41, s41, s24
	v_lshl_add_u64 v[146:147], s[20:21], 0, v[134:135]
	s_mov_b32 m0, s41
	ds_read_b128 v[180:183], v151 offset:16384
	ds_read_b128 v[184:187], v151 offset:17408
	ds_read_b128 v[188:191], v151 offset:18432
	ds_read_b128 v[206:209], v151 offset:19456
	ds_read_b128 v[210:213], v151 offset:20480
	ds_read_b128 v[214:217], v151 offset:21504
	ds_read_b128 v[218:221], v151 offset:22528
	ds_read_b128 v[222:225], v151 offset:23552
	global_load_lds_dwordx4 v134, s[20:21]
	s_add_i32 m0, s41, 0x2000
	s_add_u32 s42, s20, 0x40000
	v_lshl_add_u64 v[192:193], s[20:21], 0, v[130:131]
	s_addc_u32 s43, s21, 0
	s_add_i32 s41, s44, s24
	global_load_lds_dwordx4 v130, s[20:21]
	s_mov_b32 m0, s41
	s_nop 0
	global_load_lds_dwordx4 v134, s[42:43]
	s_add_i32 m0, s41, 0x2000
	s_nop 0
	global_load_lds_dwordx4 v130, s[42:43]
	s_mov_b32 m0, s25
	s_nop 0
	global_load_lds_dwordx4 v136, s[22:23]
	s_mov_b32 m0, s26
	s_nop 0
	global_load_lds_dwordx4 v132, s[22:23]
	s_waitcnt vmcnt(8)
	s_waitcnt lgkmcnt(0)
	s_barrier
	s_setprio 1
	v_mfma_f32_16x16x32_bf16 v[62:65], v[142:145], v[180:183], v[62:65]
	v_mfma_f32_16x16x32_bf16 v[58:61], v[156:159], v[180:183], v[58:61]
	v_mfma_f32_16x16x32_bf16 v[46:49], v[142:145], v[188:191], v[46:49]
	v_mfma_f32_16x16x32_bf16 v[42:45], v[156:159], v[188:191], v[42:45]
	v_mfma_f32_16x16x32_bf16 v[30:33], v[142:145], v[210:213], v[30:33]
	v_mfma_f32_16x16x32_bf16 v[26:29], v[156:159], v[210:213], v[26:29]
	v_mfma_f32_16x16x32_bf16 v[14:17], v[142:145], v[218:221], v[14:17]
	v_mfma_f32_16x16x32_bf16 v[10:13], v[156:159], v[218:221], v[10:13]
	v_mfma_f32_16x16x32_bf16 v[62:65], v[152:155], v[184:187], v[62:65]
	v_mfma_f32_16x16x32_bf16 v[58:61], v[160:163], v[184:187], v[58:61]
	v_mfma_f32_16x16x32_bf16 v[46:49], v[152:155], v[206:209], v[46:49]
	v_mfma_f32_16x16x32_bf16 v[42:45], v[160:163], v[206:209], v[42:45]
	v_mfma_f32_16x16x32_bf16 v[30:33], v[152:155], v[214:217], v[30:33]
	v_mfma_f32_16x16x32_bf16 v[26:29], v[160:163], v[214:217], v[26:29]
	v_mfma_f32_16x16x32_bf16 v[14:17], v[152:155], v[222:225], v[14:17]
	v_mfma_f32_16x16x32_bf16 v[10:13], v[160:163], v[222:225], v[10:13]
	v_mfma_f32_16x16x32_bf16 v[54:57], v[164:167], v[180:183], v[54:57]
	v_mfma_f32_16x16x32_bf16 v[50:53], v[172:175], v[180:183], v[50:53]
	v_mfma_f32_16x16x32_bf16 v[38:41], v[164:167], v[188:191], v[38:41]
	v_mfma_f32_16x16x32_bf16 v[34:37], v[172:175], v[188:191], v[34:37]
	v_mfma_f32_16x16x32_bf16 v[22:25], v[164:167], v[210:213], v[22:25]
	v_mfma_f32_16x16x32_bf16 v[18:21], v[172:175], v[210:213], v[18:21]
	v_mfma_f32_16x16x32_bf16 v[6:9], v[164:167], v[218:221], v[6:9]
	v_mfma_f32_16x16x32_bf16 v[2:5], v[172:175], v[218:221], v[2:5]
	v_mfma_f32_16x16x32_bf16 v[54:57], v[168:171], v[184:187], v[54:57]
	v_mfma_f32_16x16x32_bf16 v[50:53], v[176:179], v[184:187], v[50:53]
	v_mfma_f32_16x16x32_bf16 v[38:41], v[168:171], v[206:209], v[38:41]
	v_mfma_f32_16x16x32_bf16 v[34:37], v[176:179], v[206:209], v[34:37]
	v_mfma_f32_16x16x32_bf16 v[22:25], v[168:171], v[214:217], v[22:25]
	v_mfma_f32_16x16x32_bf16 v[18:21], v[176:179], v[214:217], v[18:21]
	v_mfma_f32_16x16x32_bf16 v[6:9], v[168:171], v[222:225], v[6:9]
	v_mfma_f32_16x16x32_bf16 v[2:5], v[176:179], v[222:225], v[2:5]
	s_setprio 0
	s_barrier
; #define PG8_STAGE(bufoff, gbase, voff) do { _Pragma("unroll") for (int _i = 0; _i < 2; ++_i) \
;         __builtin_amdgcn_global_load_lds((const unsigned*)((const char*)(gbase) + (voff)[_i]), (PG8_LAS unsigned*)(lds + (bufoff) + ldsw + _i * 8192), 16, 0, 0); } while (0)
; #define PG8_LDA(dst, b, h) do { _Pragma("unroll") for (int m = 0; m < 4; ++m) _Pragma("unroll") for (int k = 0; k < 2; ++k) dst[m][k] = *(const PG8_LAS bf16x8*)(lds + PG8_SA(b, h) + aoff + m * 2048 + k * 1024); } while (0)
; #define PG8_LDB(dst, b, h) do { _Pragma("unroll") for (int n = 0; n < 2; ++n) _Pragma("unroll") for (int k = 0; k < 2; ++k) dst[n][k] = *(const PG8_LAS bf16x8*)(lds + PG8_SB(b, h) + boff + n * 2048 + k * 1024); } while (0)
; #define PG8_MMA(ai, bj, At, Bt) do { __builtin_amdgcn_s_setprio(1); _Pragma("unroll") for (int m = 0; m < 4; ++m) _Pragma("unroll") for (int n = 0; n < 2; ++n) _Pragma("unroll") for (int k = 0; k < 2; ++k) \
;         acc[ai][bj][m][n] = __builtin_amdgcn_mfma_f32_16x16x32_bf16(Bt[n][k], At[m][k], acc[ai][bj][m][n], 0, 0, 0); __builtin_amdgcn_s_setprio(0); } while (0)
; #define PG8_WAIT_V(n) asm volatile("s_waitcnt vmcnt(" #n ")" ::: "memory")
; #define PG8_WAIT_L(n) asm volatile("s_waitcnt lgkmcnt(" #n ")" ::: "memory")
; #define PG8_BAR __builtin_amdgcn_s_barrier()
; #define PG8_SCHED __builtin_amdgcn_sched_barrier(0)
; template <class Epi, class Sched, bool ALIGN_EPI = false, bool SP2 = false>
; __device__ __forceinline__ void gemm_phase(PG8_LAS unsigned char* lds, const Gemm g, const Sched& S, const Epi& E) {
;     ...
;             PG8_LDB(B0, 1, 0); PG8_LDB(B1, 1, 1); PG8_SCHED; PG8_LDA(At, 1, 0); PG8_STAGE(PG8_SA(0, 1), a2 + hstepA, voffA);
;             PG8_WAIT_V(8); PG8_WAIT_L(0); PG8_BAR; PG8_MMA(0, 0, At, B0); PG8_MMA(0, 1, At, B1); PG8_BAR; PG8_SCHED;
;             PG8_LDA(At, 1, 1); PG8_STAGE(PG8_SB(1, 0), b3, voffB); PG8_STAGE(PG8_SB(1, 1), b3 + hstepB, voffB); PG8_STAGE(PG8_SA(1, 0), a3, voffA);
;             PG8_WAIT_V(8); PG8_WAIT_L(0); PG8_BAR; PG8_MMA(1, 0, At, B0); PG8_MMA(1, 1, At, B1); PG8_BAR; PG8_SCHED;
;     ...
;         }
;         if constexpr (ALIGN_EPI) { if (wr == 0) PG8_BAR; }
	s_add_i32 s41, 0, 0x18000
	v_add_u32_e32 v0, s41, v149
	s_add_i32 s42, 0, 0x1c000
	ds_read_b128 v[142:145], v0
	ds_read_b128 v[152:155], v0 offset:1024
	ds_read_b128 v[156:159], v0 offset:2048
	ds_read_b128 v[160:163], v0 offset:3072
	v_add_u32_e32 v0, s42, v149
	ds_read_b128 v[164:167], v0
	ds_read_b128 v[168:171], v0 offset:1024
	ds_read_b128 v[172:175], v0 offset:2048
	ds_read_b128 v[176:179], v0 offset:3072
	s_add_u32 s22, s22, 0x4000
	s_addc_u32 s23, s23, 0
	s_mov_b32 m0, s27
	ds_read_b128 v[180:183], v151 offset:32768
	ds_read_b128 v[184:187], v151 offset:33792
	ds_read_b128 v[188:191], v151 offset:34816
	ds_read_b128 v[206:209], v151 offset:35840
	ds_read_b128 v[210:213], v151 offset:36864
	ds_read_b128 v[214:217], v151 offset:37888
	ds_read_b128 v[218:221], v151 offset:38912
	ds_read_b128 v[222:225], v151 offset:39936
	global_load_lds_dwordx4 v136, s[22:23]
	s_mov_b32 m0, s28
	s_nop 0
	global_load_lds_dwordx4 v132, s[22:23]
	s_waitcnt vmcnt(8)
	s_waitcnt lgkmcnt(0)
	s_barrier
	s_setprio 1
	v_mfma_f32_16x16x32_bf16 v[126:129], v[142:145], v[180:183], v[126:129]
	v_mfma_f32_16x16x32_bf16 v[122:125], v[156:159], v[180:183], v[122:125]
	v_mfma_f32_16x16x32_bf16 v[110:113], v[142:145], v[188:191], v[110:113]
	v_mfma_f32_16x16x32_bf16 v[106:109], v[156:159], v[188:191], v[106:109]
	v_mfma_f32_16x16x32_bf16 v[94:97], v[142:145], v[210:213], v[94:97]
	v_mfma_f32_16x16x32_bf16 v[90:93], v[156:159], v[210:213], v[90:93]
	v_mfma_f32_16x16x32_bf16 v[78:81], v[142:145], v[218:221], v[78:81]
	v_mfma_f32_16x16x32_bf16 v[74:77], v[156:159], v[218:221], v[74:77]
	v_mfma_f32_16x16x32_bf16 v[126:129], v[152:155], v[184:187], v[126:129]
	v_mfma_f32_16x16x32_bf16 v[122:125], v[160:163], v[184:187], v[122:125]
	v_mfma_f32_16x16x32_bf16 v[110:113], v[152:155], v[206:209], v[110:113]
	v_mfma_f32_16x16x32_bf16 v[106:109], v[160:163], v[206:209], v[106:109]
	v_mfma_f32_16x16x32_bf16 v[94:97], v[152:155], v[214:217], v[94:97]
	v_mfma_f32_16x16x32_bf16 v[90:93], v[160:163], v[214:217], v[90:93]
	v_mfma_f32_16x16x32_bf16 v[78:81], v[152:155], v[222:225], v[78:81]
	v_mfma_f32_16x16x32_bf16 v[74:77], v[160:163], v[222:225], v[74:77]
	v_mfma_f32_16x16x32_bf16 v[118:121], v[164:167], v[180:183], v[118:121]
	v_mfma_f32_16x16x32_bf16 v[114:117], v[172:175], v[180:183], v[114:117]
	v_mfma_f32_16x16x32_bf16 v[102:105], v[164:167], v[188:191], v[102:105]
	v_mfma_f32_16x16x32_bf16 v[98:101], v[172:175], v[188:191], v[98:101]
	v_mfma_f32_16x16x32_bf16 v[86:89], v[164:167], v[210:213], v[86:89]
	v_mfma_f32_16x16x32_bf16 v[82:85], v[172:175], v[210:213], v[82:85]
	v_mfma_f32_16x16x32_bf16 v[70:73], v[164:167], v[218:221], v[70:73]
	v_mfma_f32_16x16x32_bf16 v[66:69], v[172:175], v[218:221], v[66:69]
	v_mfma_f32_16x16x32_bf16 v[118:121], v[168:171], v[184:187], v[118:121]
	v_mfma_f32_16x16x32_bf16 v[114:117], v[176:179], v[184:187], v[114:117]
	v_mfma_f32_16x16x32_bf16 v[102:105], v[168:171], v[206:209], v[102:105]
	v_mfma_f32_16x16x32_bf16 v[98:101], v[176:179], v[206:209], v[98:101]
	v_mfma_f32_16x16x32_bf16 v[86:89], v[168:171], v[214:217], v[86:89]
	v_mfma_f32_16x16x32_bf16 v[82:85], v[176:179], v[214:217], v[82:85]
	v_mfma_f32_16x16x32_bf16 v[70:73], v[168:171], v[222:225], v[70:73]
	v_mfma_f32_16x16x32_bf16 v[66:69], v[176:179], v[222:225], v[66:69]
	s_setprio 0
	s_barrier
	s_add_i32 s22, s41, s24
	v_lshl_add_u64 v[146:147], v[146:147], 0, s[78:79]
	s_mov_b32 m0, s22
	ds_read_b128 v[180:183], v151 offset:49152
	ds_read_b128 v[184:187], v151 offset:50176
	ds_read_b128 v[188:191], v151 offset:51200
	ds_read_b128 v[206:209], v151 offset:52224
	ds_read_b128 v[210:213], v151 offset:53248
	ds_read_b128 v[214:217], v151 offset:54272
	ds_read_b128 v[218:221], v151 offset:55296
	ds_read_b128 v[222:225], v151 offset:56320
	global_load_lds_dwordx4 v[146:147], off
	s_add_i32 m0, s22, 0x2000
	s_add_u32 s20, s20, 0x40080
	v_lshl_add_u64 v[146:147], v[192:193], 0, s[78:79]
	s_addc_u32 s21, s21, 0
	s_add_i32 s22, s42, s24
	global_load_lds_dwordx4 v[146:147], off
	s_mov_b32 m0, s22
	s_nop 0
	global_load_lds_dwordx4 v134, s[20:21]
	s_add_i32 m0, s22, 0x2000
	s_nop 0
	global_load_lds_dwordx4 v130, s[20:21]
	s_mov_b32 m0, s29
	s_nop 0
	global_load_lds_dwordx4 v136, s[18:19]
	s_mov_b32 m0, s30
	s_nop 0
	global_load_lds_dwordx4 v132, s[18:19]
	s_waitcnt vmcnt(8)
	s_waitcnt lgkmcnt(0)
	s_barrier
	s_setprio 1
	v_mfma_f32_16x16x32_bf16 v[62:65], v[142:145], v[180:183], v[62:65]
	v_mfma_f32_16x16x32_bf16 v[58:61], v[156:159], v[180:183], v[58:61]
	v_mfma_f32_16x16x32_bf16 v[46:49], v[142:145], v[188:191], v[46:49]
	v_mfma_f32_16x16x32_bf16 v[42:45], v[156:159], v[188:191], v[42:45]
	v_mfma_f32_16x16x32_bf16 v[30:33], v[142:145], v[210:213], v[30:33]
	v_mfma_f32_16x16x32_bf16 v[26:29], v[156:159], v[210:213], v[26:29]
	v_mfma_f32_16x16x32_bf16 v[14:17], v[142:145], v[218:221], v[14:17]
	v_mfma_f32_16x16x32_bf16 v[10:13], v[156:159], v[218:221], v[10:13]
	v_mfma_f32_16x16x32_bf16 v[62:65], v[152:155], v[184:187], v[62:65]
	v_mfma_f32_16x16x32_bf16 v[58:61], v[160:163], v[184:187], v[58:61]
	v_mfma_f32_16x16x32_bf16 v[46:49], v[152:155], v[206:209], v[46:49]
	v_mfma_f32_16x16x32_bf16 v[42:45], v[160:163], v[206:209], v[42:45]
	v_mfma_f32_16x16x32_bf16 v[30:33], v[152:155], v[214:217], v[30:33]
	v_mfma_f32_16x16x32_bf16 v[26:29], v[160:163], v[214:217], v[26:29]
	v_mfma_f32_16x16x32_bf16 v[14:17], v[152:155], v[222:225], v[14:17]
	v_mfma_f32_16x16x32_bf16 v[10:13], v[160:163], v[222:225], v[10:13]
	v_mfma_f32_16x16x32_bf16 v[54:57], v[164:167], v[180:183], v[54:57]
	v_mfma_f32_16x16x32_bf16 v[50:53], v[172:175], v[180:183], v[50:53]
	v_mfma_f32_16x16x32_bf16 v[38:41], v[164:167], v[188:191], v[38:41]
	v_mfma_f32_16x16x32_bf16 v[34:37], v[172:175], v[188:191], v[34:37]
	v_mfma_f32_16x16x32_bf16 v[22:25], v[164:167], v[210:213], v[22:25]
	v_mfma_f32_16x16x32_bf16 v[18:21], v[172:175], v[210:213], v[18:21]
	v_mfma_f32_16x16x32_bf16 v[6:9], v[164:167], v[218:221], v[6:9]
	v_mfma_f32_16x16x32_bf16 v[2:5], v[172:175], v[218:221], v[2:5]
	v_mfma_f32_16x16x32_bf16 v[54:57], v[168:171], v[184:187], v[54:57]
	v_mfma_f32_16x16x32_bf16 v[50:53], v[176:179], v[184:187], v[50:53]
	v_mfma_f32_16x16x32_bf16 v[38:41], v[168:171], v[206:209], v[38:41]
	v_mfma_f32_16x16x32_bf16 v[34:37], v[176:179], v[206:209], v[34:37]
	v_mfma_f32_16x16x32_bf16 v[22:25], v[168:171], v[214:217], v[22:25]
	v_mfma_f32_16x16x32_bf16 v[18:21], v[176:179], v[214:217], v[18:21]
	v_mfma_f32_16x16x32_bf16 v[6:9], v[168:171], v[222:225], v[6:9]
	v_mfma_f32_16x16x32_bf16 v[2:5], v[176:179], v[222:225], v[2:5]
	s_setprio 0
	s_barrier
	s_add_i32 s40, s40, 2
	s_add_u32 s38, s38, 0x100
	s_addc_u32 s39, s39, 0
	s_add_u32 s6, s6, 0x400000
	s_addc_u32 s7, s7, 0
	s_cmp_gt_u32 s40, 13
	s_cbranch_scc0 .LBB0_333
	s_and_b64 vcc, exec, s[8:9]
	s_cbranch_vccz .LBB0_336
	s_barrier
